# grid barrier between each resid GEMM and the following RMSNorm replaced by an 8-block group sync (rows of one m-tile), X handed over with sc0 sc1 stores/loads
# speedup vs baseline: 1.0183x; 1.0073x over previous
.Lr6_end:
.LBB0_839:
	s_cmp_lt_i32 s61, 7
	s_cbranch_scc1 .LBB0_893
	s_waitcnt vmcnt(0)
	s_barrier
	v_readfirstlane_b32 s2, v162
	s_and_b32 s3, s58, 7
	s_lshl_b32 s3, s3, 8
	s_bfe_u32 s6, s58, 0x30003
	s_lshl_b32 s6, s6, 2
	s_add_u32 s3, s3, s6
	s_add_u32 s3, s3, 0x3800
	s_add_u32 s6, s84, s3
	s_addc_u32 s7, s85, 0
	s_cmp_lg_u32 s2, 0
	s_cbranch_scc1 .Lgs6_wait
	s_mov_b64 s[8:9], exec
	s_mov_b64 exec, 1
	v_mov_b32_e32 v0, 0
	v_mov_b32_e32 v1, 1
	s_mov_b32 s10, 0
	global_atomic_add v0, v1, s[6:7]
.Lgs6_poll:
	global_load_dword v2, v0, s[6:7] sc1
	s_add_u32 s10, s10, 1
	s_waitcnt vmcnt(0)
	v_readfirstlane_b32 s2, v2
	s_nop 3
	s_cmp_gt_u32 s10, 0x400
	s_cbranch_scc1 .Lgs6_done
	s_cmp_ge_u32 s2, 8
	s_cbranch_scc1 .Lgs6_done
	s_sleep 1
	s_branch .Lgs6_poll
.Lgs6_done:
	s_mov_b64 exec, s[8:9]

.LBB0_893:
	s_cmp_gt_i32 s60, 7
	s_cselect_b64 s[2:3], -1, 0
	s_cmp_lt_i32 s61, 7
	s_cselect_b64 s[4:5], -1, 0
	s_or_b64 s[2:3], s[2:3], s[4:5]
	s_and_b64 vcc, exec, s[2:3]
	s_cbranch_vccnz .LBB0_951
	s_and_b32 s96, s58, 63
	s_lshl_b32 s96, s96, 3
	s_lshr_b32 s97, s58, 6
	s_or_b32 s96, s96, s97
	v_and_b32_e32 v0, 60, v163
	v_lshl_add_u32 v40, s96, 4, v0
	s_movk_i32 s2, 0x2000
	s_mov_b64 s[4:5], s[0:1]
	v_cmp_gt_i32_e32 vcc, s2, v40
	s_and_saveexec_b64 s[10:11], vcc
	s_cbranch_execz .LBB0_897
	v_mbcnt_lo_u32_b32 v1, -1, 0
	v_mbcnt_hi_u32_b32 v1, -1, v1
	v_and_b32_e32 v2, 64, v1
	v_add_u32_e32 v3, 64, v2
	v_xor_b32_e32 v5, 32, v1
	v_cmp_lt_i32_e32 vcc, v5, v3
	s_load_dwordx2 s[12:13], s[4:5], 0xe0
	s_load_dwordx2 s[2:3], s[4:5], 0x58
	s_load_dword s6, s[0:1], 0xf0
	v_cndmask_b32_e32 v5, v1, v5, vcc
	v_lshlrev_b32_e32 v68, 2, v5
	v_xor_b32_e32 v5, 16, v1
	v_cmp_lt_i32_e32 vcc, v5, v3
	s_waitcnt lgkmcnt(0)
	s_add_u32 s4, s12, 0x6b05000
	v_and_b32_e32 v0, 63, v162
	v_cndmask_b32_e32 v5, v1, v5, vcc
	v_lshlrev_b32_e32 v69, 2, v5
	v_xor_b32_e32 v5, 8, v1
	v_cmp_lt_i32_e32 vcc, v5, v3
	s_addc_u32 s5, s13, 0
	s_lshl_b32 s14, s6, 4
	v_cndmask_b32_e32 v5, v1, v5, vcc
	v_lshlrev_b32_e32 v70, 2, v5
	v_xor_b32_e32 v5, 4, v1
	v_cmp_lt_i32_e32 vcc, v5, v3
	v_ashrrev_i32_e32 v41, 31, v40
	v_mov_b32_e32 v43, 0
	v_cndmask_b32_e32 v5, v1, v5, vcc
	v_lshlrev_b32_e32 v71, 2, v5
	v_xor_b32_e32 v5, 2, v1
	v_cmp_lt_i32_e32 vcc, v5, v3
	v_or_b32_e32 v2, 64, v0
	v_or_b32_e32 v4, 0x80, v0
	v_cndmask_b32_e32 v5, v1, v5, vcc
	v_lshlrev_b32_e32 v72, 2, v5
	v_xor_b32_e32 v5, 1, v1
	v_cmp_lt_i32_e32 vcc, v5, v3
	v_or_b32_e32 v6, 0xc0, v0
	v_lshlrev_b32_e32 v42, 4, v0
	v_cndmask_b32_e32 v1, v1, v5, vcc
	v_lshlrev_b64 v[46:47], 11, v[40:41]
	s_ashr_i32 s15, s14, 31
	v_lshlrev_b64 v[48:49], 12, v[40:41]
	v_mov_b64_e32 v[50:51], s[4:5]
	s_mov_b32 s4, 0x358637bd
	v_lshlrev_b32_e32 v73, 2, v1
	v_lshl_add_u64 v[44:45], s[2:3], 0, v[42:43]
	v_lshl_or_b32 v46, v0, 3, v46
	s_lshl_b64 s[16:17], s[14:15], 11
	v_or_b32_e32 v48, v48, v42
	s_lshl_b64 s[18:19], s[14:15], 12
	s_mov_b64 s[20:21], 0
	s_movk_i32 s2, 0xfff
	s_movk_i32 s3, 0x6000
	s_mov_b64 s[22:23], 0x1000
	v_lshlrev_b32_e32 v42, 4, v0
	s_mov_b32 s15, 0x6b7b000
	s_mov_b32 s25, 0x6b7c000
	s_mov_b32 s26, 0x6b7d000
	v_lshlrev_b32_e32 v52, 4, v2
	v_mov_b32_e32 v53, v43
	v_lshlrev_b32_e32 v54, 4, v4
	v_mov_b32_e32 v55, v43
	v_lshlrev_b32_e32 v56, 4, v6
	v_mov_b32_e32 v57, v43
	s_mov_b32 s24, 0x3a800000
	v_mov_b64_e32 v[58:59], s[4:5]
	s_mov_b32 s27, 0x800000
	s_mov_b32 s28, 0x8b7a000
	s_mov_b32 s29, 0x8b7b000
	s_movk_i32 s30, 0x1fff
.LBB0_896:
	v_lshl_add_u64 v[16:17], s[12:13], 0, v[48:49]
	v_lshl_add_u64 v[4:5], s[12:13], 0, v[46:47]
	v_add_co_u32_e32 v8, vcc, 0x6b7a000, v16
	v_add_co_u32_e64 v60, s[4:5], s28, v4
	s_nop 0
	v_addc_co_u32_e32 v9, vcc, 0, v17, vcc
	v_addc_co_u32_e64 v61, s[4:5], 0, v5, s[4:5]
	v_add_u32_e32 v6, 0xfffff000, v40
	v_add_co_u32_e64 v62, s[4:5], s29, v4
	v_add_co_u32_e32 v12, vcc, s15, v16
	v_lshrrev_b32_e32 v6, 10, v6
	v_addc_co_u32_e64 v63, s[4:5], 0, v5, s[4:5]
	v_addc_co_u32_e32 v13, vcc, 0, v17, vcc
	v_add_u32_e32 v10, 1, v6
	v_cmp_lt_i32_e64 s[4:5], s2, v40
	v_add_co_u32_e32 v18, vcc, s25, v16
	global_load_dwordx4 v[0:3], v[44:45], off
	global_load_dwordx4 v[74:77], v[8:9], off offset:256 sc0 sc1
	global_load_dwordx4 v[36:39], v[8:9], off offset:1280 sc0 sc1
	global_load_dwordx4 v[20:23], v[8:9], off offset:2304 sc0 sc1
	global_load_dwordx4 v[4:7], v[8:9], off offset:3328 sc0 sc1
	v_cndmask_b32_e64 v14, 0, v10, s[4:5]
	v_addc_co_u32_e32 v19, vcc, 0, v17, vcc
	global_load_dwordx4 v[78:81], v[12:13], off offset:256 sc0 sc1
	global_load_dwordx4 v[82:85], v[12:13], off offset:1280 sc0 sc1
	global_load_dwordx4 v[24:27], v[12:13], off offset:2304 sc0 sc1
	global_load_dwordx4 v[8:11], v[12:13], off offset:3328 sc0 sc1
	v_mad_u64_u32 v[32:33], s[4:5], v14, s3, v[50:51]
	v_add_co_u32_e32 v102, vcc, s26, v16
	global_load_dwordx4 v[86:89], v[18:19], off offset:256 sc0 sc1
	global_load_dwordx4 v[90:93], v[18:19], off offset:1280 sc0 sc1
	global_load_dwordx4 v[28:31], v[18:19], off offset:2304 sc0 sc1
	global_load_dwordx4 v[12:15], v[18:19], off offset:3328 sc0 sc1
	v_lshl_add_u64 v[66:67], v[32:33], 0, s[22:23]
	v_lshl_add_u64 v[64:65], v[32:33], 0, v[42:43]
	v_addc_co_u32_e32 v103, vcc, 0, v17, vcc
	global_load_dwordx4 v[94:97], v[102:103], off offset:256 sc0 sc1
	global_load_dwordx4 v[98:101], v[102:103], off offset:1280 sc0 sc1
	global_load_dwordx4 v[32:35], v[102:103], off offset:2304 sc0 sc1
	global_load_dwordx4 v[16:19], v[102:103], off offset:3328 sc0 sc1
	v_lshl_add_u64 v[110:111], v[66:67], 0, v[42:43]
	global_load_dwordx4 v[102:105], v[64:65], off
	global_load_dwordx4 v[106:109], v[110:111], off
	v_lshl_add_u64 v[112:113], v[66:67], 0, v[52:53]
	v_add_u32_e32 v40, s14, v40
	v_lshl_add_u64 v[46:47], v[46:47], 0, s[16:17]
	v_lshl_add_u64 v[48:49], v[48:49], 0, s[18:19]
	s_waitcnt vmcnt(17)
	v_mov_b32_e32 v118, v75
	s_waitcnt vmcnt(16)
	v_mov_b32_e32 v119, v37
	v_mov_b32_e32 v116, v74
	v_mov_b32_e32 v117, v36
	s_waitcnt vmcnt(15)
	v_mov_b32_e32 v126, v21
	s_waitcnt vmcnt(14)
	v_mov_b32_e32 v127, v5
	v_pk_mul_f32 v[118:119], v[118:119], v[118:119]
	s_waitcnt vmcnt(13)
	v_mov_b32_e32 v136, v79
	s_waitcnt vmcnt(12)
	v_mov_b32_e32 v137, v83
	v_mov_b32_e32 v110, v76
	v_mov_b32_e32 v111, v38
	v_mov_b32_e32 v124, v20
	v_mov_b32_e32 v125, v4
	v_mov_b32_e32 v134, v78
	v_mov_b32_e32 v135, v82
	v_pk_mul_f32 v[126:127], v[126:127], v[126:127]
	s_waitcnt vmcnt(11)
	v_mov_b32_e32 v144, v25
	s_waitcnt vmcnt(10)
	v_mov_b32_e32 v145, v9
	v_pk_fma_f32 v[116:117], v[116:117], v[116:117], v[118:119]
	v_pk_mul_f32 v[118:119], v[136:137], v[136:137]
	s_waitcnt vmcnt(9)
	v_mov_b32_e32 v150, v87
	s_waitcnt vmcnt(8)
	v_mov_b32_e32 v151, v91
	v_mov_b32_e32 v114, v77
	v_mov_b32_e32 v115, v39
	v_mov_b32_e32 v120, v22
	v_mov_b32_e32 v121, v6
	v_mov_b32_e32 v130, v80
	v_mov_b32_e32 v131, v84
	v_mov_b32_e32 v142, v24
	v_mov_b32_e32 v143, v8
	v_mov_b32_e32 v148, v86
	v_mov_b32_e32 v149, v90
	v_pk_fma_f32 v[124:125], v[124:125], v[124:125], v[126:127]
	v_pk_mul_f32 v[126:127], v[144:145], v[144:145]
	s_waitcnt vmcnt(7)
	v_mov_b32_e32 v156, v29
	s_waitcnt vmcnt(6)
	v_mov_b32_e32 v157, v13
	v_pk_fma_f32 v[110:111], v[110:111], v[110:111], v[116:117]
	v_pk_fma_f32 v[116:117], v[134:135], v[134:135], v[118:119]
	v_pk_mul_f32 v[118:119], v[150:151], v[150:151]
	s_waitcnt vmcnt(5)
	v_mov_b32_e32 v160, v95
	s_waitcnt vmcnt(4)
	v_mov_b32_e32 v161, v99
	v_mov_b32_e32 v122, v23
	v_mov_b32_e32 v123, v7
	v_mov_b32_e32 v132, v81
	v_mov_b32_e32 v133, v85
	v_mov_b32_e32 v138, v26
	v_mov_b32_e32 v139, v10
	v_mov_b32_e32 v154, v28
	v_mov_b32_e32 v155, v12
	v_mov_b32_e32 v158, v94
	v_mov_b32_e32 v159, v98
	v_pk_fma_f32 v[120:121], v[120:121], v[120:121], v[124:125]
	v_pk_fma_f32 v[124:125], v[142:143], v[142:143], v[126:127]
	v_pk_mul_f32 v[126:127], v[156:157], v[156:157]
	s_waitcnt vmcnt(3)
	v_mov_b32_e32 v172, v33
	s_waitcnt vmcnt(2)
	v_mov_b32_e32 v173, v17
	s_waitcnt vmcnt(0)
	v_pk_add_f32 v[106:107], v[106:107], 1.0 op_sel_hi:[1,0]
	v_pk_fma_f32 v[110:111], v[114:115], v[114:115], v[110:111]
	v_pk_fma_f32 v[114:115], v[130:131], v[130:131], v[116:117]
	v_pk_fma_f32 v[116:117], v[148:149], v[148:149], v[118:119]
	v_pk_mul_f32 v[118:119], v[160:161], v[160:161]
	v_mov_b32_e32 v140, v27
	v_mov_b32_e32 v141, v11
	v_mov_b32_e32 v136, v88
	v_mov_b32_e32 v137, v92
	v_mov_b32_e32 v134, v96
	v_mov_b32_e32 v135, v100
	v_mov_b32_e32 v170, v32
	v_mov_b32_e32 v171, v16
	v_pk_add_f32 v[108:109], v[108:109], 1.0 op_sel_hi:[1,0]
	v_pk_fma_f32 v[120:121], v[122:123], v[122:123], v[120:121]
	v_pk_fma_f32 v[122:123], v[138:139], v[138:139], v[124:125]
	v_pk_fma_f32 v[124:125], v[154:155], v[154:155], v[126:127]
	v_pk_mul_f32 v[126:127], v[172:173], v[172:173]
	v_pk_mul_f32 v[0:1], v[0:1], v[106:107]
	v_pk_fma_f32 v[106:107], v[132:133], v[132:133], v[114:115]
	v_pk_fma_f32 v[114:115], v[158:159], v[158:159], v[118:119]
	v_mov_b32_e32 v146, v89
	v_mov_b32_e32 v147, v93
	v_mov_b32_e32 v144, v30
	v_mov_b32_e32 v145, v14
	v_mov_b32_e32 v150, v97
	v_mov_b32_e32 v151, v101
	v_mov_b32_e32 v142, v34
	v_mov_b32_e32 v143, v18
	v_pk_mul_f32 v[2:3], v[2:3], v[108:109]
	v_pk_fma_f32 v[108:109], v[136:137], v[136:137], v[116:117]
	v_pk_fma_f32 v[116:117], v[140:141], v[140:141], v[122:123]
	v_mov_b32_e32 v119, v110
	v_pk_fma_f32 v[126:127], v[170:171], v[170:171], v[126:127]
	v_pk_fma_f32 v[114:115], v[134:135], v[134:135], v[114:115]
	v_mov_b32_e32 v118, v106
	v_mov_b32_e32 v110, v107
	v_mov_b32_e32 v152, v31
	v_mov_b32_e32 v153, v15
	v_mov_b32_e32 v156, v35
	v_mov_b32_e32 v157, v19
	v_mov_b32_e32 v123, v120
	v_pk_fma_f32 v[124:125], v[144:145], v[144:145], v[124:125]
	v_pk_fma_f32 v[108:109], v[146:147], v[146:147], v[108:109]
	v_mov_b32_e32 v122, v116
	v_mov_b32_e32 v120, v117
	v_pk_fma_f32 v[116:117], v[142:143], v[142:143], v[126:127]
	v_pk_fma_f32 v[114:115], v[150:151], v[150:151], v[114:115]
	v_pk_add_f32 v[110:111], v[118:119], v[110:111]
	v_pk_fma_f32 v[106:107], v[152:153], v[152:153], v[124:125]
	v_pk_fma_f32 v[116:117], v[156:157], v[156:157], v[116:117]
	v_mov_b32_e32 v119, v108
	v_pk_add_f32 v[110:111], v[110:111], v[122:123]
	v_mov_b32_e32 v118, v114
	v_mov_b32_e32 v108, v115
	v_mov_b32_e32 v125, v106
	v_mov_b32_e32 v124, v116
	v_pk_add_f32 v[110:111], v[110:111], v[120:121]
	v_pk_add_f32 v[108:109], v[118:119], v[108:109]
	v_mov_b32_e32 v106, v117
	ds_bpermute_b32 v115, v68, v111
	ds_bpermute_b32 v114, v68, v110
	v_pk_add_f32 v[108:109], v[108:109], v[124:125]
	s_waitcnt lgkmcnt(0)
	v_pk_add_f32 v[110:111], v[110:111], v[114:115]
	v_pk_add_f32 v[106:107], v[108:109], v[106:107]
	ds_bpermute_b32 v109, v68, v107
	ds_bpermute_b32 v108, v68, v106
	ds_bpermute_b32 v115, v69, v111
	ds_bpermute_b32 v114, v69, v110
	s_waitcnt lgkmcnt(2)
	v_pk_add_f32 v[106:107], v[106:107], v[108:109]
	ds_bpermute_b32 v109, v69, v107
	ds_bpermute_b32 v108, v69, v106
	s_waitcnt lgkmcnt(2)
	v_pk_add_f32 v[110:111], v[110:111], v[114:115]
	ds_bpermute_b32 v115, v70, v111
	ds_bpermute_b32 v114, v70, v110
	s_waitcnt lgkmcnt(2)
	v_pk_add_f32 v[106:107], v[106:107], v[108:109]
	ds_bpermute_b32 v109, v70, v107
	ds_bpermute_b32 v108, v70, v106
	s_waitcnt lgkmcnt(2)
	v_pk_add_f32 v[110:111], v[110:111], v[114:115]
	ds_bpermute_b32 v115, v71, v111
	ds_bpermute_b32 v114, v71, v110
	s_waitcnt lgkmcnt(2)
	v_pk_add_f32 v[106:107], v[106:107], v[108:109]
	ds_bpermute_b32 v109, v71, v107
	ds_bpermute_b32 v108, v71, v106
	s_waitcnt lgkmcnt(2)
	v_pk_add_f32 v[110:111], v[110:111], v[114:115]
	ds_bpermute_b32 v115, v72, v111
	ds_bpermute_b32 v114, v72, v110
	s_waitcnt lgkmcnt(2)
	v_pk_add_f32 v[106:107], v[106:107], v[108:109]
	ds_bpermute_b32 v109, v72, v107
	ds_bpermute_b32 v108, v72, v106
	s_waitcnt lgkmcnt(2)
	v_pk_add_f32 v[110:111], v[110:111], v[114:115]
	ds_bpermute_b32 v115, v73, v111
	ds_bpermute_b32 v114, v73, v110
	s_waitcnt lgkmcnt(2)
	v_pk_add_f32 v[106:107], v[106:107], v[108:109]
	ds_bpermute_b32 v109, v73, v107
	ds_bpermute_b32 v108, v73, v106
	s_waitcnt lgkmcnt(2)
	v_pk_add_f32 v[110:111], v[110:111], v[114:115]
	s_waitcnt lgkmcnt(0)
	v_pk_add_f32 v[106:107], v[106:107], v[108:109]
	v_pk_fma_f32 v[110:111], v[110:111], s[24:25], v[58:59] op_sel_hi:[1,0,0]
	v_pk_fma_f32 v[106:107], v[106:107], s[24:25], v[58:59] op_sel_hi:[1,0,0]
	v_mul_f32_e32 v41, 0x4b800000, v111
	v_mul_f32_e32 v114, 0x4b800000, v110
	v_cmp_gt_f32_e32 vcc, s27, v110
	v_cmp_gt_f32_e64 s[4:5], s27, v111
	v_mul_f32_e32 v109, 0x4b800000, v107
	v_cndmask_b32_e32 v108, v110, v114, vcc
	v_cndmask_b32_e64 v41, v111, v41, s[4:5]
	v_rsq_f32_e32 v41, v41
	v_rsq_f32_e32 v108, v108
	v_mul_f32_e32 v110, 0x4b800000, v106
	v_cmp_gt_f32_e64 s[6:7], s27, v106
	v_cmp_gt_f32_e64 s[8:9], s27, v107
	s_nop 0
	v_cndmask_b32_e64 v106, v106, v110, s[6:7]
	v_cndmask_b32_e64 v107, v107, v109, s[8:9]
	v_rsq_f32_e32 v107, v107
	v_rsq_f32_e32 v109, v106
	v_mul_f32_e32 v106, 0x45800000, v41
	v_mul_f32_e32 v110, 0x45800000, v108
	v_cndmask_b32_e64 v106, v41, v106, s[4:5]
	v_cndmask_b32_e32 v108, v108, v110, vcc
	v_pk_mul_f32 v[74:75], v[74:75], v[106:107] op_sel_hi:[1,0]
	v_pk_mul_f32 v[76:77], v[76:77], v[106:107] op_sel_hi:[1,0]
	v_pk_mul_f32 v[78:79], v[78:79], v[108:109] op_sel_hi:[1,0]
	v_pk_mul_f32 v[80:81], v[80:81], v[108:109] op_sel_hi:[1,0]
	v_mul_f32_e32 v41, 0x45800000, v107
	v_mul_f32_e32 v111, 0x45800000, v109
	v_pk_fma_f32 v[74:75], v[74:75], v[0:1], v[102:103]
	v_pk_fma_f32 v[76:77], v[76:77], v[2:3], v[104:105]
	v_pk_fma_f32 v[78:79], v[78:79], v[0:1], v[102:103]
	v_pk_fma_f32 v[80:81], v[80:81], v[2:3], v[104:105]
	v_cndmask_b32_e64 v110, v107, v41, s[8:9]
	v_cndmask_b32_e64 v114, v109, v111, s[6:7]
	v_cvt_pk_bf16_f32 v74, v74, v75
	v_cvt_pk_bf16_f32 v75, v76, v77
	v_cvt_pk_bf16_f32 v76, v78, v79
	v_cvt_pk_bf16_f32 v77, v80, v81
	v_pk_mul_f32 v[78:79], v[86:87], v[110:111] op_sel_hi:[1,0]
	v_pk_mul_f32 v[80:81], v[88:89], v[110:111] op_sel_hi:[1,0]
	v_pk_mul_f32 v[86:87], v[94:95], v[114:115] op_sel_hi:[1,0]
	v_pk_mul_f32 v[88:89], v[96:97], v[114:115] op_sel_hi:[1,0]
	v_pk_fma_f32 v[78:79], v[78:79], v[0:1], v[102:103]
	v_pk_fma_f32 v[80:81], v[80:81], v[2:3], v[104:105]
	v_pk_fma_f32 v[0:1], v[86:87], v[0:1], v[102:103]
	v_pk_fma_f32 v[2:3], v[88:89], v[2:3], v[104:105]
	global_store_dwordx2 v[60:61], v[74:75], off offset:256
	global_store_dwordx2 v[60:61], v[76:77], off offset:2304
	v_cvt_pk_bf16_f32 v74, v78, v79
	v_cvt_pk_bf16_f32 v75, v80, v81
	v_cvt_pk_bf16_f32 v0, v0, v1
	v_cvt_pk_bf16_f32 v1, v2, v3
	global_store_dwordx2 v[62:63], v[74:75], off offset:256
	global_store_dwordx2 v[62:63], v[0:1], off offset:2304
	global_load_dwordx4 v[0:3], v[112:113], off
	s_nop 0
	global_load_dwordx4 v[74:77], v[64:65], off offset:1024
	global_load_dwordx4 v[78:81], v[44:45], off offset:1024
	v_pk_mul_f32 v[36:37], v[36:37], v[106:107] op_sel_hi:[1,0]
	v_pk_mul_f32 v[38:39], v[38:39], v[106:107] op_sel_hi:[1,0]
	v_pk_mul_f32 v[82:83], v[82:83], v[108:109] op_sel_hi:[1,0]
	v_pk_mul_f32 v[84:85], v[84:85], v[108:109] op_sel_hi:[1,0]
	v_pk_mul_f32 v[88:89], v[90:91], v[110:111] op_sel_hi:[1,0]
	v_pk_mul_f32 v[90:91], v[92:93], v[110:111] op_sel_hi:[1,0]
	v_pk_mul_f32 v[92:93], v[98:99], v[114:115] op_sel_hi:[1,0]
	v_pk_mul_f32 v[94:95], v[100:101], v[114:115] op_sel_hi:[1,0]
	v_lshl_add_u64 v[86:87], v[66:67], 0, v[54:55]
	v_pk_mul_f32 v[20:21], v[20:21], v[106:107] op_sel_hi:[1,0]
	v_pk_mul_f32 v[22:23], v[22:23], v[106:107] op_sel_hi:[1,0]
	v_pk_mul_f32 v[24:25], v[24:25], v[108:109] op_sel_hi:[1,0]
	v_pk_mul_f32 v[26:27], v[26:27], v[108:109] op_sel_hi:[1,0]
	v_pk_mul_f32 v[28:29], v[28:29], v[110:111] op_sel_hi:[1,0]
	v_pk_mul_f32 v[30:31], v[30:31], v[110:111] op_sel_hi:[1,0]
	v_pk_mul_f32 v[32:33], v[32:33], v[114:115] op_sel_hi:[1,0]
	v_pk_mul_f32 v[34:35], v[34:35], v[114:115] op_sel_hi:[1,0]
	v_lshl_add_u64 v[66:67], v[66:67], 0, v[56:57]
	v_pk_mul_f32 v[4:5], v[4:5], v[106:107] op_sel_hi:[1,0]
	v_pk_mul_f32 v[6:7], v[6:7], v[106:107] op_sel_hi:[1,0]
	v_cmp_lt_i32_e32 vcc, s30, v40
	v_pk_mul_f32 v[8:9], v[8:9], v[108:109] op_sel_hi:[1,0]
	v_pk_mul_f32 v[10:11], v[10:11], v[108:109] op_sel_hi:[1,0]
	v_pk_mul_f32 v[12:13], v[12:13], v[110:111] op_sel_hi:[1,0]
	v_pk_mul_f32 v[14:15], v[14:15], v[110:111] op_sel_hi:[1,0]
	v_pk_mul_f32 v[16:17], v[16:17], v[114:115] op_sel_hi:[1,0]
	v_pk_mul_f32 v[18:19], v[18:19], v[114:115] op_sel_hi:[1,0]
	s_or_b64 s[20:21], vcc, s[20:21]
	s_waitcnt vmcnt(2)
	v_pk_add_f32 v[0:1], v[0:1], 1.0 op_sel_hi:[1,0]
	v_pk_add_f32 v[2:3], v[2:3], 1.0 op_sel_hi:[1,0]
	s_waitcnt vmcnt(0)
	v_pk_mul_f32 v[0:1], v[78:79], v[0:1]
	v_pk_mul_f32 v[2:3], v[80:81], v[2:3]
	v_pk_fma_f32 v[36:37], v[36:37], v[0:1], v[74:75]
	v_pk_fma_f32 v[38:39], v[38:39], v[2:3], v[76:77]
	v_pk_fma_f32 v[78:79], v[82:83], v[0:1], v[74:75]
	v_pk_fma_f32 v[80:81], v[84:85], v[2:3], v[76:77]
	v_pk_fma_f32 v[82:83], v[88:89], v[0:1], v[74:75]
	v_pk_fma_f32 v[84:85], v[90:91], v[2:3], v[76:77]
	v_pk_fma_f32 v[0:1], v[92:93], v[0:1], v[74:75]
	v_pk_fma_f32 v[2:3], v[94:95], v[2:3], v[76:77]
	v_cvt_pk_bf16_f32 v36, v36, v37
	v_cvt_pk_bf16_f32 v37, v38, v39
	v_cvt_pk_bf16_f32 v38, v78, v79
	v_cvt_pk_bf16_f32 v39, v80, v81
	v_cvt_pk_bf16_f32 v74, v82, v83
	v_cvt_pk_bf16_f32 v75, v84, v85
	v_cvt_pk_bf16_f32 v0, v0, v1
	v_cvt_pk_bf16_f32 v1, v2, v3
	global_store_dwordx2 v[60:61], v[36:37], off offset:768
	global_store_dwordx2 v[60:61], v[38:39], off offset:2816
	global_store_dwordx2 v[62:63], v[74:75], off offset:768
	global_store_dwordx2 v[62:63], v[0:1], off offset:2816
	global_load_dwordx4 v[0:3], v[86:87], off
	s_nop 0
	global_load_dwordx4 v[36:39], v[64:65], off offset:2048
	global_load_dwordx4 v[74:77], v[44:45], off offset:2048
	s_waitcnt vmcnt(2)
	v_pk_add_f32 v[0:1], v[0:1], 1.0 op_sel_hi:[1,0]
	v_pk_add_f32 v[2:3], v[2:3], 1.0 op_sel_hi:[1,0]
	s_waitcnt vmcnt(0)
	v_pk_mul_f32 v[0:1], v[74:75], v[0:1]
	v_pk_mul_f32 v[2:3], v[76:77], v[2:3]
	v_pk_fma_f32 v[20:21], v[20:21], v[0:1], v[36:37]
	v_pk_fma_f32 v[22:23], v[22:23], v[2:3], v[38:39]
	v_pk_fma_f32 v[24:25], v[24:25], v[0:1], v[36:37]
	v_pk_fma_f32 v[26:27], v[26:27], v[2:3], v[38:39]
	v_pk_fma_f32 v[28:29], v[28:29], v[0:1], v[36:37]
	v_pk_fma_f32 v[30:31], v[30:31], v[2:3], v[38:39]
	v_pk_fma_f32 v[0:1], v[32:33], v[0:1], v[36:37]
	v_pk_fma_f32 v[2:3], v[34:35], v[2:3], v[38:39]
	v_cvt_pk_bf16_f32 v20, v20, v21
	v_cvt_pk_bf16_f32 v21, v22, v23
	v_cvt_pk_bf16_f32 v22, v24, v25
	v_cvt_pk_bf16_f32 v23, v26, v27
	v_cvt_pk_bf16_f32 v24, v28, v29
	v_cvt_pk_bf16_f32 v25, v30, v31
	v_cvt_pk_bf16_f32 v0, v0, v1
	v_cvt_pk_bf16_f32 v1, v2, v3
	global_store_dwordx2 v[60:61], v[20:21], off offset:1280
	global_store_dwordx2 v[60:61], v[22:23], off offset:3328
	global_store_dwordx2 v[62:63], v[24:25], off offset:1280
	global_store_dwordx2 v[62:63], v[0:1], off offset:3328
	global_load_dwordx4 v[0:3], v[66:67], off
	s_nop 0
	global_load_dwordx4 v[20:23], v[64:65], off offset:3072
	global_load_dwordx4 v[24:27], v[44:45], off offset:3072
	s_waitcnt vmcnt(2)
	v_pk_add_f32 v[0:1], v[0:1], 1.0 op_sel_hi:[1,0]
	v_pk_add_f32 v[2:3], v[2:3], 1.0 op_sel_hi:[1,0]
	s_waitcnt vmcnt(0)
	v_pk_mul_f32 v[0:1], v[24:25], v[0:1]
	v_pk_mul_f32 v[2:3], v[26:27], v[2:3]
	v_pk_fma_f32 v[4:5], v[4:5], v[0:1], v[20:21]
	v_pk_fma_f32 v[6:7], v[6:7], v[2:3], v[22:23]
	v_pk_fma_f32 v[8:9], v[8:9], v[0:1], v[20:21]
	v_pk_fma_f32 v[10:11], v[10:11], v[2:3], v[22:23]
	v_pk_fma_f32 v[12:13], v[12:13], v[0:1], v[20:21]
	v_pk_fma_f32 v[14:15], v[14:15], v[2:3], v[22:23]
	v_pk_fma_f32 v[0:1], v[16:17], v[0:1], v[20:21]
	v_pk_fma_f32 v[2:3], v[18:19], v[2:3], v[22:23]
	v_cvt_pk_bf16_f32 v4, v4, v5
	v_cvt_pk_bf16_f32 v5, v6, v7
	v_cvt_pk_bf16_f32 v6, v8, v9
	v_cvt_pk_bf16_f32 v7, v10, v11
	v_cvt_pk_bf16_f32 v8, v12, v13
	v_cvt_pk_bf16_f32 v9, v14, v15
	v_cvt_pk_bf16_f32 v0, v0, v1
	v_cvt_pk_bf16_f32 v1, v2, v3
	global_store_dwordx2 v[60:61], v[4:5], off offset:1792
	global_store_dwordx2 v[60:61], v[6:7], off offset:3840
	global_store_dwordx2 v[62:63], v[8:9], off offset:1792
	global_store_dwordx2 v[62:63], v[0:1], off offset:3840
	s_andn2_b64 exec, exec, s[20:21]
	s_cbranch_execnz .LBB0_896

.Lr9_end:
.LBB0_1021:
	s_cmp_lt_i32 s61, 10
	s_cbranch_scc1 .LBB0_1075
	s_waitcnt vmcnt(0)
	s_barrier
	v_readfirstlane_b32 s2, v162
	s_and_b32 s3, s58, 7
	s_lshl_b32 s3, s3, 8
	s_bfe_u32 s6, s58, 0x30003
	s_lshl_b32 s6, s6, 2
	s_add_u32 s3, s3, s6
	s_add_u32 s3, s3, 0x3820
	s_add_u32 s6, s84, s3
	s_addc_u32 s7, s85, 0
	s_cmp_lg_u32 s2, 0
	s_cbranch_scc1 .Lgs9_wait
	s_mov_b64 s[8:9], exec
	s_mov_b64 exec, 1
	v_mov_b32_e32 v0, 0
	v_mov_b32_e32 v1, 1
	s_mov_b32 s10, 0
	global_atomic_add v0, v1, s[6:7]

.LBB0_1075:
	s_cmp_gt_i32 s60, 10
	s_cselect_b64 s[2:3], -1, 0
	s_cmp_lt_i32 s61, 10
	s_cselect_b64 s[4:5], -1, 0
	s_or_b64 s[2:3], s[2:3], s[4:5]
	s_and_b64 vcc, exec, s[2:3]
	s_cbranch_vccnz .LBB0_1133
	s_and_b32 s96, s58, 63
	s_lshl_b32 s96, s96, 3
	s_lshr_b32 s97, s58, 6
	s_or_b32 s96, s96, s97
	v_and_b32_e32 v0, 60, v163
	v_lshl_add_u32 v40, s96, 4, v0
	s_movk_i32 s2, 0x2000
	s_mov_b64 s[4:5], s[0:1]
	v_cmp_gt_i32_e32 vcc, s2, v40
	s_and_saveexec_b64 s[10:11], vcc
	s_cbranch_execz .LBB0_1079
	v_mbcnt_lo_u32_b32 v1, -1, 0
	v_mbcnt_hi_u32_b32 v1, -1, v1
	v_and_b32_e32 v2, 64, v1
	v_add_u32_e32 v3, 64, v2
	v_xor_b32_e32 v5, 32, v1
	v_cmp_lt_i32_e32 vcc, v5, v3
	s_load_dwordx2 s[12:13], s[4:5], 0xe0
	s_load_dwordx2 s[2:3], s[4:5], 0x50
	v_cndmask_b32_e32 v5, v1, v5, vcc
	v_lshlrev_b32_e32 v74, 2, v5
	v_xor_b32_e32 v5, 16, v1
	v_cmp_lt_i32_e32 vcc, v5, v3
	s_load_dword s6, s[0:1], 0xf0
	s_waitcnt lgkmcnt(0)
	s_add_u32 s4, s12, 0x6b02000
	v_cndmask_b32_e32 v5, v1, v5, vcc
	v_lshlrev_b32_e32 v75, 2, v5
	v_xor_b32_e32 v5, 8, v1
	v_cmp_lt_i32_e32 vcc, v5, v3
	s_addc_u32 s5, s13, 0
	v_and_b32_e32 v0, 63, v162
	v_cndmask_b32_e32 v5, v1, v5, vcc
	v_lshlrev_b32_e32 v76, 2, v5
	v_xor_b32_e32 v5, 4, v1
	v_cmp_lt_i32_e32 vcc, v5, v3
	s_add_u32 s2, s2, 0x1000
	v_mov_b32_e32 v43, 0
	v_cndmask_b32_e32 v5, v1, v5, vcc
	v_lshlrev_b32_e32 v77, 2, v5
	v_xor_b32_e32 v5, 2, v1
	v_cmp_lt_i32_e32 vcc, v5, v3
	v_or_b32_e32 v2, 64, v0
	s_addc_u32 s3, s3, 0
	v_cndmask_b32_e32 v5, v1, v5, vcc
	v_or_b32_e32 v4, 0x80, v0
	v_lshlrev_b32_e32 v78, 2, v5
	v_xor_b32_e32 v5, 1, v1
	v_lshlrev_b32_e32 v8, 4, v2
	v_mov_b32_e32 v9, v43
	s_lshl_b32 s16, s6, 4
	v_or_b32_e32 v6, 0xc0, v0
	v_cmp_lt_i32_e32 vcc, v5, v3
	v_lshl_add_u64 v[46:47], s[2:3], 0, v[8:9]
	v_lshlrev_b32_e32 v8, 4, v4
	v_ashrrev_i32_e32 v41, 31, v40
	v_cndmask_b32_e32 v1, v1, v5, vcc
	v_lshlrev_b32_e32 v42, 4, v0
	s_waitcnt vmcnt(35)
	v_lshl_add_u64 v[48:49], s[2:3], 0, v[8:9]
	v_lshlrev_b32_e32 v8, 4, v6
	s_waitcnt vmcnt(34)
	v_lshlrev_b64 v[52:53], 11, v[40:41]
	s_ashr_i32 s17, s16, 31
	v_lshlrev_b64 v[54:55], 12, v[40:41]
	s_waitcnt vmcnt(33)
	v_mov_b64_e32 v[56:57], s[4:5]
	s_mov_b32 s4, 0x358637bd
	s_mov_b64 s[14:15], 0x1000
	v_lshlrev_b32_e32 v79, 2, v1
	v_lshl_add_u64 v[44:45], s[2:3], 0, v[42:43]
	v_lshl_add_u64 v[50:51], s[2:3], 0, v[8:9]
	v_lshl_or_b32 v52, v0, 3, v52
	s_lshl_b64 s[18:19], s[16:17], 11
	v_or_b32_e32 v54, v54, v42
	s_lshl_b64 s[20:21], s[16:17], 12
	s_mov_b64 s[22:23], 0
	s_movk_i32 s2, 0xfff
	s_movk_i32 s3, 0x6000
	v_lshlrev_b32_e32 v42, 4, v0
	s_mov_b32 s17, 0x6b7b000
	s_mov_b32 s25, 0x6b7c000
	s_mov_b32 s26, 0x6b7d000
	v_lshlrev_b32_e32 v58, 4, v2
	v_mov_b32_e32 v59, v43
	s_waitcnt vmcnt(32)
	v_lshlrev_b32_e32 v60, 4, v4
	v_mov_b32_e32 v61, v43
	v_lshlrev_b32_e32 v62, 4, v6
	v_mov_b32_e32 v63, v43
	s_mov_b32 s24, 0x3a800000
	v_mov_b64_e32 v[64:65], s[4:5]
	s_mov_b32 s27, 0x800000
	s_mov_b32 s28, 0x8b7a000
	s_mov_b32 s29, 0x8b7b000
	s_movk_i32 s30, 0x1fff
.LBB0_1078:
	v_lshl_add_u64 v[16:17], s[12:13], 0, v[54:55]
	v_lshl_add_u64 v[4:5], s[12:13], 0, v[52:53]
	v_add_co_u32_e32 v8, vcc, 0x6b7a000, v16
	v_add_co_u32_e64 v66, s[4:5], s28, v4
	s_nop 0
	v_addc_co_u32_e32 v9, vcc, 0, v17, vcc
	v_addc_co_u32_e64 v67, s[4:5], 0, v5, s[4:5]
	v_add_u32_e32 v6, 0xfffff000, v40
	v_add_co_u32_e64 v68, s[4:5], s29, v4
	v_add_co_u32_e32 v12, vcc, s17, v16
	v_lshrrev_b32_e32 v6, 10, v6
	v_addc_co_u32_e64 v69, s[4:5], 0, v5, s[4:5]
	v_addc_co_u32_e32 v13, vcc, 0, v17, vcc
	v_add_u32_e32 v10, 6, v6
	v_cmp_lt_i32_e64 s[4:5], s2, v40
	v_add_co_u32_e32 v18, vcc, s25, v16
	global_load_dwordx4 v[0:3], v[44:45], off
	global_load_dwordx4 v[80:83], v[8:9], off offset:256 sc0 sc1
	global_load_dwordx4 v[36:39], v[8:9], off offset:1280 sc0 sc1
	global_load_dwordx4 v[20:23], v[8:9], off offset:2304 sc0 sc1
	global_load_dwordx4 v[4:7], v[8:9], off offset:3328 sc0 sc1
	v_cndmask_b32_e64 v14, 5, v10, s[4:5]
	v_addc_co_u32_e32 v19, vcc, 0, v17, vcc
	global_load_dwordx4 v[84:87], v[12:13], off offset:256 sc0 sc1
	global_load_dwordx4 v[88:91], v[12:13], off offset:1280 sc0 sc1
	global_load_dwordx4 v[24:27], v[12:13], off offset:2304 sc0 sc1
	global_load_dwordx4 v[8:11], v[12:13], off offset:3328 sc0 sc1
	v_mad_u64_u32 v[32:33], s[4:5], v14, s3, v[56:57]
	v_add_co_u32_e32 v108, vcc, s26, v16
	global_load_dwordx4 v[92:95], v[18:19], off offset:256 sc0 sc1
	global_load_dwordx4 v[96:99], v[18:19], off offset:1280 sc0 sc1
	global_load_dwordx4 v[28:31], v[18:19], off offset:2304 sc0 sc1
	global_load_dwordx4 v[12:15], v[18:19], off offset:3328 sc0 sc1
	v_lshl_add_u64 v[72:73], v[32:33], 0, s[14:15]
	v_lshl_add_u64 v[70:71], v[32:33], 0, v[42:43]
	v_addc_co_u32_e32 v109, vcc, 0, v17, vcc
	global_load_dwordx4 v[100:103], v[108:109], off offset:256 sc0 sc1
	global_load_dwordx4 v[104:107], v[108:109], off offset:1280 sc0 sc1
	global_load_dwordx4 v[32:35], v[108:109], off offset:2304 sc0 sc1
	global_load_dwordx4 v[16:19], v[108:109], off offset:3328 sc0 sc1
	v_lshl_add_u64 v[116:117], v[72:73], 0, v[42:43]
	global_load_dwordx4 v[108:111], v[70:71], off
	global_load_dwordx4 v[112:115], v[116:117], off
	v_lshl_add_u64 v[118:119], v[72:73], 0, v[58:59]
	v_add_u32_e32 v40, s16, v40
	v_lshl_add_u64 v[52:53], v[52:53], 0, s[18:19]
	v_lshl_add_u64 v[54:55], v[54:55], 0, s[20:21]
	s_waitcnt vmcnt(17)
	v_mov_b32_e32 v124, v81
	s_waitcnt vmcnt(16)
	v_mov_b32_e32 v125, v37
	v_mov_b32_e32 v122, v80
	v_mov_b32_e32 v123, v36
	s_waitcnt vmcnt(15)
	v_mov_b32_e32 v134, v21
	s_waitcnt vmcnt(14)
	v_mov_b32_e32 v135, v5
	v_pk_mul_f32 v[124:125], v[124:125], v[124:125]
	s_waitcnt vmcnt(13)
	v_mov_b32_e32 v142, v85
	s_waitcnt vmcnt(12)
	v_mov_b32_e32 v143, v89
	v_mov_b32_e32 v116, v82
	v_mov_b32_e32 v117, v38
	v_mov_b32_e32 v132, v20
	v_mov_b32_e32 v133, v4
	v_mov_b32_e32 v140, v84
	v_mov_b32_e32 v141, v88
	v_pk_mul_f32 v[134:135], v[134:135], v[134:135]
	s_waitcnt vmcnt(11)
	v_mov_b32_e32 v150, v25
	s_waitcnt vmcnt(10)
	v_mov_b32_e32 v151, v9
	v_pk_fma_f32 v[122:123], v[122:123], v[122:123], v[124:125]
	v_pk_mul_f32 v[124:125], v[142:143], v[142:143]
	s_waitcnt vmcnt(9)
	v_mov_b32_e32 v156, v93
	s_waitcnt vmcnt(8)
	v_mov_b32_e32 v157, v97
	v_mov_b32_e32 v120, v83
	v_mov_b32_e32 v121, v39
	v_mov_b32_e32 v126, v22
	v_mov_b32_e32 v127, v6
	v_mov_b32_e32 v136, v86
	v_mov_b32_e32 v137, v90
	v_mov_b32_e32 v148, v24
	v_mov_b32_e32 v149, v8
	v_mov_b32_e32 v154, v92
	v_mov_b32_e32 v155, v96
	v_pk_fma_f32 v[132:133], v[132:133], v[132:133], v[134:135]
	v_pk_mul_f32 v[134:135], v[150:151], v[150:151]
	s_waitcnt vmcnt(7)
	v_mov_b32_e32 v170, v29
	s_waitcnt vmcnt(6)
	v_mov_b32_e32 v171, v13
	v_pk_fma_f32 v[116:117], v[116:117], v[116:117], v[122:123]
	v_pk_fma_f32 v[122:123], v[140:141], v[140:141], v[124:125]
	v_pk_mul_f32 v[124:125], v[156:157], v[156:157]
	s_waitcnt vmcnt(5)
	v_mov_b32_e32 v174, v101
	s_waitcnt vmcnt(4)
	v_mov_b32_e32 v175, v105
	v_mov_b32_e32 v130, v23
	v_mov_b32_e32 v131, v7
	v_mov_b32_e32 v138, v87
	v_mov_b32_e32 v139, v91
	v_mov_b32_e32 v144, v26
	v_mov_b32_e32 v145, v10
	v_mov_b32_e32 v160, v28
	v_mov_b32_e32 v161, v12
	v_mov_b32_e32 v172, v100
	v_mov_b32_e32 v173, v104
	v_pk_fma_f32 v[126:127], v[126:127], v[126:127], v[132:133]
	v_pk_fma_f32 v[132:133], v[148:149], v[148:149], v[134:135]
	v_pk_mul_f32 v[134:135], v[170:171], v[170:171]
	s_waitcnt vmcnt(3)
	v_mov_b32_e32 v178, v33
	s_waitcnt vmcnt(2)
	v_mov_b32_e32 v179, v17
	s_waitcnt vmcnt(0)
	v_pk_add_f32 v[112:113], v[112:113], 1.0 op_sel_hi:[1,0]
	v_pk_fma_f32 v[116:117], v[120:121], v[120:121], v[116:117]
	v_pk_fma_f32 v[120:121], v[136:137], v[136:137], v[122:123]
	v_pk_fma_f32 v[122:123], v[154:155], v[154:155], v[124:125]
	v_pk_mul_f32 v[124:125], v[174:175], v[174:175]
	v_mov_b32_e32 v146, v27
	v_mov_b32_e32 v147, v11
	v_mov_b32_e32 v142, v94
	v_mov_b32_e32 v143, v98
	v_mov_b32_e32 v140, v102
	v_mov_b32_e32 v141, v106
	v_mov_b32_e32 v176, v32
	v_mov_b32_e32 v177, v16
	v_pk_add_f32 v[114:115], v[114:115], 1.0 op_sel_hi:[1,0]
	v_pk_fma_f32 v[126:127], v[130:131], v[130:131], v[126:127]
	v_pk_fma_f32 v[130:131], v[144:145], v[144:145], v[132:133]
	v_pk_fma_f32 v[132:133], v[160:161], v[160:161], v[134:135]
	v_pk_mul_f32 v[134:135], v[178:179], v[178:179]
	v_pk_mul_f32 v[0:1], v[0:1], v[112:113]
	v_pk_fma_f32 v[112:113], v[138:139], v[138:139], v[120:121]
	v_pk_fma_f32 v[120:121], v[172:173], v[172:173], v[124:125]
	v_mov_b32_e32 v152, v95
	v_mov_b32_e32 v153, v99
	v_mov_b32_e32 v150, v30
	v_mov_b32_e32 v151, v14
	v_mov_b32_e32 v156, v103
	v_mov_b32_e32 v157, v107
	v_mov_b32_e32 v148, v34
	v_mov_b32_e32 v149, v18
	v_pk_mul_f32 v[2:3], v[2:3], v[114:115]
	v_pk_fma_f32 v[114:115], v[142:143], v[142:143], v[122:123]
	v_pk_fma_f32 v[122:123], v[146:147], v[146:147], v[130:131]
	v_mov_b32_e32 v125, v116
	v_pk_fma_f32 v[134:135], v[176:177], v[176:177], v[134:135]
	v_pk_fma_f32 v[120:121], v[140:141], v[140:141], v[120:121]
	v_mov_b32_e32 v124, v112
	v_mov_b32_e32 v116, v113
	v_mov_b32_e32 v158, v31
	v_mov_b32_e32 v159, v15
	v_mov_b32_e32 v170, v35
	v_mov_b32_e32 v171, v19
	v_mov_b32_e32 v131, v126
	v_pk_fma_f32 v[132:133], v[150:151], v[150:151], v[132:133]
	v_pk_fma_f32 v[114:115], v[152:153], v[152:153], v[114:115]
	v_mov_b32_e32 v130, v122
	v_mov_b32_e32 v126, v123
	v_pk_fma_f32 v[122:123], v[148:149], v[148:149], v[134:135]
	v_pk_fma_f32 v[120:121], v[156:157], v[156:157], v[120:121]
	v_pk_add_f32 v[116:117], v[124:125], v[116:117]
	v_pk_fma_f32 v[112:113], v[158:159], v[158:159], v[132:133]
	v_pk_fma_f32 v[122:123], v[170:171], v[170:171], v[122:123]
	v_mov_b32_e32 v125, v114
	v_pk_add_f32 v[116:117], v[116:117], v[130:131]
	v_mov_b32_e32 v124, v120
	v_mov_b32_e32 v114, v121
	v_mov_b32_e32 v133, v112
	v_mov_b32_e32 v132, v122
	v_pk_add_f32 v[116:117], v[116:117], v[126:127]
	v_pk_add_f32 v[114:115], v[124:125], v[114:115]
	v_mov_b32_e32 v112, v123
	ds_bpermute_b32 v121, v74, v117
	ds_bpermute_b32 v120, v74, v116
	v_pk_add_f32 v[114:115], v[114:115], v[132:133]
	s_waitcnt lgkmcnt(0)
	v_pk_add_f32 v[116:117], v[116:117], v[120:121]
	v_pk_add_f32 v[112:113], v[114:115], v[112:113]
	ds_bpermute_b32 v115, v74, v113
	ds_bpermute_b32 v114, v74, v112
	ds_bpermute_b32 v121, v75, v117
	ds_bpermute_b32 v120, v75, v116
	s_waitcnt lgkmcnt(2)
	v_pk_add_f32 v[112:113], v[112:113], v[114:115]
	ds_bpermute_b32 v115, v75, v113
	ds_bpermute_b32 v114, v75, v112
	s_waitcnt lgkmcnt(2)
	v_pk_add_f32 v[116:117], v[116:117], v[120:121]
	ds_bpermute_b32 v121, v76, v117
	ds_bpermute_b32 v120, v76, v116
	s_waitcnt lgkmcnt(2)
	v_pk_add_f32 v[112:113], v[112:113], v[114:115]
	ds_bpermute_b32 v115, v76, v113
	ds_bpermute_b32 v114, v76, v112
	s_waitcnt lgkmcnt(2)
	v_pk_add_f32 v[116:117], v[116:117], v[120:121]
	ds_bpermute_b32 v121, v77, v117
	ds_bpermute_b32 v120, v77, v116
	s_waitcnt lgkmcnt(2)
	v_pk_add_f32 v[112:113], v[112:113], v[114:115]
	ds_bpermute_b32 v115, v77, v113
	ds_bpermute_b32 v114, v77, v112
	s_waitcnt lgkmcnt(2)
	v_pk_add_f32 v[116:117], v[116:117], v[120:121]
	ds_bpermute_b32 v121, v78, v117
	ds_bpermute_b32 v120, v78, v116
	s_waitcnt lgkmcnt(2)
	v_pk_add_f32 v[112:113], v[112:113], v[114:115]
	ds_bpermute_b32 v115, v78, v113
	ds_bpermute_b32 v114, v78, v112
	s_waitcnt lgkmcnt(2)
	v_pk_add_f32 v[116:117], v[116:117], v[120:121]
	ds_bpermute_b32 v121, v79, v117
	ds_bpermute_b32 v120, v79, v116
	s_waitcnt lgkmcnt(2)
	v_pk_add_f32 v[112:113], v[112:113], v[114:115]
	ds_bpermute_b32 v115, v79, v113
	ds_bpermute_b32 v114, v79, v112
	s_waitcnt lgkmcnt(2)
	v_pk_add_f32 v[116:117], v[116:117], v[120:121]
	s_waitcnt lgkmcnt(0)
	v_pk_add_f32 v[112:113], v[112:113], v[114:115]
	v_pk_fma_f32 v[116:117], v[116:117], s[24:25], v[64:65] op_sel_hi:[1,0,0]
	v_pk_fma_f32 v[112:113], v[112:113], s[24:25], v[64:65] op_sel_hi:[1,0,0]
	v_mul_f32_e32 v41, 0x4b800000, v117
	v_mul_f32_e32 v120, 0x4b800000, v116
	v_cmp_gt_f32_e32 vcc, s27, v116
	v_cmp_gt_f32_e64 s[4:5], s27, v117
	v_mul_f32_e32 v115, 0x4b800000, v113
	v_cndmask_b32_e32 v114, v116, v120, vcc
	v_cndmask_b32_e64 v41, v117, v41, s[4:5]
	v_rsq_f32_e32 v41, v41
	v_rsq_f32_e32 v114, v114
	v_mul_f32_e32 v116, 0x4b800000, v112
	v_cmp_gt_f32_e64 s[6:7], s27, v112
	v_cmp_gt_f32_e64 s[8:9], s27, v113
	s_nop 0
	v_cndmask_b32_e64 v112, v112, v116, s[6:7]
	v_cndmask_b32_e64 v113, v113, v115, s[8:9]
	v_rsq_f32_e32 v113, v113
	v_rsq_f32_e32 v115, v112
	v_mul_f32_e32 v112, 0x45800000, v41
	v_mul_f32_e32 v116, 0x45800000, v114
	v_cndmask_b32_e64 v112, v41, v112, s[4:5]
	v_cndmask_b32_e32 v114, v114, v116, vcc
	v_pk_mul_f32 v[80:81], v[80:81], v[112:113] op_sel_hi:[1,0]
	v_pk_mul_f32 v[82:83], v[82:83], v[112:113] op_sel_hi:[1,0]
	v_pk_mul_f32 v[84:85], v[84:85], v[114:115] op_sel_hi:[1,0]
	v_pk_mul_f32 v[86:87], v[86:87], v[114:115] op_sel_hi:[1,0]
	v_mul_f32_e32 v41, 0x45800000, v113
	v_mul_f32_e32 v117, 0x45800000, v115
	v_pk_fma_f32 v[80:81], v[80:81], v[0:1], v[108:109]
	v_pk_fma_f32 v[82:83], v[82:83], v[2:3], v[110:111]
	v_pk_fma_f32 v[84:85], v[84:85], v[0:1], v[108:109]
	v_pk_fma_f32 v[86:87], v[86:87], v[2:3], v[110:111]
	v_cndmask_b32_e64 v116, v113, v41, s[8:9]
	v_cndmask_b32_e64 v120, v115, v117, s[6:7]
	v_cvt_pk_bf16_f32 v80, v80, v81
	v_cvt_pk_bf16_f32 v81, v82, v83
	v_cvt_pk_bf16_f32 v82, v84, v85
	v_cvt_pk_bf16_f32 v83, v86, v87
	v_pk_mul_f32 v[84:85], v[92:93], v[116:117] op_sel_hi:[1,0]
	v_pk_mul_f32 v[86:87], v[94:95], v[116:117] op_sel_hi:[1,0]
	v_pk_mul_f32 v[92:93], v[100:101], v[120:121] op_sel_hi:[1,0]
	v_pk_mul_f32 v[94:95], v[102:103], v[120:121] op_sel_hi:[1,0]
	v_pk_fma_f32 v[84:85], v[84:85], v[0:1], v[108:109]
	v_pk_fma_f32 v[86:87], v[86:87], v[2:3], v[110:111]
	v_pk_fma_f32 v[0:1], v[92:93], v[0:1], v[108:109]
	v_pk_fma_f32 v[2:3], v[94:95], v[2:3], v[110:111]
	global_store_dwordx2 v[66:67], v[80:81], off offset:256
	global_store_dwordx2 v[66:67], v[82:83], off offset:2304
	v_cvt_pk_bf16_f32 v80, v84, v85
	v_cvt_pk_bf16_f32 v81, v86, v87
	v_cvt_pk_bf16_f32 v0, v0, v1
	v_cvt_pk_bf16_f32 v1, v2, v3
	global_store_dwordx2 v[68:69], v[80:81], off offset:256
	global_store_dwordx2 v[68:69], v[0:1], off offset:2304
	global_load_dwordx4 v[0:3], v[118:119], off
	s_nop 0
	global_load_dwordx4 v[80:83], v[70:71], off offset:1024
	global_load_dwordx4 v[84:87], v[46:47], off
	v_pk_mul_f32 v[36:37], v[36:37], v[112:113] op_sel_hi:[1,0]
	v_pk_mul_f32 v[38:39], v[38:39], v[112:113] op_sel_hi:[1,0]
	v_pk_mul_f32 v[88:89], v[88:89], v[114:115] op_sel_hi:[1,0]
	v_pk_mul_f32 v[90:91], v[90:91], v[114:115] op_sel_hi:[1,0]
	v_pk_mul_f32 v[94:95], v[96:97], v[116:117] op_sel_hi:[1,0]
	v_pk_mul_f32 v[96:97], v[98:99], v[116:117] op_sel_hi:[1,0]
	v_pk_mul_f32 v[98:99], v[104:105], v[120:121] op_sel_hi:[1,0]
	v_pk_mul_f32 v[100:101], v[106:107], v[120:121] op_sel_hi:[1,0]
	v_lshl_add_u64 v[92:93], v[72:73], 0, v[60:61]
	v_pk_mul_f32 v[20:21], v[20:21], v[112:113] op_sel_hi:[1,0]
	v_pk_mul_f32 v[22:23], v[22:23], v[112:113] op_sel_hi:[1,0]
	v_pk_mul_f32 v[24:25], v[24:25], v[114:115] op_sel_hi:[1,0]
	v_pk_mul_f32 v[26:27], v[26:27], v[114:115] op_sel_hi:[1,0]
	v_pk_mul_f32 v[28:29], v[28:29], v[116:117] op_sel_hi:[1,0]
	v_pk_mul_f32 v[30:31], v[30:31], v[116:117] op_sel_hi:[1,0]
	v_pk_mul_f32 v[32:33], v[32:33], v[120:121] op_sel_hi:[1,0]
	v_pk_mul_f32 v[34:35], v[34:35], v[120:121] op_sel_hi:[1,0]
	v_lshl_add_u64 v[72:73], v[72:73], 0, v[62:63]
	v_pk_mul_f32 v[4:5], v[4:5], v[112:113] op_sel_hi:[1,0]
	v_pk_mul_f32 v[6:7], v[6:7], v[112:113] op_sel_hi:[1,0]
	v_cmp_lt_i32_e32 vcc, s30, v40
	v_pk_mul_f32 v[8:9], v[8:9], v[114:115] op_sel_hi:[1,0]
	v_pk_mul_f32 v[10:11], v[10:11], v[114:115] op_sel_hi:[1,0]
	v_pk_mul_f32 v[12:13], v[12:13], v[116:117] op_sel_hi:[1,0]
	v_pk_mul_f32 v[14:15], v[14:15], v[116:117] op_sel_hi:[1,0]
	v_pk_mul_f32 v[16:17], v[16:17], v[120:121] op_sel_hi:[1,0]
	v_pk_mul_f32 v[18:19], v[18:19], v[120:121] op_sel_hi:[1,0]
	s_or_b64 s[22:23], vcc, s[22:23]
	s_waitcnt vmcnt(2)
	v_pk_add_f32 v[0:1], v[0:1], 1.0 op_sel_hi:[1,0]
	v_pk_add_f32 v[2:3], v[2:3], 1.0 op_sel_hi:[1,0]
	s_waitcnt vmcnt(0)
	v_pk_mul_f32 v[0:1], v[84:85], v[0:1]
	v_pk_mul_f32 v[2:3], v[86:87], v[2:3]
	v_pk_fma_f32 v[36:37], v[36:37], v[0:1], v[80:81]
	v_pk_fma_f32 v[38:39], v[38:39], v[2:3], v[82:83]
	v_pk_fma_f32 v[84:85], v[88:89], v[0:1], v[80:81]
	v_pk_fma_f32 v[86:87], v[90:91], v[2:3], v[82:83]
	v_pk_fma_f32 v[88:89], v[94:95], v[0:1], v[80:81]
	v_pk_fma_f32 v[90:91], v[96:97], v[2:3], v[82:83]
	v_pk_fma_f32 v[0:1], v[98:99], v[0:1], v[80:81]
	v_pk_fma_f32 v[2:3], v[100:101], v[2:3], v[82:83]
	v_cvt_pk_bf16_f32 v36, v36, v37
	v_cvt_pk_bf16_f32 v37, v38, v39
	v_cvt_pk_bf16_f32 v38, v84, v85
	v_cvt_pk_bf16_f32 v39, v86, v87
	v_cvt_pk_bf16_f32 v80, v88, v89
	v_cvt_pk_bf16_f32 v81, v90, v91
	v_cvt_pk_bf16_f32 v0, v0, v1
	v_cvt_pk_bf16_f32 v1, v2, v3
	global_store_dwordx2 v[66:67], v[36:37], off offset:768
	global_store_dwordx2 v[66:67], v[38:39], off offset:2816
	global_store_dwordx2 v[68:69], v[80:81], off offset:768
	global_store_dwordx2 v[68:69], v[0:1], off offset:2816
	global_load_dwordx4 v[0:3], v[92:93], off
	s_nop 0
	global_load_dwordx4 v[36:39], v[70:71], off offset:2048
	global_load_dwordx4 v[80:83], v[48:49], off
	s_waitcnt vmcnt(2)
	v_pk_add_f32 v[0:1], v[0:1], 1.0 op_sel_hi:[1,0]
	v_pk_add_f32 v[2:3], v[2:3], 1.0 op_sel_hi:[1,0]
	s_waitcnt vmcnt(0)
	v_pk_mul_f32 v[0:1], v[80:81], v[0:1]
	v_pk_mul_f32 v[2:3], v[82:83], v[2:3]
	v_pk_fma_f32 v[20:21], v[20:21], v[0:1], v[36:37]
	v_pk_fma_f32 v[22:23], v[22:23], v[2:3], v[38:39]
	v_pk_fma_f32 v[24:25], v[24:25], v[0:1], v[36:37]
	v_pk_fma_f32 v[26:27], v[26:27], v[2:3], v[38:39]
	v_pk_fma_f32 v[28:29], v[28:29], v[0:1], v[36:37]
	v_pk_fma_f32 v[30:31], v[30:31], v[2:3], v[38:39]
	v_pk_fma_f32 v[0:1], v[32:33], v[0:1], v[36:37]
	v_pk_fma_f32 v[2:3], v[34:35], v[2:3], v[38:39]
	v_cvt_pk_bf16_f32 v20, v20, v21
	v_cvt_pk_bf16_f32 v21, v22, v23
	v_cvt_pk_bf16_f32 v22, v24, v25
	v_cvt_pk_bf16_f32 v23, v26, v27
	v_cvt_pk_bf16_f32 v24, v28, v29
	v_cvt_pk_bf16_f32 v25, v30, v31
	v_cvt_pk_bf16_f32 v0, v0, v1
	v_cvt_pk_bf16_f32 v1, v2, v3
	global_store_dwordx2 v[66:67], v[20:21], off offset:1280
	global_store_dwordx2 v[66:67], v[22:23], off offset:3328
	global_store_dwordx2 v[68:69], v[24:25], off offset:1280
	global_store_dwordx2 v[68:69], v[0:1], off offset:3328
	global_load_dwordx4 v[0:3], v[72:73], off
	s_nop 0
	global_load_dwordx4 v[20:23], v[70:71], off offset:3072
	global_load_dwordx4 v[24:27], v[50:51], off
	s_waitcnt vmcnt(2)
	v_pk_add_f32 v[0:1], v[0:1], 1.0 op_sel_hi:[1,0]
	v_pk_add_f32 v[2:3], v[2:3], 1.0 op_sel_hi:[1,0]
	s_waitcnt vmcnt(0)
	v_pk_mul_f32 v[0:1], v[24:25], v[0:1]
	v_pk_mul_f32 v[2:3], v[26:27], v[2:3]
	v_pk_fma_f32 v[4:5], v[4:5], v[0:1], v[20:21]
	v_pk_fma_f32 v[6:7], v[6:7], v[2:3], v[22:23]
	v_pk_fma_f32 v[8:9], v[8:9], v[0:1], v[20:21]
	v_pk_fma_f32 v[10:11], v[10:11], v[2:3], v[22:23]
	v_pk_fma_f32 v[12:13], v[12:13], v[0:1], v[20:21]
	v_pk_fma_f32 v[14:15], v[14:15], v[2:3], v[22:23]
	v_pk_fma_f32 v[0:1], v[16:17], v[0:1], v[20:21]
	v_pk_fma_f32 v[2:3], v[18:19], v[2:3], v[22:23]
	v_cvt_pk_bf16_f32 v4, v4, v5
	v_cvt_pk_bf16_f32 v5, v6, v7
	v_cvt_pk_bf16_f32 v6, v8, v9
	v_cvt_pk_bf16_f32 v7, v10, v11
	v_cvt_pk_bf16_f32 v8, v12, v13
	v_cvt_pk_bf16_f32 v9, v14, v15
	v_cvt_pk_bf16_f32 v0, v0, v1
	v_cvt_pk_bf16_f32 v1, v2, v3
	global_store_dwordx2 v[66:67], v[4:5], off offset:1792
	global_store_dwordx2 v[66:67], v[6:7], off offset:3840
	global_store_dwordx2 v[68:69], v[8:9], off offset:1792
	global_store_dwordx2 v[68:69], v[0:1], off offset:3840
	s_andn2_b64 exec, exec, s[22:23]
	s_cbranch_execnz .LBB0_1078

.Lr13_end:
.LBB0_1274:
	s_cmp_lt_i32 s61, 14
	s_cbranch_scc1 .LBB0_1328
	s_waitcnt vmcnt(0)
	s_barrier
	v_readfirstlane_b32 s2, v162
	s_and_b32 s3, s58, 7
	s_lshl_b32 s3, s3, 8
	s_bfe_u32 s6, s58, 0x30003
	s_lshl_b32 s6, s6, 2
	s_add_u32 s3, s3, s6
	s_add_u32 s3, s3, 0x3840
	s_add_u32 s6, s84, s3
	s_addc_u32 s7, s85, 0
	s_cmp_lg_u32 s2, 0
	s_cbranch_scc1 .Lgs13_wait
	s_mov_b64 s[8:9], exec
	s_mov_b64 exec, 1
	v_mov_b32_e32 v0, 0
	v_mov_b32_e32 v1, 1
	s_mov_b32 s10, 0
	global_atomic_add v0, v1, s[6:7]

.LBB0_1328:
	s_cmp_gt_i32 s60, 14
	s_cselect_b64 s[2:3], -1, 0
	s_cmp_lt_i32 s61, 14
	s_cselect_b64 s[4:5], -1, 0
	s_or_b64 s[2:3], s[2:3], s[4:5]
	s_and_b64 vcc, exec, s[2:3]
	s_cbranch_vccnz .LBB0_1386
	s_and_b32 s96, s58, 63
	s_lshl_b32 s96, s96, 3
	s_lshr_b32 s97, s58, 6
	s_or_b32 s96, s96, s97
	v_and_b32_e32 v0, 60, v163
	v_lshl_add_u32 v40, s96, 4, v0
	s_movk_i32 s2, 0x2000
	s_mov_b64 s[4:5], s[0:1]
	v_cmp_gt_i32_e32 vcc, s2, v40
	s_and_saveexec_b64 s[10:11], vcc
	s_cbranch_execz .LBB0_1332
	v_mbcnt_lo_u32_b32 v1, -1, 0
	v_mbcnt_hi_u32_b32 v1, -1, v1
	v_and_b32_e32 v2, 64, v1
	v_add_u32_e32 v3, 64, v2
	v_xor_b32_e32 v5, 32, v1
	v_cmp_lt_i32_e32 vcc, v5, v3
	s_load_dwordx2 s[2:3], s[4:5], 0x58
	s_load_dwordx2 s[12:13], s[4:5], 0xe0
	v_cndmask_b32_e32 v5, v1, v5, vcc
	v_lshlrev_b32_e32 v74, 2, v5
	v_xor_b32_e32 v5, 16, v1
	v_cmp_lt_i32_e32 vcc, v5, v3
	s_load_dword s6, s[0:1], 0xf0
	s_waitcnt lgkmcnt(0)
	s_add_u32 s2, s2, 0x1000
	v_cndmask_b32_e32 v5, v1, v5, vcc
	v_lshlrev_b32_e32 v75, 2, v5
	v_xor_b32_e32 v5, 8, v1
	v_cmp_lt_i32_e32 vcc, v5, v3
	v_and_b32_e32 v0, 63, v162
	s_addc_u32 s3, s3, 0
	v_cndmask_b32_e32 v5, v1, v5, vcc
	v_lshlrev_b32_e32 v76, 2, v5
	v_xor_b32_e32 v5, 4, v1
	v_cmp_lt_i32_e32 vcc, v5, v3
	v_mov_b32_e32 v43, 0
	v_or_b32_e32 v2, 64, v0
	v_cndmask_b32_e32 v5, v1, v5, vcc
	v_lshlrev_b32_e32 v77, 2, v5
	v_xor_b32_e32 v5, 2, v1
	v_cmp_lt_i32_e32 vcc, v5, v3
	s_add_u32 s4, s12, 0x6b05000
	v_or_b32_e32 v4, 0x80, v0
	v_cndmask_b32_e32 v5, v1, v5, vcc
	v_lshlrev_b32_e32 v78, 2, v5
	v_xor_b32_e32 v5, 1, v1
	v_lshlrev_b32_e32 v8, 4, v2
	v_mov_b32_e32 v9, v43
	s_addc_u32 s5, s13, 0
	s_lshl_b32 s16, s6, 4
	v_or_b32_e32 v6, 0xc0, v0
	v_cmp_lt_i32_e32 vcc, v5, v3
	v_lshl_add_u64 v[46:47], s[2:3], 0, v[8:9]
	v_lshlrev_b32_e32 v8, 4, v4
	v_ashrrev_i32_e32 v41, 31, v40
	v_cndmask_b32_e32 v1, v1, v5, vcc
	v_lshlrev_b32_e32 v42, 4, v0
	s_waitcnt vmcnt(35)
	v_lshl_add_u64 v[48:49], s[2:3], 0, v[8:9]
	v_lshlrev_b32_e32 v8, 4, v6
	s_waitcnt vmcnt(34)
	v_lshlrev_b64 v[52:53], 11, v[40:41]
	s_ashr_i32 s17, s16, 31
	v_lshlrev_b64 v[54:55], 12, v[40:41]
	s_waitcnt vmcnt(33)
	v_mov_b64_e32 v[56:57], s[4:5]
	s_mov_b32 s4, 0x358637bd
	s_mov_b64 s[14:15], 0x1000
	v_lshlrev_b32_e32 v79, 2, v1
	v_lshl_add_u64 v[44:45], s[2:3], 0, v[42:43]
	v_lshl_add_u64 v[50:51], s[2:3], 0, v[8:9]
	v_lshl_or_b32 v52, v0, 3, v52
	s_lshl_b64 s[18:19], s[16:17], 11
	v_or_b32_e32 v54, v54, v42
	s_lshl_b64 s[20:21], s[16:17], 12
	s_mov_b64 s[22:23], 0
	s_movk_i32 s2, 0xfff
	s_movk_i32 s3, 0x6000
	v_lshlrev_b32_e32 v42, 4, v0
	s_mov_b32 s17, 0x6b7b000
	s_mov_b32 s25, 0x6b7c000
	s_mov_b32 s26, 0x6b7d000
	v_lshlrev_b32_e32 v58, 4, v2
	v_mov_b32_e32 v59, v43
	s_waitcnt vmcnt(32)
	v_lshlrev_b32_e32 v60, 4, v4
	v_mov_b32_e32 v61, v43
	v_lshlrev_b32_e32 v62, 4, v6
	v_mov_b32_e32 v63, v43
	s_mov_b32 s24, 0x3a800000
	v_mov_b64_e32 v[64:65], s[4:5]
	s_mov_b32 s27, 0x800000
	s_mov_b32 s28, 0x8b7a000
	s_mov_b32 s29, 0x8b7b000
	s_movk_i32 s30, 0x1fff

.Lr16_end:
.LBB0_1456:
	s_cmp_lt_i32 s61, 17
	s_cbranch_scc1 .LBB0_1510
	s_waitcnt vmcnt(0)
	s_barrier
	v_readfirstlane_b32 s2, v162
	s_and_b32 s3, s58, 7
	s_lshl_b32 s3, s3, 8
	s_bfe_u32 s6, s58, 0x30003
	s_lshl_b32 s6, s6, 2
	s_add_u32 s3, s3, s6
	s_add_u32 s3, s3, 0x3860
	s_add_u32 s6, s84, s3
	s_addc_u32 s7, s85, 0
	s_cmp_lg_u32 s2, 0
	s_cbranch_scc1 .Lgs16_wait
	s_mov_b64 s[8:9], exec
	s_mov_b64 exec, 1
	v_mov_b32_e32 v0, 0
	v_mov_b32_e32 v1, 1
	s_mov_b32 s10, 0
	global_atomic_add v0, v1, s[6:7]

.LBB0_1510:
	s_cmp_gt_i32 s60, 17
	s_cselect_b64 s[2:3], -1, 0
	s_cmp_lt_i32 s61, 17
	s_cselect_b64 s[4:5], -1, 0
	s_or_b64 s[2:3], s[2:3], s[4:5]
	s_and_b64 vcc, exec, s[2:3]
	s_cbranch_vccnz .LBB0_1573
	s_and_b32 s96, s58, 63
	s_lshl_b32 s96, s96, 3
	s_lshr_b32 s97, s58, 6
	s_or_b32 s96, s96, s97
	s_mov_b64 s[12:13], s[0:1]
	s_load_dwordx2 s[14:15], s[12:13], 0xe0
	s_load_dword s2, s[0:1], 0xf0
	v_and_b32_e32 v0, 60, v163
	s_add_u32 s10, s0, 0xf0
	v_lshl_add_u32 v40, s96, 4, v0
	s_movk_i32 s3, 0x2000
	s_addc_u32 s11, s1, 0
	v_cmp_gt_i32_e32 vcc, s3, v40
	s_and_saveexec_b64 s[16:17], vcc
	s_cbranch_execz .LBB0_1514
	v_mbcnt_lo_u32_b32 v1, -1, 0
	v_mbcnt_hi_u32_b32 v1, -1, v1
	v_and_b32_e32 v2, 64, v1
	v_add_u32_e32 v3, 64, v2
	v_xor_b32_e32 v5, 32, v1
	v_cmp_lt_i32_e32 vcc, v5, v3
	s_load_dwordx2 s[4:5], s[12:13], 0x50
	s_waitcnt lgkmcnt(0)
	s_add_u32 s6, s14, 0x6b02000
	v_cndmask_b32_e32 v5, v1, v5, vcc
	v_lshlrev_b32_e32 v74, 2, v5
	v_xor_b32_e32 v5, 16, v1
	v_cmp_lt_i32_e32 vcc, v5, v3
	v_and_b32_e32 v0, 63, v162
	s_addc_u32 s7, s15, 0
	v_cndmask_b32_e32 v5, v1, v5, vcc
	v_lshlrev_b32_e32 v75, 2, v5
	v_xor_b32_e32 v5, 8, v1
	v_cmp_lt_i32_e32 vcc, v5, v3
	s_add_u32 s4, s4, 0x2000
	v_mov_b32_e32 v43, 0
	v_cndmask_b32_e32 v5, v1, v5, vcc
	v_lshlrev_b32_e32 v76, 2, v5
	v_xor_b32_e32 v5, 4, v1
	v_cmp_lt_i32_e32 vcc, v5, v3
	v_or_b32_e32 v2, 64, v0
	s_addc_u32 s5, s5, 0
	v_cndmask_b32_e32 v5, v1, v5, vcc
	v_lshlrev_b32_e32 v77, 2, v5
	v_xor_b32_e32 v5, 2, v1
	v_cmp_lt_i32_e32 vcc, v5, v3
	v_or_b32_e32 v4, 0x80, v0
	v_lshlrev_b32_e32 v8, 4, v2
	v_cndmask_b32_e32 v5, v1, v5, vcc
	v_mov_b32_e32 v9, v43
	v_or_b32_e32 v6, 0xc0, v0
	v_lshlrev_b32_e32 v78, 2, v5
	v_xor_b32_e32 v5, 1, v1
	v_lshl_add_u64 v[46:47], s[4:5], 0, v[8:9]
	v_lshlrev_b32_e32 v8, 4, v4
	s_lshl_b32 s18, s2, 4
	v_cmp_lt_i32_e32 vcc, v5, v3
	v_lshlrev_b32_e32 v42, 4, v0
	s_waitcnt vmcnt(35)
	v_lshl_add_u64 v[48:49], s[4:5], 0, v[8:9]
	v_lshlrev_b32_e32 v8, 4, v6
	v_ashrrev_i32_e32 v41, 31, v40
	v_cndmask_b32_e32 v1, v1, v5, vcc
	v_lshl_add_u64 v[44:45], s[4:5], 0, v[42:43]
	v_lshl_add_u64 v[50:51], s[4:5], 0, v[8:9]
	s_waitcnt vmcnt(34)
	v_lshlrev_b64 v[52:53], 11, v[40:41]
	s_ashr_i32 s19, s18, 31
	v_lshlrev_b64 v[54:55], 12, v[40:41]
	s_mov_b32 s4, 0x358637bd
	v_lshlrev_b32_e32 v79, 2, v1
	v_lshl_or_b32 v52, v0, 3, v52
	s_lshl_b64 s[20:21], s[18:19], 11
	v_or_b32_e32 v54, v54, v42
	s_lshl_b64 s[22:23], s[18:19], 12
	s_mov_b64 s[24:25], 0
	s_movk_i32 s3, 0xfff
	s_movk_i32 s19, 0x6000
	s_waitcnt vmcnt(33)
	v_mov_b64_e32 v[56:57], s[6:7]
	s_mov_b64 s[26:27], 0x1000
	v_lshlrev_b32_e32 v42, 4, v0
	s_mov_b32 s29, 0x6b7b000
	s_mov_b32 s30, 0x6b7c000
	s_mov_b32 s31, 0x6b7d000
	v_lshlrev_b32_e32 v58, 4, v2
	v_mov_b32_e32 v59, v43
	s_waitcnt vmcnt(32)
	v_lshlrev_b32_e32 v60, 4, v4
	v_mov_b32_e32 v61, v43
	v_lshlrev_b32_e32 v62, 4, v6
	v_mov_b32_e32 v63, v43
	s_mov_b32 s28, 0x3a800000
	v_mov_b64_e32 v[64:65], s[4:5]
	s_mov_b32 s34, 0x800000
	s_mov_b32 s35, 0x8b7a000
	s_mov_b32 s36, 0x8b7b000
	s_movk_i32 s37, 0x1fff
.LBB0_1513:
	v_lshl_add_u64 v[16:17], s[14:15], 0, v[54:55]
	v_lshl_add_u64 v[4:5], s[14:15], 0, v[52:53]
	v_add_co_u32_e32 v8, vcc, 0x6b7a000, v16
	v_add_co_u32_e64 v66, s[4:5], s35, v4
	s_nop 0
	v_addc_co_u32_e32 v9, vcc, 0, v17, vcc
	v_addc_co_u32_e64 v67, s[4:5], 0, v5, s[4:5]
	v_add_u32_e32 v6, 0xfffff000, v40
	v_add_co_u32_e64 v68, s[4:5], s36, v4
	v_add_co_u32_e32 v12, vcc, s29, v16
	v_lshrrev_b32_e32 v6, 10, v6
	v_addc_co_u32_e64 v69, s[4:5], 0, v5, s[4:5]
	v_addc_co_u32_e32 v13, vcc, 0, v17, vcc
	v_add_u32_e32 v10, 11, v6
	v_cmp_lt_i32_e64 s[4:5], s3, v40
	v_add_co_u32_e32 v18, vcc, s30, v16
	global_load_dwordx4 v[0:3], v[44:45], off
	global_load_dwordx4 v[80:83], v[8:9], off offset:256 sc0 sc1
	global_load_dwordx4 v[36:39], v[8:9], off offset:1280 sc0 sc1
	global_load_dwordx4 v[20:23], v[8:9], off offset:2304 sc0 sc1
	global_load_dwordx4 v[4:7], v[8:9], off offset:3328 sc0 sc1
	v_cndmask_b32_e64 v14, 10, v10, s[4:5]
	v_addc_co_u32_e32 v19, vcc, 0, v17, vcc
	global_load_dwordx4 v[84:87], v[12:13], off offset:256 sc0 sc1
	global_load_dwordx4 v[88:91], v[12:13], off offset:1280 sc0 sc1
	global_load_dwordx4 v[24:27], v[12:13], off offset:2304 sc0 sc1
	global_load_dwordx4 v[8:11], v[12:13], off offset:3328 sc0 sc1
	v_mad_u64_u32 v[32:33], s[4:5], v14, s19, v[56:57]
	v_add_co_u32_e32 v108, vcc, s31, v16
	global_load_dwordx4 v[92:95], v[18:19], off offset:256 sc0 sc1
	global_load_dwordx4 v[96:99], v[18:19], off offset:1280 sc0 sc1
	global_load_dwordx4 v[28:31], v[18:19], off offset:2304 sc0 sc1
	global_load_dwordx4 v[12:15], v[18:19], off offset:3328 sc0 sc1
	v_lshl_add_u64 v[72:73], v[32:33], 0, s[26:27]
	v_lshl_add_u64 v[70:71], v[32:33], 0, v[42:43]
	v_addc_co_u32_e32 v109, vcc, 0, v17, vcc
	global_load_dwordx4 v[100:103], v[108:109], off offset:256 sc0 sc1
	global_load_dwordx4 v[104:107], v[108:109], off offset:1280 sc0 sc1
	global_load_dwordx4 v[32:35], v[108:109], off offset:2304 sc0 sc1
	global_load_dwordx4 v[16:19], v[108:109], off offset:3328 sc0 sc1
	v_lshl_add_u64 v[116:117], v[72:73], 0, v[42:43]
	global_load_dwordx4 v[108:111], v[70:71], off
	global_load_dwordx4 v[112:115], v[116:117], off
	v_lshl_add_u64 v[118:119], v[72:73], 0, v[58:59]
	v_add_u32_e32 v40, s18, v40
	v_lshl_add_u64 v[52:53], v[52:53], 0, s[20:21]
	v_lshl_add_u64 v[54:55], v[54:55], 0, s[22:23]
	s_waitcnt vmcnt(17)
	v_mov_b32_e32 v124, v81
	s_waitcnt vmcnt(16)
	v_mov_b32_e32 v125, v37
	v_mov_b32_e32 v122, v80
	v_mov_b32_e32 v123, v36
	s_waitcnt vmcnt(15)
	v_mov_b32_e32 v134, v21
	s_waitcnt vmcnt(14)
	v_mov_b32_e32 v135, v5
	v_pk_mul_f32 v[124:125], v[124:125], v[124:125]
	s_waitcnt vmcnt(13)
	v_mov_b32_e32 v142, v85
	s_waitcnt vmcnt(12)
	v_mov_b32_e32 v143, v89
	v_mov_b32_e32 v116, v82
	v_mov_b32_e32 v117, v38
	v_mov_b32_e32 v132, v20
	v_mov_b32_e32 v133, v4
	v_mov_b32_e32 v140, v84
	v_mov_b32_e32 v141, v88
	v_pk_mul_f32 v[134:135], v[134:135], v[134:135]
	s_waitcnt vmcnt(11)
	v_mov_b32_e32 v150, v25
	s_waitcnt vmcnt(10)
	v_mov_b32_e32 v151, v9
	v_pk_fma_f32 v[122:123], v[122:123], v[122:123], v[124:125]
	v_pk_mul_f32 v[124:125], v[142:143], v[142:143]
	s_waitcnt vmcnt(9)
	v_mov_b32_e32 v156, v93
	s_waitcnt vmcnt(8)
	v_mov_b32_e32 v157, v97
	v_mov_b32_e32 v120, v83
	v_mov_b32_e32 v121, v39
	v_mov_b32_e32 v126, v22
	v_mov_b32_e32 v127, v6
	v_mov_b32_e32 v136, v86
	v_mov_b32_e32 v137, v90
	v_mov_b32_e32 v148, v24
	v_mov_b32_e32 v149, v8
	v_mov_b32_e32 v154, v92
	v_mov_b32_e32 v155, v96
	v_pk_fma_f32 v[132:133], v[132:133], v[132:133], v[134:135]
	v_pk_mul_f32 v[134:135], v[150:151], v[150:151]
	s_waitcnt vmcnt(7)
	v_mov_b32_e32 v170, v29
	s_waitcnt vmcnt(6)
	v_mov_b32_e32 v171, v13
	v_pk_fma_f32 v[116:117], v[116:117], v[116:117], v[122:123]
	v_pk_fma_f32 v[122:123], v[140:141], v[140:141], v[124:125]
	v_pk_mul_f32 v[124:125], v[156:157], v[156:157]
	s_waitcnt vmcnt(5)
	v_mov_b32_e32 v174, v101
	s_waitcnt vmcnt(4)
	v_mov_b32_e32 v175, v105
	v_mov_b32_e32 v130, v23
	v_mov_b32_e32 v131, v7
	v_mov_b32_e32 v138, v87
	v_mov_b32_e32 v139, v91
	v_mov_b32_e32 v144, v26
	v_mov_b32_e32 v145, v10
	v_mov_b32_e32 v160, v28
	v_mov_b32_e32 v161, v12
	v_mov_b32_e32 v172, v100
	v_mov_b32_e32 v173, v104
	v_pk_fma_f32 v[126:127], v[126:127], v[126:127], v[132:133]
	v_pk_fma_f32 v[132:133], v[148:149], v[148:149], v[134:135]
	v_pk_mul_f32 v[134:135], v[170:171], v[170:171]
	s_waitcnt vmcnt(3)
	v_mov_b32_e32 v178, v33
	s_waitcnt vmcnt(2)
	v_mov_b32_e32 v179, v17
	s_waitcnt vmcnt(0)
	v_pk_add_f32 v[112:113], v[112:113], 1.0 op_sel_hi:[1,0]
	v_pk_fma_f32 v[116:117], v[120:121], v[120:121], v[116:117]
	v_pk_fma_f32 v[120:121], v[136:137], v[136:137], v[122:123]
	v_pk_fma_f32 v[122:123], v[154:155], v[154:155], v[124:125]
	v_pk_mul_f32 v[124:125], v[174:175], v[174:175]
	v_mov_b32_e32 v146, v27
	v_mov_b32_e32 v147, v11
	v_mov_b32_e32 v142, v94
	v_mov_b32_e32 v143, v98
	v_mov_b32_e32 v140, v102
	v_mov_b32_e32 v141, v106
	v_mov_b32_e32 v176, v32
	v_mov_b32_e32 v177, v16
	v_pk_add_f32 v[114:115], v[114:115], 1.0 op_sel_hi:[1,0]
	v_pk_fma_f32 v[126:127], v[130:131], v[130:131], v[126:127]
	v_pk_fma_f32 v[130:131], v[144:145], v[144:145], v[132:133]
	v_pk_fma_f32 v[132:133], v[160:161], v[160:161], v[134:135]
	v_pk_mul_f32 v[134:135], v[178:179], v[178:179]
	v_pk_mul_f32 v[0:1], v[0:1], v[112:113]
	v_pk_fma_f32 v[112:113], v[138:139], v[138:139], v[120:121]
	v_pk_fma_f32 v[120:121], v[172:173], v[172:173], v[124:125]
	v_mov_b32_e32 v152, v95
	v_mov_b32_e32 v153, v99
	v_mov_b32_e32 v150, v30
	v_mov_b32_e32 v151, v14
	v_mov_b32_e32 v156, v103
	v_mov_b32_e32 v157, v107
	v_mov_b32_e32 v148, v34
	v_mov_b32_e32 v149, v18
	v_pk_mul_f32 v[2:3], v[2:3], v[114:115]
	v_pk_fma_f32 v[114:115], v[142:143], v[142:143], v[122:123]
	v_pk_fma_f32 v[122:123], v[146:147], v[146:147], v[130:131]
	v_mov_b32_e32 v125, v116
	v_pk_fma_f32 v[134:135], v[176:177], v[176:177], v[134:135]
	v_pk_fma_f32 v[120:121], v[140:141], v[140:141], v[120:121]
	v_mov_b32_e32 v124, v112
	v_mov_b32_e32 v116, v113
	v_mov_b32_e32 v158, v31
	v_mov_b32_e32 v159, v15
	v_mov_b32_e32 v170, v35
	v_mov_b32_e32 v171, v19
	v_mov_b32_e32 v131, v126
	v_pk_fma_f32 v[132:133], v[150:151], v[150:151], v[132:133]
	v_pk_fma_f32 v[114:115], v[152:153], v[152:153], v[114:115]
	v_mov_b32_e32 v130, v122
	v_mov_b32_e32 v126, v123
	v_pk_fma_f32 v[122:123], v[148:149], v[148:149], v[134:135]
	v_pk_fma_f32 v[120:121], v[156:157], v[156:157], v[120:121]
	v_pk_add_f32 v[116:117], v[124:125], v[116:117]
	v_pk_fma_f32 v[112:113], v[158:159], v[158:159], v[132:133]
	v_pk_fma_f32 v[122:123], v[170:171], v[170:171], v[122:123]
	v_mov_b32_e32 v125, v114
	v_pk_add_f32 v[116:117], v[116:117], v[130:131]
	v_mov_b32_e32 v124, v120
	v_mov_b32_e32 v114, v121
	v_mov_b32_e32 v133, v112
	v_mov_b32_e32 v132, v122
	v_pk_add_f32 v[116:117], v[116:117], v[126:127]
	v_pk_add_f32 v[114:115], v[124:125], v[114:115]
	v_mov_b32_e32 v112, v123
	ds_bpermute_b32 v121, v74, v117
	ds_bpermute_b32 v120, v74, v116
	v_pk_add_f32 v[114:115], v[114:115], v[132:133]
	s_waitcnt lgkmcnt(0)
	v_pk_add_f32 v[116:117], v[116:117], v[120:121]
	v_pk_add_f32 v[112:113], v[114:115], v[112:113]
	ds_bpermute_b32 v115, v74, v113
	ds_bpermute_b32 v114, v74, v112
	ds_bpermute_b32 v121, v75, v117
	ds_bpermute_b32 v120, v75, v116
	s_waitcnt lgkmcnt(2)
	v_pk_add_f32 v[112:113], v[112:113], v[114:115]
	ds_bpermute_b32 v115, v75, v113
	ds_bpermute_b32 v114, v75, v112
	s_waitcnt lgkmcnt(2)
	v_pk_add_f32 v[116:117], v[116:117], v[120:121]
	ds_bpermute_b32 v121, v76, v117
	ds_bpermute_b32 v120, v76, v116
	s_waitcnt lgkmcnt(2)
	v_pk_add_f32 v[112:113], v[112:113], v[114:115]
	ds_bpermute_b32 v115, v76, v113
	ds_bpermute_b32 v114, v76, v112
	s_waitcnt lgkmcnt(2)
	v_pk_add_f32 v[116:117], v[116:117], v[120:121]
	ds_bpermute_b32 v121, v77, v117
	ds_bpermute_b32 v120, v77, v116
	s_waitcnt lgkmcnt(2)
	v_pk_add_f32 v[112:113], v[112:113], v[114:115]
	ds_bpermute_b32 v115, v77, v113
	ds_bpermute_b32 v114, v77, v112
	s_waitcnt lgkmcnt(2)
	v_pk_add_f32 v[116:117], v[116:117], v[120:121]
	ds_bpermute_b32 v121, v78, v117
	ds_bpermute_b32 v120, v78, v116
	s_waitcnt lgkmcnt(2)
	v_pk_add_f32 v[112:113], v[112:113], v[114:115]
	ds_bpermute_b32 v115, v78, v113
	ds_bpermute_b32 v114, v78, v112
	s_waitcnt lgkmcnt(2)
	v_pk_add_f32 v[116:117], v[116:117], v[120:121]
	ds_bpermute_b32 v121, v79, v117
	ds_bpermute_b32 v120, v79, v116
	s_waitcnt lgkmcnt(2)
	v_pk_add_f32 v[112:113], v[112:113], v[114:115]
	ds_bpermute_b32 v115, v79, v113
	ds_bpermute_b32 v114, v79, v112
	s_waitcnt lgkmcnt(2)
	v_pk_add_f32 v[116:117], v[116:117], v[120:121]
	s_waitcnt lgkmcnt(0)
	v_pk_add_f32 v[112:113], v[112:113], v[114:115]
	v_pk_fma_f32 v[116:117], v[116:117], s[28:29], v[64:65] op_sel_hi:[1,0,0]
	v_pk_fma_f32 v[112:113], v[112:113], s[28:29], v[64:65] op_sel_hi:[1,0,0]
	v_mul_f32_e32 v41, 0x4b800000, v117
	v_mul_f32_e32 v120, 0x4b800000, v116
	v_cmp_gt_f32_e32 vcc, s34, v116
	v_cmp_gt_f32_e64 s[4:5], s34, v117
	v_mul_f32_e32 v115, 0x4b800000, v113
	v_cndmask_b32_e32 v114, v116, v120, vcc
	v_cndmask_b32_e64 v41, v117, v41, s[4:5]
	v_rsq_f32_e32 v41, v41
	v_rsq_f32_e32 v114, v114
	v_mul_f32_e32 v116, 0x4b800000, v112
	v_cmp_gt_f32_e64 s[6:7], s34, v112
	v_cmp_gt_f32_e64 s[8:9], s34, v113
	s_nop 0
	v_cndmask_b32_e64 v112, v112, v116, s[6:7]
	v_cndmask_b32_e64 v113, v113, v115, s[8:9]
	v_rsq_f32_e32 v113, v113
	v_rsq_f32_e32 v115, v112
	v_mul_f32_e32 v112, 0x45800000, v41
	v_mul_f32_e32 v116, 0x45800000, v114
	v_cndmask_b32_e64 v112, v41, v112, s[4:5]
	v_cndmask_b32_e32 v114, v114, v116, vcc
	v_pk_mul_f32 v[80:81], v[80:81], v[112:113] op_sel_hi:[1,0]
	v_pk_mul_f32 v[82:83], v[82:83], v[112:113] op_sel_hi:[1,0]
	v_pk_mul_f32 v[84:85], v[84:85], v[114:115] op_sel_hi:[1,0]
	v_pk_mul_f32 v[86:87], v[86:87], v[114:115] op_sel_hi:[1,0]
	v_mul_f32_e32 v41, 0x45800000, v113
	v_mul_f32_e32 v117, 0x45800000, v115
	v_pk_fma_f32 v[80:81], v[80:81], v[0:1], v[108:109]
	v_pk_fma_f32 v[82:83], v[82:83], v[2:3], v[110:111]
	v_pk_fma_f32 v[84:85], v[84:85], v[0:1], v[108:109]
	v_pk_fma_f32 v[86:87], v[86:87], v[2:3], v[110:111]
	v_cndmask_b32_e64 v116, v113, v41, s[8:9]
	v_cndmask_b32_e64 v120, v115, v117, s[6:7]
	v_cvt_pk_bf16_f32 v80, v80, v81
	v_cvt_pk_bf16_f32 v81, v82, v83
	v_cvt_pk_bf16_f32 v82, v84, v85
	v_cvt_pk_bf16_f32 v83, v86, v87
	v_pk_mul_f32 v[84:85], v[92:93], v[116:117] op_sel_hi:[1,0]
	v_pk_mul_f32 v[86:87], v[94:95], v[116:117] op_sel_hi:[1,0]
	v_pk_mul_f32 v[92:93], v[100:101], v[120:121] op_sel_hi:[1,0]
	v_pk_mul_f32 v[94:95], v[102:103], v[120:121] op_sel_hi:[1,0]
	v_pk_fma_f32 v[84:85], v[84:85], v[0:1], v[108:109]
	v_pk_fma_f32 v[86:87], v[86:87], v[2:3], v[110:111]
	v_pk_fma_f32 v[0:1], v[92:93], v[0:1], v[108:109]
	v_pk_fma_f32 v[2:3], v[94:95], v[2:3], v[110:111]
	global_store_dwordx2 v[66:67], v[80:81], off offset:256
	global_store_dwordx2 v[66:67], v[82:83], off offset:2304
	v_cvt_pk_bf16_f32 v80, v84, v85
	v_cvt_pk_bf16_f32 v81, v86, v87
	v_cvt_pk_bf16_f32 v0, v0, v1
	v_cvt_pk_bf16_f32 v1, v2, v3
	global_store_dwordx2 v[68:69], v[80:81], off offset:256
	global_store_dwordx2 v[68:69], v[0:1], off offset:2304
	global_load_dwordx4 v[0:3], v[118:119], off
	s_nop 0
	global_load_dwordx4 v[80:83], v[70:71], off offset:1024
	global_load_dwordx4 v[84:87], v[46:47], off
	v_pk_mul_f32 v[36:37], v[36:37], v[112:113] op_sel_hi:[1,0]
	v_pk_mul_f32 v[38:39], v[38:39], v[112:113] op_sel_hi:[1,0]
	v_pk_mul_f32 v[88:89], v[88:89], v[114:115] op_sel_hi:[1,0]
	v_pk_mul_f32 v[90:91], v[90:91], v[114:115] op_sel_hi:[1,0]
	v_pk_mul_f32 v[94:95], v[96:97], v[116:117] op_sel_hi:[1,0]
	v_pk_mul_f32 v[96:97], v[98:99], v[116:117] op_sel_hi:[1,0]
	v_pk_mul_f32 v[98:99], v[104:105], v[120:121] op_sel_hi:[1,0]
	v_pk_mul_f32 v[100:101], v[106:107], v[120:121] op_sel_hi:[1,0]
	v_lshl_add_u64 v[92:93], v[72:73], 0, v[60:61]
	v_pk_mul_f32 v[20:21], v[20:21], v[112:113] op_sel_hi:[1,0]
	v_pk_mul_f32 v[22:23], v[22:23], v[112:113] op_sel_hi:[1,0]
	v_pk_mul_f32 v[24:25], v[24:25], v[114:115] op_sel_hi:[1,0]
	v_pk_mul_f32 v[26:27], v[26:27], v[114:115] op_sel_hi:[1,0]
	v_pk_mul_f32 v[28:29], v[28:29], v[116:117] op_sel_hi:[1,0]
	v_pk_mul_f32 v[30:31], v[30:31], v[116:117] op_sel_hi:[1,0]
	v_pk_mul_f32 v[32:33], v[32:33], v[120:121] op_sel_hi:[1,0]
	v_pk_mul_f32 v[34:35], v[34:35], v[120:121] op_sel_hi:[1,0]
	v_lshl_add_u64 v[72:73], v[72:73], 0, v[62:63]
	v_pk_mul_f32 v[4:5], v[4:5], v[112:113] op_sel_hi:[1,0]
	v_pk_mul_f32 v[6:7], v[6:7], v[112:113] op_sel_hi:[1,0]
	v_cmp_lt_i32_e32 vcc, s37, v40
	v_pk_mul_f32 v[8:9], v[8:9], v[114:115] op_sel_hi:[1,0]
	v_pk_mul_f32 v[10:11], v[10:11], v[114:115] op_sel_hi:[1,0]
	v_pk_mul_f32 v[12:13], v[12:13], v[116:117] op_sel_hi:[1,0]
	v_pk_mul_f32 v[14:15], v[14:15], v[116:117] op_sel_hi:[1,0]
	v_pk_mul_f32 v[16:17], v[16:17], v[120:121] op_sel_hi:[1,0]
	v_pk_mul_f32 v[18:19], v[18:19], v[120:121] op_sel_hi:[1,0]
	s_or_b64 s[24:25], vcc, s[24:25]
	s_waitcnt vmcnt(2)
	v_pk_add_f32 v[0:1], v[0:1], 1.0 op_sel_hi:[1,0]
	v_pk_add_f32 v[2:3], v[2:3], 1.0 op_sel_hi:[1,0]
	s_waitcnt vmcnt(0)
	v_pk_mul_f32 v[0:1], v[84:85], v[0:1]
	v_pk_mul_f32 v[2:3], v[86:87], v[2:3]
	v_pk_fma_f32 v[36:37], v[36:37], v[0:1], v[80:81]
	v_pk_fma_f32 v[38:39], v[38:39], v[2:3], v[82:83]
	v_pk_fma_f32 v[84:85], v[88:89], v[0:1], v[80:81]
	v_pk_fma_f32 v[86:87], v[90:91], v[2:3], v[82:83]
	v_pk_fma_f32 v[88:89], v[94:95], v[0:1], v[80:81]
	v_pk_fma_f32 v[90:91], v[96:97], v[2:3], v[82:83]
	v_pk_fma_f32 v[0:1], v[98:99], v[0:1], v[80:81]
	v_pk_fma_f32 v[2:3], v[100:101], v[2:3], v[82:83]
	v_cvt_pk_bf16_f32 v36, v36, v37
	v_cvt_pk_bf16_f32 v37, v38, v39
	v_cvt_pk_bf16_f32 v38, v84, v85
	v_cvt_pk_bf16_f32 v39, v86, v87
	v_cvt_pk_bf16_f32 v80, v88, v89
	v_cvt_pk_bf16_f32 v81, v90, v91
	v_cvt_pk_bf16_f32 v0, v0, v1
	v_cvt_pk_bf16_f32 v1, v2, v3
	global_store_dwordx2 v[66:67], v[36:37], off offset:768
	global_store_dwordx2 v[66:67], v[38:39], off offset:2816
	global_store_dwordx2 v[68:69], v[80:81], off offset:768
	global_store_dwordx2 v[68:69], v[0:1], off offset:2816
	global_load_dwordx4 v[0:3], v[92:93], off
	s_nop 0
	global_load_dwordx4 v[36:39], v[70:71], off offset:2048
	global_load_dwordx4 v[80:83], v[48:49], off
	s_waitcnt vmcnt(2)
	v_pk_add_f32 v[0:1], v[0:1], 1.0 op_sel_hi:[1,0]
	v_pk_add_f32 v[2:3], v[2:3], 1.0 op_sel_hi:[1,0]
	s_waitcnt vmcnt(0)
	v_pk_mul_f32 v[0:1], v[80:81], v[0:1]
	v_pk_mul_f32 v[2:3], v[82:83], v[2:3]
	v_pk_fma_f32 v[20:21], v[20:21], v[0:1], v[36:37]
	v_pk_fma_f32 v[22:23], v[22:23], v[2:3], v[38:39]
	v_pk_fma_f32 v[24:25], v[24:25], v[0:1], v[36:37]
	v_pk_fma_f32 v[26:27], v[26:27], v[2:3], v[38:39]
	v_pk_fma_f32 v[28:29], v[28:29], v[0:1], v[36:37]
	v_pk_fma_f32 v[30:31], v[30:31], v[2:3], v[38:39]
	v_pk_fma_f32 v[0:1], v[32:33], v[0:1], v[36:37]
	v_pk_fma_f32 v[2:3], v[34:35], v[2:3], v[38:39]
	v_cvt_pk_bf16_f32 v20, v20, v21
	v_cvt_pk_bf16_f32 v21, v22, v23
	v_cvt_pk_bf16_f32 v22, v24, v25
	v_cvt_pk_bf16_f32 v23, v26, v27
	v_cvt_pk_bf16_f32 v24, v28, v29
	v_cvt_pk_bf16_f32 v25, v30, v31
	v_cvt_pk_bf16_f32 v0, v0, v1
	v_cvt_pk_bf16_f32 v1, v2, v3
	global_store_dwordx2 v[66:67], v[20:21], off offset:1280
	global_store_dwordx2 v[66:67], v[22:23], off offset:3328
	global_store_dwordx2 v[68:69], v[24:25], off offset:1280
	global_store_dwordx2 v[68:69], v[0:1], off offset:3328
	global_load_dwordx4 v[0:3], v[72:73], off
	s_nop 0
	global_load_dwordx4 v[20:23], v[70:71], off offset:3072
	global_load_dwordx4 v[24:27], v[50:51], off
	s_waitcnt vmcnt(2)
	v_pk_add_f32 v[0:1], v[0:1], 1.0 op_sel_hi:[1,0]
	v_pk_add_f32 v[2:3], v[2:3], 1.0 op_sel_hi:[1,0]
	s_waitcnt vmcnt(0)
	v_pk_mul_f32 v[0:1], v[24:25], v[0:1]
	v_pk_mul_f32 v[2:3], v[26:27], v[2:3]
	v_pk_fma_f32 v[4:5], v[4:5], v[0:1], v[20:21]
	v_pk_fma_f32 v[6:7], v[6:7], v[2:3], v[22:23]
	v_pk_fma_f32 v[8:9], v[8:9], v[0:1], v[20:21]
	v_pk_fma_f32 v[10:11], v[10:11], v[2:3], v[22:23]
	v_pk_fma_f32 v[12:13], v[12:13], v[0:1], v[20:21]
	v_pk_fma_f32 v[14:15], v[14:15], v[2:3], v[22:23]
	v_pk_fma_f32 v[0:1], v[16:17], v[0:1], v[20:21]
	v_pk_fma_f32 v[2:3], v[18:19], v[2:3], v[22:23]
	v_cvt_pk_bf16_f32 v4, v4, v5
	v_cvt_pk_bf16_f32 v5, v6, v7
	v_cvt_pk_bf16_f32 v6, v8, v9
	v_cvt_pk_bf16_f32 v7, v10, v11
	v_cvt_pk_bf16_f32 v8, v12, v13
	v_cvt_pk_bf16_f32 v9, v14, v15
	v_cvt_pk_bf16_f32 v0, v0, v1
	v_cvt_pk_bf16_f32 v1, v2, v3
	global_store_dwordx2 v[66:67], v[4:5], off offset:1792
	global_store_dwordx2 v[66:67], v[6:7], off offset:3840
	global_store_dwordx2 v[68:69], v[8:9], off offset:1792
	global_store_dwordx2 v[68:69], v[0:1], off offset:3840
	s_andn2_b64 exec, exec, s[24:25]
	s_cbranch_execnz .LBB0_1513

.Lr22_end:
.LBB0_2298:
	s_cmp_lt_i32 s61, 23
	s_cbranch_scc1 .LBB0_2352
	s_waitcnt vmcnt(0)
	s_barrier
	v_readfirstlane_b32 s2, v162
	s_and_b32 s3, s58, 7
	s_lshl_b32 s3, s3, 8
	s_bfe_u32 s6, s58, 0x30003
	s_lshl_b32 s6, s6, 2
	s_add_u32 s3, s3, s6
	s_add_u32 s3, s3, 0x3880
	s_add_u32 s6, s84, s3
	s_addc_u32 s7, s85, 0
	s_cmp_lg_u32 s2, 0
	s_cbranch_scc1 .Lgs22_wait
	s_mov_b64 s[8:9], exec
	s_mov_b64 exec, 1
	v_mov_b32_e32 v0, 0
	v_mov_b32_e32 v1, 1
	s_mov_b32 s10, 0
	global_atomic_add v0, v1, s[6:7]

.LBB0_2352:
	s_cmp_gt_i32 s60, 23
	s_cselect_b64 s[2:3], -1, 0
	s_cmp_lt_i32 s61, 23
	s_cselect_b64 s[4:5], -1, 0
	s_or_b64 s[2:3], s[2:3], s[4:5]
	s_and_b64 vcc, exec, s[2:3]
	s_cbranch_vccnz .LBB0_2410
	s_and_b32 s96, s58, 63
	s_lshl_b32 s96, s96, 3
	s_lshr_b32 s97, s58, 6
	s_or_b32 s96, s96, s97
	v_and_b32_e32 v0, 60, v163
	v_lshl_add_u32 v40, s96, 4, v0
	s_movk_i32 s2, 0x2000
	s_mov_b64 s[4:5], s[0:1]
	v_cmp_gt_i32_e32 vcc, s2, v40
	s_and_saveexec_b64 s[10:11], vcc
	s_cbranch_execz .LBB0_2356
	v_mbcnt_lo_u32_b32 v1, -1, 0
	v_mbcnt_hi_u32_b32 v1, -1, v1
	v_and_b32_e32 v2, 64, v1
	v_add_u32_e32 v3, 64, v2
	v_xor_b32_e32 v5, 32, v1
	v_cmp_lt_i32_e32 vcc, v5, v3
	s_load_dwordx2 s[2:3], s[4:5], 0x58
	s_load_dwordx2 s[12:13], s[4:5], 0xe0
	s_load_dword s6, s[0:1], 0xf0
	v_cndmask_b32_e32 v5, v1, v5, vcc
	v_lshlrev_b32_e32 v74, 2, v5
	v_xor_b32_e32 v5, 16, v1
	v_cmp_lt_i32_e32 vcc, v5, v3
	v_and_b32_e32 v0, 63, v162
	s_waitcnt lgkmcnt(0)
	s_add_u32 s2, s2, 0x2000
	v_cndmask_b32_e32 v5, v1, v5, vcc
	v_lshlrev_b32_e32 v75, 2, v5
	v_xor_b32_e32 v5, 8, v1
	v_cmp_lt_i32_e32 vcc, v5, v3
	s_addc_u32 s3, s3, 0
	v_mov_b32_e32 v43, 0
	v_cndmask_b32_e32 v5, v1, v5, vcc
	v_lshlrev_b32_e32 v76, 2, v5
	v_xor_b32_e32 v5, 4, v1
	v_cmp_lt_i32_e32 vcc, v5, v3
	v_or_b32_e32 v2, 64, v0
	s_add_u32 s4, s12, 0x6b05000
	v_cndmask_b32_e32 v5, v1, v5, vcc
	v_lshlrev_b32_e32 v77, 2, v5
	v_xor_b32_e32 v5, 2, v1
	v_cmp_lt_i32_e32 vcc, v5, v3
	v_or_b32_e32 v4, 0x80, v0
	v_lshlrev_b32_e32 v8, 4, v2
	v_cndmask_b32_e32 v5, v1, v5, vcc
	v_lshlrev_b32_e32 v78, 2, v5
	v_xor_b32_e32 v5, 1, v1
	v_mov_b32_e32 v9, v43
	s_addc_u32 s5, s13, 0
	s_lshl_b32 s14, s6, 4
	v_or_b32_e32 v6, 0xc0, v0
	v_cmp_lt_i32_e32 vcc, v5, v3
	v_lshl_add_u64 v[46:47], s[2:3], 0, v[8:9]
	v_lshlrev_b32_e32 v8, 4, v4
	v_ashrrev_i32_e32 v41, 31, v40
	v_cndmask_b32_e32 v1, v1, v5, vcc
	v_lshlrev_b32_e32 v42, 4, v0
	s_waitcnt vmcnt(35)
	v_lshl_add_u64 v[48:49], s[2:3], 0, v[8:9]
	v_lshlrev_b32_e32 v8, 4, v6
	s_waitcnt vmcnt(34)
	v_lshlrev_b64 v[52:53], 11, v[40:41]
	s_ashr_i32 s15, s14, 31
	v_lshlrev_b64 v[54:55], 12, v[40:41]
	s_waitcnt vmcnt(33)
	v_mov_b64_e32 v[56:57], s[4:5]
	s_mov_b32 s4, 0x358637bd
	v_lshlrev_b32_e32 v79, 2, v1
	v_lshl_add_u64 v[44:45], s[2:3], 0, v[42:43]
	v_lshl_add_u64 v[50:51], s[2:3], 0, v[8:9]
	v_lshl_or_b32 v52, v0, 3, v52
	s_lshl_b64 s[16:17], s[14:15], 11
	v_or_b32_e32 v54, v54, v42
	s_lshl_b64 s[18:19], s[14:15], 12
	s_mov_b64 s[20:21], 0
	s_movk_i32 s2, 0xfff
	s_movk_i32 s3, 0x6000
	s_mov_b64 s[22:23], 0x1000
	v_lshlrev_b32_e32 v42, 4, v0
	s_mov_b32 s15, 0x6b7b000
	s_mov_b32 s25, 0x6b7c000
	s_mov_b32 s26, 0x6b7d000
	v_lshlrev_b32_e32 v58, 4, v2
	v_mov_b32_e32 v59, v43
	s_waitcnt vmcnt(32)
	v_lshlrev_b32_e32 v60, 4, v4
	v_mov_b32_e32 v61, v43
	v_lshlrev_b32_e32 v62, 4, v6
	v_mov_b32_e32 v63, v43
	s_mov_b32 s24, 0x3a800000
	v_mov_b64_e32 v[64:65], s[4:5]
	s_mov_b32 s27, 0x800000
	s_mov_b32 s28, 0x8b7a000
	s_mov_b32 s29, 0x8b7b000
	s_movk_i32 s30, 0x1fff
.LBB0_2355:
	v_lshl_add_u64 v[16:17], s[12:13], 0, v[54:55]
	v_lshl_add_u64 v[4:5], s[12:13], 0, v[52:53]
	v_add_co_u32_e32 v8, vcc, 0x6b7a000, v16
	v_add_co_u32_e64 v66, s[4:5], s28, v4
	s_nop 0
	v_addc_co_u32_e32 v9, vcc, 0, v17, vcc
	v_addc_co_u32_e64 v67, s[4:5], 0, v5, s[4:5]
	v_add_u32_e32 v6, 0xfffff000, v40
	v_add_co_u32_e64 v68, s[4:5], s29, v4
	v_add_co_u32_e32 v12, vcc, s15, v16
	v_lshrrev_b32_e32 v6, 10, v6
	v_addc_co_u32_e64 v69, s[4:5], 0, v5, s[4:5]
	v_addc_co_u32_e32 v13, vcc, 0, v17, vcc
	v_add_u32_e32 v10, 11, v6
	v_cmp_lt_i32_e64 s[4:5], s2, v40
	v_add_co_u32_e32 v18, vcc, s25, v16
	global_load_dwordx4 v[0:3], v[44:45], off
	global_load_dwordx4 v[80:83], v[8:9], off offset:256 sc0 sc1
	global_load_dwordx4 v[36:39], v[8:9], off offset:1280 sc0 sc1
	global_load_dwordx4 v[20:23], v[8:9], off offset:2304 sc0 sc1
	global_load_dwordx4 v[4:7], v[8:9], off offset:3328 sc0 sc1
	v_cndmask_b32_e64 v14, 10, v10, s[4:5]
	v_addc_co_u32_e32 v19, vcc, 0, v17, vcc
	global_load_dwordx4 v[84:87], v[12:13], off offset:256 sc0 sc1
	global_load_dwordx4 v[88:91], v[12:13], off offset:1280 sc0 sc1
	global_load_dwordx4 v[24:27], v[12:13], off offset:2304 sc0 sc1
	global_load_dwordx4 v[8:11], v[12:13], off offset:3328 sc0 sc1
	v_mad_u64_u32 v[32:33], s[4:5], v14, s3, v[56:57]
	v_add_co_u32_e32 v108, vcc, s26, v16
	global_load_dwordx4 v[92:95], v[18:19], off offset:256 sc0 sc1
	global_load_dwordx4 v[96:99], v[18:19], off offset:1280 sc0 sc1
	global_load_dwordx4 v[28:31], v[18:19], off offset:2304 sc0 sc1
	global_load_dwordx4 v[12:15], v[18:19], off offset:3328 sc0 sc1
	v_lshl_add_u64 v[72:73], v[32:33], 0, s[22:23]
	v_lshl_add_u64 v[70:71], v[32:33], 0, v[42:43]
	v_addc_co_u32_e32 v109, vcc, 0, v17, vcc
	global_load_dwordx4 v[100:103], v[108:109], off offset:256 sc0 sc1
	global_load_dwordx4 v[104:107], v[108:109], off offset:1280 sc0 sc1
	global_load_dwordx4 v[32:35], v[108:109], off offset:2304 sc0 sc1
	global_load_dwordx4 v[16:19], v[108:109], off offset:3328 sc0 sc1
	v_lshl_add_u64 v[116:117], v[72:73], 0, v[42:43]
	global_load_dwordx4 v[108:111], v[70:71], off
	global_load_dwordx4 v[112:115], v[116:117], off
	v_lshl_add_u64 v[118:119], v[72:73], 0, v[58:59]
	v_add_u32_e32 v40, s14, v40
	v_lshl_add_u64 v[52:53], v[52:53], 0, s[16:17]
	v_lshl_add_u64 v[54:55], v[54:55], 0, s[18:19]
	s_waitcnt vmcnt(17)
	v_mov_b32_e32 v124, v81
	s_waitcnt vmcnt(16)
	v_mov_b32_e32 v125, v37
	v_mov_b32_e32 v122, v80
	v_mov_b32_e32 v123, v36
	s_waitcnt vmcnt(15)
	v_mov_b32_e32 v132, v21
	s_waitcnt vmcnt(14)
	v_mov_b32_e32 v133, v5
	v_pk_mul_f32 v[124:125], v[124:125], v[124:125]
	s_waitcnt vmcnt(13)
	v_mov_b32_e32 v140, v85
	s_waitcnt vmcnt(12)
	v_mov_b32_e32 v141, v89
	v_mov_b32_e32 v116, v82
	v_mov_b32_e32 v117, v38
	v_mov_b32_e32 v130, v20
	v_mov_b32_e32 v131, v4
	v_mov_b32_e32 v138, v84
	v_mov_b32_e32 v139, v88
	v_pk_mul_f32 v[132:133], v[132:133], v[132:133]
	s_waitcnt vmcnt(11)
	v_mov_b32_e32 v148, v25
	s_waitcnt vmcnt(10)
	v_mov_b32_e32 v149, v9
	v_pk_fma_f32 v[122:123], v[122:123], v[122:123], v[124:125]
	v_pk_mul_f32 v[124:125], v[140:141], v[140:141]
	s_waitcnt vmcnt(9)
	v_mov_b32_e32 v154, v93
	s_waitcnt vmcnt(8)
	v_mov_b32_e32 v155, v97
	v_mov_b32_e32 v120, v83
	v_mov_b32_e32 v121, v39
	v_mov_b32_e32 v126, v22
	v_mov_b32_e32 v127, v6
	v_mov_b32_e32 v134, v86
	v_mov_b32_e32 v135, v90
	v_mov_b32_e32 v146, v24
	v_mov_b32_e32 v147, v8
	v_mov_b32_e32 v152, v92
	v_mov_b32_e32 v153, v96
	v_pk_fma_f32 v[130:131], v[130:131], v[130:131], v[132:133]
	v_pk_mul_f32 v[132:133], v[148:149], v[148:149]
	s_waitcnt vmcnt(7)
	v_mov_b32_e32 v160, v29
	s_waitcnt vmcnt(6)
	v_mov_b32_e32 v161, v13
	v_pk_fma_f32 v[116:117], v[116:117], v[116:117], v[122:123]
	v_pk_fma_f32 v[122:123], v[138:139], v[138:139], v[124:125]
	v_pk_mul_f32 v[124:125], v[154:155], v[154:155]
	s_waitcnt vmcnt(5)
	v_mov_b32_e32 v166, v101
	s_waitcnt vmcnt(4)
	v_mov_b32_e32 v167, v105
	v_mov_b32_e32 v128, v23
	v_mov_b32_e32 v129, v7
	v_mov_b32_e32 v136, v87
	v_mov_b32_e32 v137, v91
	v_mov_b32_e32 v142, v26
	v_mov_b32_e32 v143, v10
	v_mov_b32_e32 v158, v28
	v_mov_b32_e32 v159, v12
	v_mov_b32_e32 v164, v100
	v_mov_b32_e32 v165, v104
	v_pk_fma_f32 v[126:127], v[126:127], v[126:127], v[130:131]
	v_pk_fma_f32 v[130:131], v[146:147], v[146:147], v[132:133]
	v_pk_mul_f32 v[132:133], v[160:161], v[160:161]
	s_waitcnt vmcnt(3)
	v_mov_b32_e32 v170, v33
	s_waitcnt vmcnt(2)
	v_mov_b32_e32 v171, v17
	s_waitcnt vmcnt(0)
	v_pk_add_f32 v[112:113], v[112:113], 1.0 op_sel_hi:[1,0]
	v_pk_fma_f32 v[116:117], v[120:121], v[120:121], v[116:117]
	v_pk_fma_f32 v[120:121], v[134:135], v[134:135], v[122:123]
	v_pk_fma_f32 v[122:123], v[152:153], v[152:153], v[124:125]
	v_pk_mul_f32 v[124:125], v[166:167], v[166:167]
	v_mov_b32_e32 v144, v27
	v_mov_b32_e32 v145, v11
	v_mov_b32_e32 v140, v94
	v_mov_b32_e32 v141, v98
	v_mov_b32_e32 v138, v102
	v_mov_b32_e32 v139, v106
	v_mov_b32_e32 v168, v32
	v_mov_b32_e32 v169, v16
	v_pk_add_f32 v[114:115], v[114:115], 1.0 op_sel_hi:[1,0]
	v_pk_fma_f32 v[126:127], v[128:129], v[128:129], v[126:127]
	v_pk_fma_f32 v[128:129], v[142:143], v[142:143], v[130:131]
	v_pk_fma_f32 v[130:131], v[158:159], v[158:159], v[132:133]
	v_pk_mul_f32 v[132:133], v[170:171], v[170:171]
	v_pk_mul_f32 v[0:1], v[0:1], v[112:113]
	v_pk_fma_f32 v[112:113], v[136:137], v[136:137], v[120:121]
	v_pk_fma_f32 v[120:121], v[164:165], v[164:165], v[124:125]
	v_mov_b32_e32 v150, v95
	v_mov_b32_e32 v151, v99
	v_mov_b32_e32 v148, v30
	v_mov_b32_e32 v149, v14
	v_mov_b32_e32 v154, v103
	v_mov_b32_e32 v155, v107
	v_mov_b32_e32 v146, v34
	v_mov_b32_e32 v147, v18
	v_pk_mul_f32 v[2:3], v[2:3], v[114:115]
	v_pk_fma_f32 v[114:115], v[140:141], v[140:141], v[122:123]
	v_pk_fma_f32 v[122:123], v[144:145], v[144:145], v[128:129]
	v_mov_b32_e32 v125, v116
	v_pk_fma_f32 v[132:133], v[168:169], v[168:169], v[132:133]
	v_pk_fma_f32 v[120:121], v[138:139], v[138:139], v[120:121]
	v_mov_b32_e32 v124, v112
	v_mov_b32_e32 v116, v113
	v_mov_b32_e32 v156, v31
	v_mov_b32_e32 v157, v15
	v_mov_b32_e32 v160, v35
	v_mov_b32_e32 v161, v19
	v_mov_b32_e32 v129, v126
	v_pk_fma_f32 v[130:131], v[148:149], v[148:149], v[130:131]
	v_pk_fma_f32 v[114:115], v[150:151], v[150:151], v[114:115]
	v_mov_b32_e32 v128, v122
	v_mov_b32_e32 v126, v123
	v_pk_fma_f32 v[122:123], v[146:147], v[146:147], v[132:133]
	v_pk_fma_f32 v[120:121], v[154:155], v[154:155], v[120:121]
	v_pk_add_f32 v[116:117], v[124:125], v[116:117]
	v_pk_fma_f32 v[112:113], v[156:157], v[156:157], v[130:131]
	v_pk_fma_f32 v[122:123], v[160:161], v[160:161], v[122:123]
	v_mov_b32_e32 v125, v114
	v_pk_add_f32 v[116:117], v[116:117], v[128:129]
	v_mov_b32_e32 v124, v120
	v_mov_b32_e32 v114, v121
	v_mov_b32_e32 v131, v112
	v_mov_b32_e32 v130, v122
	v_pk_add_f32 v[116:117], v[116:117], v[126:127]
	v_pk_add_f32 v[114:115], v[124:125], v[114:115]
	v_mov_b32_e32 v112, v123
	ds_bpermute_b32 v121, v74, v117
	ds_bpermute_b32 v120, v74, v116
	v_pk_add_f32 v[114:115], v[114:115], v[130:131]
	s_waitcnt lgkmcnt(0)
	v_pk_add_f32 v[116:117], v[116:117], v[120:121]
	v_pk_add_f32 v[112:113], v[114:115], v[112:113]
	ds_bpermute_b32 v115, v74, v113
	ds_bpermute_b32 v114, v74, v112
	ds_bpermute_b32 v121, v75, v117
	ds_bpermute_b32 v120, v75, v116
	s_waitcnt lgkmcnt(2)
	v_pk_add_f32 v[112:113], v[112:113], v[114:115]
	ds_bpermute_b32 v115, v75, v113
	ds_bpermute_b32 v114, v75, v112
	s_waitcnt lgkmcnt(2)
	v_pk_add_f32 v[116:117], v[116:117], v[120:121]
	ds_bpermute_b32 v121, v76, v117
	ds_bpermute_b32 v120, v76, v116
	s_waitcnt lgkmcnt(2)
	v_pk_add_f32 v[112:113], v[112:113], v[114:115]
	ds_bpermute_b32 v115, v76, v113
	ds_bpermute_b32 v114, v76, v112
	s_waitcnt lgkmcnt(2)
	v_pk_add_f32 v[116:117], v[116:117], v[120:121]
	ds_bpermute_b32 v121, v77, v117
	ds_bpermute_b32 v120, v77, v116
	s_waitcnt lgkmcnt(2)
	v_pk_add_f32 v[112:113], v[112:113], v[114:115]
	ds_bpermute_b32 v115, v77, v113
	ds_bpermute_b32 v114, v77, v112
	s_waitcnt lgkmcnt(2)
	v_pk_add_f32 v[116:117], v[116:117], v[120:121]
	ds_bpermute_b32 v121, v78, v117
	ds_bpermute_b32 v120, v78, v116
	s_waitcnt lgkmcnt(2)
	v_pk_add_f32 v[112:113], v[112:113], v[114:115]
	ds_bpermute_b32 v115, v78, v113
	ds_bpermute_b32 v114, v78, v112
	s_waitcnt lgkmcnt(2)
	v_pk_add_f32 v[116:117], v[116:117], v[120:121]
	ds_bpermute_b32 v121, v79, v117
	ds_bpermute_b32 v120, v79, v116
	s_waitcnt lgkmcnt(2)
	v_pk_add_f32 v[112:113], v[112:113], v[114:115]
	ds_bpermute_b32 v115, v79, v113
	ds_bpermute_b32 v114, v79, v112
	s_waitcnt lgkmcnt(2)
	v_pk_add_f32 v[116:117], v[116:117], v[120:121]
	s_waitcnt lgkmcnt(0)
	v_pk_add_f32 v[112:113], v[112:113], v[114:115]
	v_pk_fma_f32 v[116:117], v[116:117], s[24:25], v[64:65] op_sel_hi:[1,0,0]
	v_pk_fma_f32 v[112:113], v[112:113], s[24:25], v[64:65] op_sel_hi:[1,0,0]
	v_mul_f32_e32 v41, 0x4b800000, v117
	v_mul_f32_e32 v120, 0x4b800000, v116
	v_cmp_gt_f32_e32 vcc, s27, v116
	v_cmp_gt_f32_e64 s[4:5], s27, v117
	v_mul_f32_e32 v115, 0x4b800000, v113
	v_cndmask_b32_e32 v114, v116, v120, vcc
	v_cndmask_b32_e64 v41, v117, v41, s[4:5]
	v_rsq_f32_e32 v41, v41
	v_rsq_f32_e32 v114, v114
	v_mul_f32_e32 v116, 0x4b800000, v112
	v_cmp_gt_f32_e64 s[6:7], s27, v112
	v_cmp_gt_f32_e64 s[8:9], s27, v113
	s_nop 0
	v_cndmask_b32_e64 v112, v112, v116, s[6:7]
	v_cndmask_b32_e64 v113, v113, v115, s[8:9]
	v_rsq_f32_e32 v113, v113
	v_rsq_f32_e32 v115, v112
	v_mul_f32_e32 v112, 0x45800000, v41
	v_mul_f32_e32 v116, 0x45800000, v114
	v_cndmask_b32_e64 v112, v41, v112, s[4:5]
	v_cndmask_b32_e32 v114, v114, v116, vcc
	v_pk_mul_f32 v[80:81], v[80:81], v[112:113] op_sel_hi:[1,0]
	v_pk_mul_f32 v[82:83], v[82:83], v[112:113] op_sel_hi:[1,0]
	v_pk_mul_f32 v[84:85], v[84:85], v[114:115] op_sel_hi:[1,0]
	v_pk_mul_f32 v[86:87], v[86:87], v[114:115] op_sel_hi:[1,0]
	v_mul_f32_e32 v41, 0x45800000, v113
	v_mul_f32_e32 v117, 0x45800000, v115
	v_pk_fma_f32 v[80:81], v[80:81], v[0:1], v[108:109]
	v_pk_fma_f32 v[82:83], v[82:83], v[2:3], v[110:111]
	v_pk_fma_f32 v[84:85], v[84:85], v[0:1], v[108:109]
	v_pk_fma_f32 v[86:87], v[86:87], v[2:3], v[110:111]
	v_cndmask_b32_e64 v116, v113, v41, s[8:9]
	v_cndmask_b32_e64 v120, v115, v117, s[6:7]
	v_cvt_pk_bf16_f32 v80, v80, v81
	v_cvt_pk_bf16_f32 v81, v82, v83
	v_cvt_pk_bf16_f32 v82, v84, v85
	v_cvt_pk_bf16_f32 v83, v86, v87
	v_pk_mul_f32 v[84:85], v[92:93], v[116:117] op_sel_hi:[1,0]
	v_pk_mul_f32 v[86:87], v[94:95], v[116:117] op_sel_hi:[1,0]
	v_pk_mul_f32 v[92:93], v[100:101], v[120:121] op_sel_hi:[1,0]
	v_pk_mul_f32 v[94:95], v[102:103], v[120:121] op_sel_hi:[1,0]
	v_pk_fma_f32 v[84:85], v[84:85], v[0:1], v[108:109]
	v_pk_fma_f32 v[86:87], v[86:87], v[2:3], v[110:111]
	v_pk_fma_f32 v[0:1], v[92:93], v[0:1], v[108:109]
	v_pk_fma_f32 v[2:3], v[94:95], v[2:3], v[110:111]
	global_store_dwordx2 v[66:67], v[80:81], off offset:256
	global_store_dwordx2 v[66:67], v[82:83], off offset:2304
	v_cvt_pk_bf16_f32 v80, v84, v85
	v_cvt_pk_bf16_f32 v81, v86, v87
	v_cvt_pk_bf16_f32 v0, v0, v1
	v_cvt_pk_bf16_f32 v1, v2, v3
	global_store_dwordx2 v[68:69], v[80:81], off offset:256
	global_store_dwordx2 v[68:69], v[0:1], off offset:2304
	global_load_dwordx4 v[0:3], v[118:119], off
	s_nop 0
	global_load_dwordx4 v[80:83], v[70:71], off offset:1024
	global_load_dwordx4 v[84:87], v[46:47], off
	v_pk_mul_f32 v[36:37], v[36:37], v[112:113] op_sel_hi:[1,0]
	v_pk_mul_f32 v[38:39], v[38:39], v[112:113] op_sel_hi:[1,0]
	v_pk_mul_f32 v[88:89], v[88:89], v[114:115] op_sel_hi:[1,0]
	v_pk_mul_f32 v[90:91], v[90:91], v[114:115] op_sel_hi:[1,0]
	v_pk_mul_f32 v[94:95], v[96:97], v[116:117] op_sel_hi:[1,0]
	v_pk_mul_f32 v[96:97], v[98:99], v[116:117] op_sel_hi:[1,0]
	v_pk_mul_f32 v[98:99], v[104:105], v[120:121] op_sel_hi:[1,0]
	v_pk_mul_f32 v[100:101], v[106:107], v[120:121] op_sel_hi:[1,0]
	v_lshl_add_u64 v[92:93], v[72:73], 0, v[60:61]
	v_pk_mul_f32 v[20:21], v[20:21], v[112:113] op_sel_hi:[1,0]
	v_pk_mul_f32 v[22:23], v[22:23], v[112:113] op_sel_hi:[1,0]
	v_pk_mul_f32 v[24:25], v[24:25], v[114:115] op_sel_hi:[1,0]
	v_pk_mul_f32 v[26:27], v[26:27], v[114:115] op_sel_hi:[1,0]
	v_pk_mul_f32 v[28:29], v[28:29], v[116:117] op_sel_hi:[1,0]
	v_pk_mul_f32 v[30:31], v[30:31], v[116:117] op_sel_hi:[1,0]
	v_pk_mul_f32 v[32:33], v[32:33], v[120:121] op_sel_hi:[1,0]
	v_pk_mul_f32 v[34:35], v[34:35], v[120:121] op_sel_hi:[1,0]
	v_lshl_add_u64 v[72:73], v[72:73], 0, v[62:63]
	v_pk_mul_f32 v[4:5], v[4:5], v[112:113] op_sel_hi:[1,0]
	v_pk_mul_f32 v[6:7], v[6:7], v[112:113] op_sel_hi:[1,0]
	v_cmp_lt_i32_e32 vcc, s30, v40
	v_pk_mul_f32 v[8:9], v[8:9], v[114:115] op_sel_hi:[1,0]
	v_pk_mul_f32 v[10:11], v[10:11], v[114:115] op_sel_hi:[1,0]
	v_pk_mul_f32 v[12:13], v[12:13], v[116:117] op_sel_hi:[1,0]
	v_pk_mul_f32 v[14:15], v[14:15], v[116:117] op_sel_hi:[1,0]
	v_pk_mul_f32 v[16:17], v[16:17], v[120:121] op_sel_hi:[1,0]
	v_pk_mul_f32 v[18:19], v[18:19], v[120:121] op_sel_hi:[1,0]
	s_or_b64 s[20:21], vcc, s[20:21]
	s_waitcnt vmcnt(2)
	v_pk_add_f32 v[0:1], v[0:1], 1.0 op_sel_hi:[1,0]
	v_pk_add_f32 v[2:3], v[2:3], 1.0 op_sel_hi:[1,0]
	s_waitcnt vmcnt(0)
	v_pk_mul_f32 v[0:1], v[84:85], v[0:1]
	v_pk_mul_f32 v[2:3], v[86:87], v[2:3]
	v_pk_fma_f32 v[36:37], v[36:37], v[0:1], v[80:81]
	v_pk_fma_f32 v[38:39], v[38:39], v[2:3], v[82:83]
	v_pk_fma_f32 v[84:85], v[88:89], v[0:1], v[80:81]
	v_pk_fma_f32 v[86:87], v[90:91], v[2:3], v[82:83]
	v_pk_fma_f32 v[88:89], v[94:95], v[0:1], v[80:81]
	v_pk_fma_f32 v[90:91], v[96:97], v[2:3], v[82:83]
	v_pk_fma_f32 v[0:1], v[98:99], v[0:1], v[80:81]
	v_pk_fma_f32 v[2:3], v[100:101], v[2:3], v[82:83]
	v_cvt_pk_bf16_f32 v36, v36, v37
	v_cvt_pk_bf16_f32 v37, v38, v39
	v_cvt_pk_bf16_f32 v38, v84, v85
	v_cvt_pk_bf16_f32 v39, v86, v87
	v_cvt_pk_bf16_f32 v80, v88, v89
	v_cvt_pk_bf16_f32 v81, v90, v91
	v_cvt_pk_bf16_f32 v0, v0, v1
	v_cvt_pk_bf16_f32 v1, v2, v3
	global_store_dwordx2 v[66:67], v[36:37], off offset:768
	global_store_dwordx2 v[66:67], v[38:39], off offset:2816
	global_store_dwordx2 v[68:69], v[80:81], off offset:768
	global_store_dwordx2 v[68:69], v[0:1], off offset:2816
	global_load_dwordx4 v[0:3], v[92:93], off
	s_nop 0
	global_load_dwordx4 v[36:39], v[70:71], off offset:2048
	global_load_dwordx4 v[80:83], v[48:49], off
	s_waitcnt vmcnt(2)
	v_pk_add_f32 v[0:1], v[0:1], 1.0 op_sel_hi:[1,0]
	v_pk_add_f32 v[2:3], v[2:3], 1.0 op_sel_hi:[1,0]
	s_waitcnt vmcnt(0)
	v_pk_mul_f32 v[0:1], v[80:81], v[0:1]
	v_pk_mul_f32 v[2:3], v[82:83], v[2:3]
	v_pk_fma_f32 v[20:21], v[20:21], v[0:1], v[36:37]
	v_pk_fma_f32 v[22:23], v[22:23], v[2:3], v[38:39]
	v_pk_fma_f32 v[24:25], v[24:25], v[0:1], v[36:37]
	v_pk_fma_f32 v[26:27], v[26:27], v[2:3], v[38:39]
	v_pk_fma_f32 v[28:29], v[28:29], v[0:1], v[36:37]
	v_pk_fma_f32 v[30:31], v[30:31], v[2:3], v[38:39]
	v_pk_fma_f32 v[0:1], v[32:33], v[0:1], v[36:37]
	v_pk_fma_f32 v[2:3], v[34:35], v[2:3], v[38:39]
	v_cvt_pk_bf16_f32 v20, v20, v21
	v_cvt_pk_bf16_f32 v21, v22, v23
	v_cvt_pk_bf16_f32 v22, v24, v25
	v_cvt_pk_bf16_f32 v23, v26, v27
	v_cvt_pk_bf16_f32 v24, v28, v29
	v_cvt_pk_bf16_f32 v25, v30, v31
	v_cvt_pk_bf16_f32 v0, v0, v1
	v_cvt_pk_bf16_f32 v1, v2, v3
	global_store_dwordx2 v[66:67], v[20:21], off offset:1280
	global_store_dwordx2 v[66:67], v[22:23], off offset:3328
	global_store_dwordx2 v[68:69], v[24:25], off offset:1280
	global_store_dwordx2 v[68:69], v[0:1], off offset:3328
	global_load_dwordx4 v[0:3], v[72:73], off
	s_nop 0
	global_load_dwordx4 v[20:23], v[70:71], off offset:3072
	global_load_dwordx4 v[24:27], v[50:51], off
	s_waitcnt vmcnt(2)
	v_pk_add_f32 v[0:1], v[0:1], 1.0 op_sel_hi:[1,0]
	v_pk_add_f32 v[2:3], v[2:3], 1.0 op_sel_hi:[1,0]
	s_waitcnt vmcnt(0)
	v_pk_mul_f32 v[0:1], v[24:25], v[0:1]
	v_pk_mul_f32 v[2:3], v[26:27], v[2:3]
	v_pk_fma_f32 v[4:5], v[4:5], v[0:1], v[20:21]
	v_pk_fma_f32 v[6:7], v[6:7], v[2:3], v[22:23]
	v_pk_fma_f32 v[8:9], v[8:9], v[0:1], v[20:21]
	v_pk_fma_f32 v[10:11], v[10:11], v[2:3], v[22:23]
	v_pk_fma_f32 v[12:13], v[12:13], v[0:1], v[20:21]
	v_pk_fma_f32 v[14:15], v[14:15], v[2:3], v[22:23]
	v_pk_fma_f32 v[0:1], v[16:17], v[0:1], v[20:21]
	v_pk_fma_f32 v[2:3], v[18:19], v[2:3], v[22:23]
	v_cvt_pk_bf16_f32 v4, v4, v5
	v_cvt_pk_bf16_f32 v5, v6, v7
	v_cvt_pk_bf16_f32 v6, v8, v9
	v_cvt_pk_bf16_f32 v7, v10, v11
	v_cvt_pk_bf16_f32 v8, v12, v13
	v_cvt_pk_bf16_f32 v9, v14, v15
	v_cvt_pk_bf16_f32 v0, v0, v1
	v_cvt_pk_bf16_f32 v1, v2, v3
	global_store_dwordx2 v[66:67], v[4:5], off offset:1792
	global_store_dwordx2 v[66:67], v[6:7], off offset:3840
	global_store_dwordx2 v[68:69], v[8:9], off offset:1792
	global_store_dwordx2 v[68:69], v[0:1], off offset:3840
	s_andn2_b64 exec, exec, s[20:21]
	s_cbranch_execnz .LBB0_2355

.Lr25_end:
.LBB0_2480:
	s_cmp_lt_i32 s61, 26
	s_cbranch_scc1 .LBB0_2534
	s_waitcnt vmcnt(0)
	s_barrier
	v_readfirstlane_b32 s2, v162
	s_and_b32 s3, s58, 7
	s_lshl_b32 s3, s3, 8
	s_bfe_u32 s6, s58, 0x30003
	s_lshl_b32 s6, s6, 2
	s_add_u32 s3, s3, s6
	s_add_u32 s3, s3, 0x38a0
	s_add_u32 s6, s84, s3
	s_addc_u32 s7, s85, 0
	s_cmp_lg_u32 s2, 0
	s_cbranch_scc1 .Lgs25_wait
	s_mov_b64 s[8:9], exec
	s_mov_b64 exec, 1
	v_mov_b32_e32 v0, 0
	v_mov_b32_e32 v1, 1
	s_mov_b32 s10, 0
	global_atomic_add v0, v1, s[6:7]

.LBB0_2534:
	s_cmp_gt_i32 s60, 26
	s_cselect_b64 s[2:3], -1, 0
	s_cmp_lt_i32 s61, 26
	s_cselect_b64 s[4:5], -1, 0
	s_or_b64 s[2:3], s[2:3], s[4:5]
	s_and_b64 vcc, exec, s[2:3]
	s_cbranch_vccnz .LBB0_2592
	s_and_b32 s96, s58, 63
	s_lshl_b32 s96, s96, 3
	s_lshr_b32 s97, s58, 6
	s_or_b32 s96, s96, s97
	v_and_b32_e32 v0, 60, v163
	v_lshl_add_u32 v40, s96, 4, v0
	s_movk_i32 s2, 0x2000
	s_mov_b64 s[4:5], s[0:1]
	v_cmp_gt_i32_e32 vcc, s2, v40
	s_and_saveexec_b64 s[10:11], vcc
	s_cbranch_execz .LBB0_2538
	v_mbcnt_lo_u32_b32 v1, -1, 0
	v_mbcnt_hi_u32_b32 v1, -1, v1
	v_and_b32_e32 v2, 64, v1
	v_add_u32_e32 v3, 64, v2
	v_xor_b32_e32 v5, 32, v1
	v_cmp_lt_i32_e32 vcc, v5, v3
	s_load_dwordx2 s[12:13], s[4:5], 0xe0
	s_load_dwordx2 s[2:3], s[4:5], 0x50
	s_load_dword s6, s[0:1], 0xf0
	v_cndmask_b32_e32 v5, v1, v5, vcc
	v_lshlrev_b32_e32 v74, 2, v5
	v_xor_b32_e32 v5, 16, v1
	v_cmp_lt_i32_e32 vcc, v5, v3
	s_waitcnt lgkmcnt(0)
	s_add_u32 s4, s12, 0x6b02000
	v_and_b32_e32 v0, 63, v162
	v_cndmask_b32_e32 v5, v1, v5, vcc
	v_lshlrev_b32_e32 v75, 2, v5
	v_xor_b32_e32 v5, 8, v1
	v_cmp_lt_i32_e32 vcc, v5, v3
	s_addc_u32 s5, s13, 0
	s_add_u32 s2, s2, 0x3000
	v_cndmask_b32_e32 v5, v1, v5, vcc
	v_lshlrev_b32_e32 v76, 2, v5
	v_xor_b32_e32 v5, 4, v1
	v_cmp_lt_i32_e32 vcc, v5, v3
	v_mov_b32_e32 v43, 0
	v_or_b32_e32 v2, 64, v0
	v_cndmask_b32_e32 v5, v1, v5, vcc
	v_lshlrev_b32_e32 v77, 2, v5
	v_xor_b32_e32 v5, 2, v1
	v_cmp_lt_i32_e32 vcc, v5, v3
	s_addc_u32 s3, s3, 0
	v_or_b32_e32 v4, 0x80, v0
	v_cndmask_b32_e32 v5, v1, v5, vcc
	v_lshlrev_b32_e32 v78, 2, v5
	v_xor_b32_e32 v5, 1, v1
	v_lshlrev_b32_e32 v8, 4, v2
	v_mov_b32_e32 v9, v43
	s_lshl_b32 s14, s6, 4
	v_or_b32_e32 v6, 0xc0, v0
	v_cmp_lt_i32_e32 vcc, v5, v3
	v_lshl_add_u64 v[46:47], s[2:3], 0, v[8:9]
	v_lshlrev_b32_e32 v8, 4, v4
	v_ashrrev_i32_e32 v41, 31, v40
	v_cndmask_b32_e32 v1, v1, v5, vcc
	v_lshlrev_b32_e32 v42, 4, v0
	s_waitcnt vmcnt(35)
	v_lshl_add_u64 v[48:49], s[2:3], 0, v[8:9]
	v_lshlrev_b32_e32 v8, 4, v6
	s_waitcnt vmcnt(34)
	v_lshlrev_b64 v[52:53], 11, v[40:41]
	s_ashr_i32 s15, s14, 31
	v_lshlrev_b64 v[54:55], 12, v[40:41]
	s_waitcnt vmcnt(33)
	v_mov_b64_e32 v[56:57], s[4:5]
	s_mov_b32 s4, 0x358637bd
	v_lshlrev_b32_e32 v79, 2, v1
	v_lshl_add_u64 v[44:45], s[2:3], 0, v[42:43]
	v_lshl_add_u64 v[50:51], s[2:3], 0, v[8:9]
	v_lshl_or_b32 v52, v0, 3, v52
	s_lshl_b64 s[16:17], s[14:15], 11
	v_or_b32_e32 v54, v54, v42
	s_lshl_b64 s[18:19], s[14:15], 12
	s_mov_b64 s[20:21], 0
	s_movk_i32 s2, 0xfff
	s_movk_i32 s3, 0x6000
	s_mov_b64 s[22:23], 0x1000
	v_lshlrev_b32_e32 v42, 4, v0
	s_mov_b32 s15, 0x6b7b000
	s_mov_b32 s25, 0x6b7c000
	s_mov_b32 s26, 0x6b7d000
	v_lshlrev_b32_e32 v58, 4, v2
	v_mov_b32_e32 v59, v43
	s_waitcnt vmcnt(32)
	v_lshlrev_b32_e32 v60, 4, v4
	v_mov_b32_e32 v61, v43
	v_lshlrev_b32_e32 v62, 4, v6
	v_mov_b32_e32 v63, v43
	s_mov_b32 s24, 0x3a800000
	v_mov_b64_e32 v[64:65], s[4:5]
	s_mov_b32 s27, 0x800000
	s_mov_b32 s28, 0x8b7a000
	s_mov_b32 s29, 0x8b7b000
	s_movk_i32 s30, 0x1fff
.LBB0_2537:
	v_lshl_add_u64 v[16:17], s[12:13], 0, v[54:55]
	v_lshl_add_u64 v[4:5], s[12:13], 0, v[52:53]
	v_add_co_u32_e32 v8, vcc, 0x6b7a000, v16
	v_add_co_u32_e64 v66, s[4:5], s28, v4
	s_nop 0
	v_addc_co_u32_e32 v9, vcc, 0, v17, vcc
	v_addc_co_u32_e64 v67, s[4:5], 0, v5, s[4:5]
	v_add_u32_e32 v6, 0xfffff000, v40
	v_add_co_u32_e64 v68, s[4:5], s29, v4
	v_add_co_u32_e32 v12, vcc, s15, v16
	v_lshrrev_b32_e32 v6, 10, v6
	v_addc_co_u32_e64 v69, s[4:5], 0, v5, s[4:5]
	v_addc_co_u32_e32 v13, vcc, 0, v17, vcc
	v_add_u32_e32 v10, 16, v6
	v_cmp_lt_i32_e64 s[4:5], s2, v40
	v_add_co_u32_e32 v18, vcc, s25, v16
	global_load_dwordx4 v[0:3], v[44:45], off
	global_load_dwordx4 v[80:83], v[8:9], off offset:256 sc0 sc1
	global_load_dwordx4 v[36:39], v[8:9], off offset:1280 sc0 sc1
	global_load_dwordx4 v[20:23], v[8:9], off offset:2304 sc0 sc1
	global_load_dwordx4 v[4:7], v[8:9], off offset:3328 sc0 sc1
	v_cndmask_b32_e64 v14, 15, v10, s[4:5]
	v_addc_co_u32_e32 v19, vcc, 0, v17, vcc
	global_load_dwordx4 v[84:87], v[12:13], off offset:256 sc0 sc1
	global_load_dwordx4 v[88:91], v[12:13], off offset:1280 sc0 sc1
	global_load_dwordx4 v[24:27], v[12:13], off offset:2304 sc0 sc1
	global_load_dwordx4 v[8:11], v[12:13], off offset:3328 sc0 sc1
	v_mad_u64_u32 v[32:33], s[4:5], v14, s3, v[56:57]
	v_add_co_u32_e32 v108, vcc, s26, v16
	global_load_dwordx4 v[92:95], v[18:19], off offset:256 sc0 sc1
	global_load_dwordx4 v[96:99], v[18:19], off offset:1280 sc0 sc1
	global_load_dwordx4 v[28:31], v[18:19], off offset:2304 sc0 sc1
	global_load_dwordx4 v[12:15], v[18:19], off offset:3328 sc0 sc1
	v_lshl_add_u64 v[72:73], v[32:33], 0, s[22:23]
	v_lshl_add_u64 v[70:71], v[32:33], 0, v[42:43]
	v_addc_co_u32_e32 v109, vcc, 0, v17, vcc
	global_load_dwordx4 v[100:103], v[108:109], off offset:256 sc0 sc1
	global_load_dwordx4 v[104:107], v[108:109], off offset:1280 sc0 sc1
	global_load_dwordx4 v[32:35], v[108:109], off offset:2304 sc0 sc1
	global_load_dwordx4 v[16:19], v[108:109], off offset:3328 sc0 sc1
	v_lshl_add_u64 v[116:117], v[72:73], 0, v[42:43]
	global_load_dwordx4 v[108:111], v[70:71], off
	global_load_dwordx4 v[112:115], v[116:117], off
	v_lshl_add_u64 v[118:119], v[72:73], 0, v[58:59]
	v_add_u32_e32 v40, s14, v40
	v_lshl_add_u64 v[52:53], v[52:53], 0, s[16:17]
	v_lshl_add_u64 v[54:55], v[54:55], 0, s[18:19]
	s_waitcnt vmcnt(17)
	v_mov_b32_e32 v124, v81
	s_waitcnt vmcnt(16)
	v_mov_b32_e32 v125, v37
	v_mov_b32_e32 v122, v80
	v_mov_b32_e32 v123, v36
	s_waitcnt vmcnt(15)
	v_mov_b32_e32 v132, v21
	s_waitcnt vmcnt(14)
	v_mov_b32_e32 v133, v5
	v_pk_mul_f32 v[124:125], v[124:125], v[124:125]
	s_waitcnt vmcnt(13)
	v_mov_b32_e32 v140, v85
	s_waitcnt vmcnt(12)
	v_mov_b32_e32 v141, v89
	v_mov_b32_e32 v116, v82
	v_mov_b32_e32 v117, v38
	v_mov_b32_e32 v130, v20
	v_mov_b32_e32 v131, v4
	v_mov_b32_e32 v138, v84
	v_mov_b32_e32 v139, v88
	v_pk_mul_f32 v[132:133], v[132:133], v[132:133]
	s_waitcnt vmcnt(11)
	v_mov_b32_e32 v148, v25
	s_waitcnt vmcnt(10)
	v_mov_b32_e32 v149, v9
	v_pk_fma_f32 v[122:123], v[122:123], v[122:123], v[124:125]
	v_pk_mul_f32 v[124:125], v[140:141], v[140:141]
	s_waitcnt vmcnt(9)
	v_mov_b32_e32 v154, v93
	s_waitcnt vmcnt(8)
	v_mov_b32_e32 v155, v97
	v_mov_b32_e32 v120, v83
	v_mov_b32_e32 v121, v39
	v_mov_b32_e32 v126, v22
	v_mov_b32_e32 v127, v6
	v_mov_b32_e32 v134, v86
	v_mov_b32_e32 v135, v90
	v_mov_b32_e32 v146, v24
	v_mov_b32_e32 v147, v8
	v_mov_b32_e32 v152, v92
	v_mov_b32_e32 v153, v96
	v_pk_fma_f32 v[130:131], v[130:131], v[130:131], v[132:133]
	v_pk_mul_f32 v[132:133], v[148:149], v[148:149]
	s_waitcnt vmcnt(7)
	v_mov_b32_e32 v160, v29
	s_waitcnt vmcnt(6)
	v_mov_b32_e32 v161, v13
	v_pk_fma_f32 v[116:117], v[116:117], v[116:117], v[122:123]
	v_pk_fma_f32 v[122:123], v[138:139], v[138:139], v[124:125]
	v_pk_mul_f32 v[124:125], v[154:155], v[154:155]
	s_waitcnt vmcnt(5)
	v_mov_b32_e32 v166, v101
	s_waitcnt vmcnt(4)
	v_mov_b32_e32 v167, v105
	v_mov_b32_e32 v128, v23
	v_mov_b32_e32 v129, v7
	v_mov_b32_e32 v136, v87
	v_mov_b32_e32 v137, v91
	v_mov_b32_e32 v142, v26
	v_mov_b32_e32 v143, v10
	v_mov_b32_e32 v158, v28
	v_mov_b32_e32 v159, v12
	v_mov_b32_e32 v164, v100
	v_mov_b32_e32 v165, v104
	v_pk_fma_f32 v[126:127], v[126:127], v[126:127], v[130:131]
	v_pk_fma_f32 v[130:131], v[146:147], v[146:147], v[132:133]
	v_pk_mul_f32 v[132:133], v[160:161], v[160:161]
	s_waitcnt vmcnt(3)
	v_mov_b32_e32 v170, v33
	s_waitcnt vmcnt(2)
	v_mov_b32_e32 v171, v17
	s_waitcnt vmcnt(0)
	v_pk_add_f32 v[112:113], v[112:113], 1.0 op_sel_hi:[1,0]
	v_pk_fma_f32 v[116:117], v[120:121], v[120:121], v[116:117]
	v_pk_fma_f32 v[120:121], v[134:135], v[134:135], v[122:123]
	v_pk_fma_f32 v[122:123], v[152:153], v[152:153], v[124:125]
	v_pk_mul_f32 v[124:125], v[166:167], v[166:167]
	v_mov_b32_e32 v144, v27
	v_mov_b32_e32 v145, v11
	v_mov_b32_e32 v140, v94
	v_mov_b32_e32 v141, v98
	v_mov_b32_e32 v138, v102
	v_mov_b32_e32 v139, v106
	v_mov_b32_e32 v168, v32
	v_mov_b32_e32 v169, v16
	v_pk_add_f32 v[114:115], v[114:115], 1.0 op_sel_hi:[1,0]
	v_pk_fma_f32 v[126:127], v[128:129], v[128:129], v[126:127]
	v_pk_fma_f32 v[128:129], v[142:143], v[142:143], v[130:131]
	v_pk_fma_f32 v[130:131], v[158:159], v[158:159], v[132:133]
	v_pk_mul_f32 v[132:133], v[170:171], v[170:171]
	v_pk_mul_f32 v[0:1], v[0:1], v[112:113]
	v_pk_fma_f32 v[112:113], v[136:137], v[136:137], v[120:121]
	v_pk_fma_f32 v[120:121], v[164:165], v[164:165], v[124:125]
	v_mov_b32_e32 v150, v95
	v_mov_b32_e32 v151, v99
	v_mov_b32_e32 v148, v30
	v_mov_b32_e32 v149, v14
	v_mov_b32_e32 v154, v103
	v_mov_b32_e32 v155, v107
	v_mov_b32_e32 v146, v34
	v_mov_b32_e32 v147, v18
	v_pk_mul_f32 v[2:3], v[2:3], v[114:115]
	v_pk_fma_f32 v[114:115], v[140:141], v[140:141], v[122:123]
	v_pk_fma_f32 v[122:123], v[144:145], v[144:145], v[128:129]
	v_mov_b32_e32 v125, v116
	v_pk_fma_f32 v[132:133], v[168:169], v[168:169], v[132:133]
	v_pk_fma_f32 v[120:121], v[138:139], v[138:139], v[120:121]
	v_mov_b32_e32 v124, v112
	v_mov_b32_e32 v116, v113
	v_mov_b32_e32 v156, v31
	v_mov_b32_e32 v157, v15
	v_mov_b32_e32 v160, v35
	v_mov_b32_e32 v161, v19
	v_mov_b32_e32 v129, v126
	v_pk_fma_f32 v[130:131], v[148:149], v[148:149], v[130:131]
	v_pk_fma_f32 v[114:115], v[150:151], v[150:151], v[114:115]
	v_mov_b32_e32 v128, v122
	v_mov_b32_e32 v126, v123
	v_pk_fma_f32 v[122:123], v[146:147], v[146:147], v[132:133]
	v_pk_fma_f32 v[120:121], v[154:155], v[154:155], v[120:121]
	v_pk_add_f32 v[116:117], v[124:125], v[116:117]
	v_pk_fma_f32 v[112:113], v[156:157], v[156:157], v[130:131]
	v_pk_fma_f32 v[122:123], v[160:161], v[160:161], v[122:123]
	v_mov_b32_e32 v125, v114
	v_pk_add_f32 v[116:117], v[116:117], v[128:129]
	v_mov_b32_e32 v124, v120
	v_mov_b32_e32 v114, v121
	v_mov_b32_e32 v131, v112
	v_mov_b32_e32 v130, v122
	v_pk_add_f32 v[116:117], v[116:117], v[126:127]
	v_pk_add_f32 v[114:115], v[124:125], v[114:115]
	v_mov_b32_e32 v112, v123
	ds_bpermute_b32 v121, v74, v117
	ds_bpermute_b32 v120, v74, v116
	v_pk_add_f32 v[114:115], v[114:115], v[130:131]
	s_waitcnt lgkmcnt(0)
	v_pk_add_f32 v[116:117], v[116:117], v[120:121]
	v_pk_add_f32 v[112:113], v[114:115], v[112:113]
	ds_bpermute_b32 v115, v74, v113
	ds_bpermute_b32 v114, v74, v112
	ds_bpermute_b32 v121, v75, v117
	ds_bpermute_b32 v120, v75, v116
	s_waitcnt lgkmcnt(2)
	v_pk_add_f32 v[112:113], v[112:113], v[114:115]
	ds_bpermute_b32 v115, v75, v113
	ds_bpermute_b32 v114, v75, v112
	s_waitcnt lgkmcnt(2)
	v_pk_add_f32 v[116:117], v[116:117], v[120:121]
	ds_bpermute_b32 v121, v76, v117
	ds_bpermute_b32 v120, v76, v116
	s_waitcnt lgkmcnt(2)
	v_pk_add_f32 v[112:113], v[112:113], v[114:115]
	ds_bpermute_b32 v115, v76, v113
	ds_bpermute_b32 v114, v76, v112
	s_waitcnt lgkmcnt(2)
	v_pk_add_f32 v[116:117], v[116:117], v[120:121]
	ds_bpermute_b32 v121, v77, v117
	ds_bpermute_b32 v120, v77, v116
	s_waitcnt lgkmcnt(2)
	v_pk_add_f32 v[112:113], v[112:113], v[114:115]
	ds_bpermute_b32 v115, v77, v113
	ds_bpermute_b32 v114, v77, v112
	s_waitcnt lgkmcnt(2)
	v_pk_add_f32 v[116:117], v[116:117], v[120:121]
	ds_bpermute_b32 v121, v78, v117
	ds_bpermute_b32 v120, v78, v116
	s_waitcnt lgkmcnt(2)
	v_pk_add_f32 v[112:113], v[112:113], v[114:115]
	ds_bpermute_b32 v115, v78, v113
	ds_bpermute_b32 v114, v78, v112
	s_waitcnt lgkmcnt(2)
	v_pk_add_f32 v[116:117], v[116:117], v[120:121]
	ds_bpermute_b32 v121, v79, v117
	ds_bpermute_b32 v120, v79, v116
	s_waitcnt lgkmcnt(2)
	v_pk_add_f32 v[112:113], v[112:113], v[114:115]
	ds_bpermute_b32 v115, v79, v113
	ds_bpermute_b32 v114, v79, v112
	s_waitcnt lgkmcnt(2)
	v_pk_add_f32 v[116:117], v[116:117], v[120:121]
	s_waitcnt lgkmcnt(0)
	v_pk_add_f32 v[112:113], v[112:113], v[114:115]
	v_pk_fma_f32 v[116:117], v[116:117], s[24:25], v[64:65] op_sel_hi:[1,0,0]
	v_pk_fma_f32 v[112:113], v[112:113], s[24:25], v[64:65] op_sel_hi:[1,0,0]
	v_mul_f32_e32 v41, 0x4b800000, v117
	v_mul_f32_e32 v120, 0x4b800000, v116
	v_cmp_gt_f32_e32 vcc, s27, v116
	v_cmp_gt_f32_e64 s[4:5], s27, v117
	v_mul_f32_e32 v115, 0x4b800000, v113
	v_cndmask_b32_e32 v114, v116, v120, vcc
	v_cndmask_b32_e64 v41, v117, v41, s[4:5]
	v_rsq_f32_e32 v41, v41
	v_rsq_f32_e32 v114, v114
	v_mul_f32_e32 v116, 0x4b800000, v112
	v_cmp_gt_f32_e64 s[6:7], s27, v112
	v_cmp_gt_f32_e64 s[8:9], s27, v113
	s_nop 0
	v_cndmask_b32_e64 v112, v112, v116, s[6:7]
	v_cndmask_b32_e64 v113, v113, v115, s[8:9]
	v_rsq_f32_e32 v113, v113
	v_rsq_f32_e32 v115, v112
	v_mul_f32_e32 v112, 0x45800000, v41
	v_mul_f32_e32 v116, 0x45800000, v114
	v_cndmask_b32_e64 v112, v41, v112, s[4:5]
	v_cndmask_b32_e32 v114, v114, v116, vcc
	v_pk_mul_f32 v[80:81], v[80:81], v[112:113] op_sel_hi:[1,0]
	v_pk_mul_f32 v[82:83], v[82:83], v[112:113] op_sel_hi:[1,0]
	v_pk_mul_f32 v[84:85], v[84:85], v[114:115] op_sel_hi:[1,0]
	v_pk_mul_f32 v[86:87], v[86:87], v[114:115] op_sel_hi:[1,0]
	v_mul_f32_e32 v41, 0x45800000, v113
	v_mul_f32_e32 v117, 0x45800000, v115
	v_pk_fma_f32 v[80:81], v[80:81], v[0:1], v[108:109]
	v_pk_fma_f32 v[82:83], v[82:83], v[2:3], v[110:111]
	v_pk_fma_f32 v[84:85], v[84:85], v[0:1], v[108:109]
	v_pk_fma_f32 v[86:87], v[86:87], v[2:3], v[110:111]
	v_cndmask_b32_e64 v116, v113, v41, s[8:9]
	v_cndmask_b32_e64 v120, v115, v117, s[6:7]
	v_cvt_pk_bf16_f32 v80, v80, v81
	v_cvt_pk_bf16_f32 v81, v82, v83
	v_cvt_pk_bf16_f32 v82, v84, v85
	v_cvt_pk_bf16_f32 v83, v86, v87
	v_pk_mul_f32 v[84:85], v[92:93], v[116:117] op_sel_hi:[1,0]
	v_pk_mul_f32 v[86:87], v[94:95], v[116:117] op_sel_hi:[1,0]
	v_pk_mul_f32 v[92:93], v[100:101], v[120:121] op_sel_hi:[1,0]
	v_pk_mul_f32 v[94:95], v[102:103], v[120:121] op_sel_hi:[1,0]
	v_pk_fma_f32 v[84:85], v[84:85], v[0:1], v[108:109]
	v_pk_fma_f32 v[86:87], v[86:87], v[2:3], v[110:111]
	v_pk_fma_f32 v[0:1], v[92:93], v[0:1], v[108:109]
	v_pk_fma_f32 v[2:3], v[94:95], v[2:3], v[110:111]
	global_store_dwordx2 v[66:67], v[80:81], off offset:256
	global_store_dwordx2 v[66:67], v[82:83], off offset:2304
	v_cvt_pk_bf16_f32 v80, v84, v85
	v_cvt_pk_bf16_f32 v81, v86, v87
	v_cvt_pk_bf16_f32 v0, v0, v1
	v_cvt_pk_bf16_f32 v1, v2, v3
	global_store_dwordx2 v[68:69], v[80:81], off offset:256
	global_store_dwordx2 v[68:69], v[0:1], off offset:2304
	global_load_dwordx4 v[0:3], v[118:119], off
	s_nop 0
	global_load_dwordx4 v[80:83], v[70:71], off offset:1024
	global_load_dwordx4 v[84:87], v[46:47], off
	v_pk_mul_f32 v[36:37], v[36:37], v[112:113] op_sel_hi:[1,0]
	v_pk_mul_f32 v[38:39], v[38:39], v[112:113] op_sel_hi:[1,0]
	v_pk_mul_f32 v[88:89], v[88:89], v[114:115] op_sel_hi:[1,0]
	v_pk_mul_f32 v[90:91], v[90:91], v[114:115] op_sel_hi:[1,0]
	v_pk_mul_f32 v[94:95], v[96:97], v[116:117] op_sel_hi:[1,0]
	v_pk_mul_f32 v[96:97], v[98:99], v[116:117] op_sel_hi:[1,0]
	v_pk_mul_f32 v[98:99], v[104:105], v[120:121] op_sel_hi:[1,0]
	v_pk_mul_f32 v[100:101], v[106:107], v[120:121] op_sel_hi:[1,0]
	v_lshl_add_u64 v[92:93], v[72:73], 0, v[60:61]
	v_pk_mul_f32 v[20:21], v[20:21], v[112:113] op_sel_hi:[1,0]
	v_pk_mul_f32 v[22:23], v[22:23], v[112:113] op_sel_hi:[1,0]
	v_pk_mul_f32 v[24:25], v[24:25], v[114:115] op_sel_hi:[1,0]
	v_pk_mul_f32 v[26:27], v[26:27], v[114:115] op_sel_hi:[1,0]
	v_pk_mul_f32 v[28:29], v[28:29], v[116:117] op_sel_hi:[1,0]
	v_pk_mul_f32 v[30:31], v[30:31], v[116:117] op_sel_hi:[1,0]
	v_pk_mul_f32 v[32:33], v[32:33], v[120:121] op_sel_hi:[1,0]
	v_pk_mul_f32 v[34:35], v[34:35], v[120:121] op_sel_hi:[1,0]
	v_lshl_add_u64 v[72:73], v[72:73], 0, v[62:63]
	v_pk_mul_f32 v[4:5], v[4:5], v[112:113] op_sel_hi:[1,0]
	v_pk_mul_f32 v[6:7], v[6:7], v[112:113] op_sel_hi:[1,0]
	v_cmp_lt_i32_e32 vcc, s30, v40
	v_pk_mul_f32 v[8:9], v[8:9], v[114:115] op_sel_hi:[1,0]
	v_pk_mul_f32 v[10:11], v[10:11], v[114:115] op_sel_hi:[1,0]
	v_pk_mul_f32 v[12:13], v[12:13], v[116:117] op_sel_hi:[1,0]
	v_pk_mul_f32 v[14:15], v[14:15], v[116:117] op_sel_hi:[1,0]
	v_pk_mul_f32 v[16:17], v[16:17], v[120:121] op_sel_hi:[1,0]
	v_pk_mul_f32 v[18:19], v[18:19], v[120:121] op_sel_hi:[1,0]
	s_or_b64 s[20:21], vcc, s[20:21]
	s_waitcnt vmcnt(2)
	v_pk_add_f32 v[0:1], v[0:1], 1.0 op_sel_hi:[1,0]
	v_pk_add_f32 v[2:3], v[2:3], 1.0 op_sel_hi:[1,0]
	s_waitcnt vmcnt(0)
	v_pk_mul_f32 v[0:1], v[84:85], v[0:1]
	v_pk_mul_f32 v[2:3], v[86:87], v[2:3]
	v_pk_fma_f32 v[36:37], v[36:37], v[0:1], v[80:81]
	v_pk_fma_f32 v[38:39], v[38:39], v[2:3], v[82:83]
	v_pk_fma_f32 v[84:85], v[88:89], v[0:1], v[80:81]
	v_pk_fma_f32 v[86:87], v[90:91], v[2:3], v[82:83]
	v_pk_fma_f32 v[88:89], v[94:95], v[0:1], v[80:81]
	v_pk_fma_f32 v[90:91], v[96:97], v[2:3], v[82:83]
	v_pk_fma_f32 v[0:1], v[98:99], v[0:1], v[80:81]
	v_pk_fma_f32 v[2:3], v[100:101], v[2:3], v[82:83]
	v_cvt_pk_bf16_f32 v36, v36, v37
	v_cvt_pk_bf16_f32 v37, v38, v39
	v_cvt_pk_bf16_f32 v38, v84, v85
	v_cvt_pk_bf16_f32 v39, v86, v87
	v_cvt_pk_bf16_f32 v80, v88, v89
	v_cvt_pk_bf16_f32 v81, v90, v91
	v_cvt_pk_bf16_f32 v0, v0, v1
	v_cvt_pk_bf16_f32 v1, v2, v3
	global_store_dwordx2 v[66:67], v[36:37], off offset:768
	global_store_dwordx2 v[66:67], v[38:39], off offset:2816
	global_store_dwordx2 v[68:69], v[80:81], off offset:768
	global_store_dwordx2 v[68:69], v[0:1], off offset:2816
	global_load_dwordx4 v[0:3], v[92:93], off
	s_nop 0
	global_load_dwordx4 v[36:39], v[70:71], off offset:2048
	global_load_dwordx4 v[80:83], v[48:49], off
	s_waitcnt vmcnt(2)
	v_pk_add_f32 v[0:1], v[0:1], 1.0 op_sel_hi:[1,0]
	v_pk_add_f32 v[2:3], v[2:3], 1.0 op_sel_hi:[1,0]
	s_waitcnt vmcnt(0)
	v_pk_mul_f32 v[0:1], v[80:81], v[0:1]
	v_pk_mul_f32 v[2:3], v[82:83], v[2:3]
	v_pk_fma_f32 v[20:21], v[20:21], v[0:1], v[36:37]
	v_pk_fma_f32 v[22:23], v[22:23], v[2:3], v[38:39]
	v_pk_fma_f32 v[24:25], v[24:25], v[0:1], v[36:37]
	v_pk_fma_f32 v[26:27], v[26:27], v[2:3], v[38:39]
	v_pk_fma_f32 v[28:29], v[28:29], v[0:1], v[36:37]
	v_pk_fma_f32 v[30:31], v[30:31], v[2:3], v[38:39]
	v_pk_fma_f32 v[0:1], v[32:33], v[0:1], v[36:37]
	v_pk_fma_f32 v[2:3], v[34:35], v[2:3], v[38:39]
	v_cvt_pk_bf16_f32 v20, v20, v21
	v_cvt_pk_bf16_f32 v21, v22, v23
	v_cvt_pk_bf16_f32 v22, v24, v25
	v_cvt_pk_bf16_f32 v23, v26, v27
	v_cvt_pk_bf16_f32 v24, v28, v29
	v_cvt_pk_bf16_f32 v25, v30, v31
	v_cvt_pk_bf16_f32 v0, v0, v1
	v_cvt_pk_bf16_f32 v1, v2, v3
	global_store_dwordx2 v[66:67], v[20:21], off offset:1280
	global_store_dwordx2 v[66:67], v[22:23], off offset:3328
	global_store_dwordx2 v[68:69], v[24:25], off offset:1280
	global_store_dwordx2 v[68:69], v[0:1], off offset:3328
	global_load_dwordx4 v[0:3], v[72:73], off
	s_nop 0
	global_load_dwordx4 v[20:23], v[70:71], off offset:3072
	global_load_dwordx4 v[24:27], v[50:51], off
	s_waitcnt vmcnt(2)
	v_pk_add_f32 v[0:1], v[0:1], 1.0 op_sel_hi:[1,0]
	v_pk_add_f32 v[2:3], v[2:3], 1.0 op_sel_hi:[1,0]
	s_waitcnt vmcnt(0)
	v_pk_mul_f32 v[0:1], v[24:25], v[0:1]
	v_pk_mul_f32 v[2:3], v[26:27], v[2:3]
	v_pk_fma_f32 v[4:5], v[4:5], v[0:1], v[20:21]
	v_pk_fma_f32 v[6:7], v[6:7], v[2:3], v[22:23]
	v_pk_fma_f32 v[8:9], v[8:9], v[0:1], v[20:21]
	v_pk_fma_f32 v[10:11], v[10:11], v[2:3], v[22:23]
	v_pk_fma_f32 v[12:13], v[12:13], v[0:1], v[20:21]
	v_pk_fma_f32 v[14:15], v[14:15], v[2:3], v[22:23]
	v_pk_fma_f32 v[0:1], v[16:17], v[0:1], v[20:21]
	v_pk_fma_f32 v[2:3], v[18:19], v[2:3], v[22:23]
	v_cvt_pk_bf16_f32 v4, v4, v5
	v_cvt_pk_bf16_f32 v5, v6, v7
	v_cvt_pk_bf16_f32 v6, v8, v9
	v_cvt_pk_bf16_f32 v7, v10, v11
	v_cvt_pk_bf16_f32 v8, v12, v13
	v_cvt_pk_bf16_f32 v9, v14, v15
	v_cvt_pk_bf16_f32 v0, v0, v1
	v_cvt_pk_bf16_f32 v1, v2, v3
	global_store_dwordx2 v[66:67], v[4:5], off offset:1792
	global_store_dwordx2 v[66:67], v[6:7], off offset:3840
	global_store_dwordx2 v[68:69], v[8:9], off offset:1792
	global_store_dwordx2 v[68:69], v[0:1], off offset:3840
	s_andn2_b64 exec, exec, s[20:21]
	s_cbranch_execnz .LBB0_2537

.Lr29_end:
.LBB0_2733:
	s_cmp_lt_i32 s61, 30
	s_cbranch_scc1 .LBB0_2787
	s_waitcnt vmcnt(0)
	s_barrier
	v_readfirstlane_b32 s2, v162
	s_and_b32 s3, s58, 7
	s_lshl_b32 s3, s3, 8
	s_bfe_u32 s6, s58, 0x30003
	s_lshl_b32 s6, s6, 2
	s_add_u32 s3, s3, s6
	s_add_u32 s3, s3, 0x38c0
	s_add_u32 s6, s84, s3
	s_addc_u32 s7, s85, 0
	s_cmp_lg_u32 s2, 0
	s_cbranch_scc1 .Lgs29_wait
	s_mov_b64 s[8:9], exec
	s_mov_b64 exec, 1
	v_mov_b32_e32 v0, 0
	v_mov_b32_e32 v1, 1
	s_mov_b32 s10, 0
	global_atomic_add v0, v1, s[6:7]

.LBB0_2787:
	s_cmp_gt_i32 s60, 30
	s_cselect_b64 s[2:3], -1, 0
	s_cmp_lt_i32 s61, 30
	s_cselect_b64 s[4:5], -1, 0
	s_or_b64 s[2:3], s[2:3], s[4:5]
	s_and_b64 vcc, exec, s[2:3]
	s_cbranch_vccnz .LBB0_2845
	s_and_b32 s96, s58, 63
	s_lshl_b32 s96, s96, 3
	s_lshr_b32 s97, s58, 6
	s_or_b32 s96, s96, s97
	v_and_b32_e32 v0, 60, v163
	v_lshl_add_u32 v40, s96, 4, v0
	s_movk_i32 s2, 0x2000
	s_mov_b64 s[4:5], s[0:1]
	v_cmp_gt_i32_e32 vcc, s2, v40
	s_and_saveexec_b64 s[10:11], vcc
	s_cbranch_execz .LBB0_2791
	v_mbcnt_lo_u32_b32 v1, -1, 0
	v_mbcnt_hi_u32_b32 v1, -1, v1
	v_and_b32_e32 v2, 64, v1
	v_add_u32_e32 v3, 64, v2
	v_xor_b32_e32 v5, 32, v1
	v_cmp_lt_i32_e32 vcc, v5, v3
	s_load_dwordx2 s[2:3], s[4:5], 0x58
	s_load_dwordx2 s[12:13], s[4:5], 0xe0
	s_load_dword s6, s[0:1], 0xf0
	v_cndmask_b32_e32 v5, v1, v5, vcc
	v_lshlrev_b32_e32 v74, 2, v5
	v_xor_b32_e32 v5, 16, v1
	v_cmp_lt_i32_e32 vcc, v5, v3
	v_and_b32_e32 v0, 63, v162
	s_waitcnt lgkmcnt(0)
	s_add_u32 s2, s2, 0x3000
	v_cndmask_b32_e32 v5, v1, v5, vcc
	v_lshlrev_b32_e32 v75, 2, v5
	v_xor_b32_e32 v5, 8, v1
	v_cmp_lt_i32_e32 vcc, v5, v3
	s_addc_u32 s3, s3, 0
	v_mov_b32_e32 v43, 0
	v_cndmask_b32_e32 v5, v1, v5, vcc
	v_lshlrev_b32_e32 v76, 2, v5
	v_xor_b32_e32 v5, 4, v1
	v_cmp_lt_i32_e32 vcc, v5, v3
	v_or_b32_e32 v2, 64, v0
	s_add_u32 s4, s12, 0x6b05000
	v_cndmask_b32_e32 v5, v1, v5, vcc
	v_lshlrev_b32_e32 v77, 2, v5
	v_xor_b32_e32 v5, 2, v1
	v_cmp_lt_i32_e32 vcc, v5, v3
	v_or_b32_e32 v4, 0x80, v0
	v_lshlrev_b32_e32 v8, 4, v2
	v_cndmask_b32_e32 v5, v1, v5, vcc
	v_lshlrev_b32_e32 v78, 2, v5
	v_xor_b32_e32 v5, 1, v1
	v_mov_b32_e32 v9, v43
	s_addc_u32 s5, s13, 0
	s_lshl_b32 s14, s6, 4
	v_or_b32_e32 v6, 0xc0, v0
	v_cmp_lt_i32_e32 vcc, v5, v3
	v_lshl_add_u64 v[46:47], s[2:3], 0, v[8:9]
	v_lshlrev_b32_e32 v8, 4, v4
	v_ashrrev_i32_e32 v41, 31, v40
	v_cndmask_b32_e32 v1, v1, v5, vcc
	v_lshlrev_b32_e32 v42, 4, v0
	s_waitcnt vmcnt(35)
	v_lshl_add_u64 v[48:49], s[2:3], 0, v[8:9]
	v_lshlrev_b32_e32 v8, 4, v6
	s_waitcnt vmcnt(34)
	v_lshlrev_b64 v[52:53], 11, v[40:41]
	s_ashr_i32 s15, s14, 31
	v_lshlrev_b64 v[54:55], 12, v[40:41]
	s_waitcnt vmcnt(33)
	v_mov_b64_e32 v[56:57], s[4:5]
	s_mov_b32 s4, 0x358637bd
	v_lshlrev_b32_e32 v79, 2, v1
	v_lshl_add_u64 v[44:45], s[2:3], 0, v[42:43]
	v_lshl_add_u64 v[50:51], s[2:3], 0, v[8:9]
	v_lshl_or_b32 v52, v0, 3, v52
	s_lshl_b64 s[16:17], s[14:15], 11
	v_or_b32_e32 v54, v54, v42
	s_lshl_b64 s[18:19], s[14:15], 12
	s_mov_b64 s[20:21], 0
	s_movk_i32 s2, 0xfff
	s_movk_i32 s3, 0x6000
	s_mov_b64 s[22:23], 0x1000
	v_lshlrev_b32_e32 v42, 4, v0
	s_mov_b32 s15, 0x6b7b000
	s_mov_b32 s25, 0x6b7c000
	s_mov_b32 s26, 0x6b7d000
	v_lshlrev_b32_e32 v58, 4, v2
	v_mov_b32_e32 v59, v43
	s_waitcnt vmcnt(32)
	v_lshlrev_b32_e32 v60, 4, v4
	v_mov_b32_e32 v61, v43
	v_lshlrev_b32_e32 v62, 4, v6
	v_mov_b32_e32 v63, v43
	s_mov_b32 s24, 0x3a800000
	v_mov_b64_e32 v[64:65], s[4:5]
	s_mov_b32 s27, 0x800000
	s_mov_b32 s28, 0x8b7a000
	s_mov_b32 s29, 0x8b7b000
	s_movk_i32 s30, 0x1fff

.Lr32_end:
.LBB0_2915:
	s_cmp_lt_i32 s61, 33
	s_cbranch_scc1 .LBB0_2969
	s_waitcnt vmcnt(0)
	s_barrier
	v_readfirstlane_b32 s2, v162
	s_and_b32 s3, s58, 7
	s_lshl_b32 s3, s3, 8
	s_bfe_u32 s6, s58, 0x30003
	s_lshl_b32 s6, s6, 2
	s_add_u32 s3, s3, s6
	s_add_u32 s3, s3, 0x38e0
	s_add_u32 s6, s84, s3
	s_addc_u32 s7, s85, 0
	s_cmp_lg_u32 s2, 0
	s_cbranch_scc1 .Lgs32_wait
	s_mov_b64 s[8:9], exec
	s_mov_b64 exec, 1
	v_mov_b32_e32 v0, 0
	v_mov_b32_e32 v1, 1
	s_mov_b32 s10, 0
	global_atomic_add v0, v1, s[6:7]

.LBB0_2969:
	s_cmp_gt_i32 s60, 33
	s_cselect_b64 s[2:3], -1, 0
	s_cmp_lt_i32 s61, 33
	s_cselect_b64 s[4:5], -1, 0
	s_or_b64 s[2:3], s[2:3], s[4:5]
	s_and_b64 vcc, exec, s[2:3]
	s_cbranch_vccnz .LBB0_3027
	s_and_b32 s96, s58, 63
	s_lshl_b32 s96, s96, 3
	s_lshr_b32 s97, s58, 6
	s_or_b32 s96, s96, s97
	v_and_b32_e32 v0, 60, v163
	v_lshl_add_u32 v32, s96, 4, v0
	s_movk_i32 s17, 0x2000
	s_mov_b64 s[10:11], s[0:1]
	v_cmp_gt_i32_e32 vcc, s17, v32
	s_and_saveexec_b64 s[8:9], vcc
	s_cbranch_execz .LBB0_2973
	v_mbcnt_lo_u32_b32 v1, -1, 0
	v_mbcnt_hi_u32_b32 v1, -1, v1
	v_and_b32_e32 v2, 64, v1
	v_add_u32_e32 v2, 64, v2
	v_xor_b32_e32 v3, 32, v1
	v_cmp_lt_i32_e32 vcc, v3, v2
	s_load_dwordx4 s[4:7], s[10:11], 0xd0
	s_load_dwordx2 s[2:3], s[10:11], 0xe0
	s_load_dword s12, s[0:1], 0xf0
	v_cndmask_b32_e32 v3, v1, v3, vcc
	s_waitcnt vmcnt(34)
	v_lshlrev_b32_e32 v52, 2, v3
	v_xor_b32_e32 v3, 16, v1
	v_cmp_lt_i32_e32 vcc, v3, v2
	v_and_b32_e32 v0, 63, v162
	v_ashrrev_i32_e32 v33, 31, v32
	v_cndmask_b32_e32 v3, v1, v3, vcc
	v_lshlrev_b32_e32 v53, 2, v3
	v_xor_b32_e32 v3, 8, v1
	v_cmp_lt_i32_e32 vcc, v3, v2
	s_waitcnt lgkmcnt(0)
	s_lshl_b32 s10, s12, 4
	v_lshlrev_b32_e32 v34, 4, v0
	v_cndmask_b32_e32 v3, v1, v3, vcc
	v_lshlrev_b32_e32 v54, 2, v3
	v_xor_b32_e32 v3, 4, v1
	v_cmp_lt_i32_e32 vcc, v3, v2
	v_mov_b32_e32 v35, 0
	s_ashr_i32 s11, s10, 31
	v_cndmask_b32_e32 v3, v1, v3, vcc
	v_lshlrev_b32_e32 v55, 2, v3
	v_xor_b32_e32 v3, 2, v1
	v_cmp_lt_i32_e32 vcc, v3, v2
	v_lshl_add_u64 v[36:37], s[4:5], 0, v[34:35]
	s_lshl_b64 s[12:13], s[10:11], 12
	v_cndmask_b32_e32 v3, v1, v3, vcc
	s_waitcnt vmcnt(33)
	v_lshlrev_b32_e32 v56, 2, v3
	v_xor_b32_e32 v3, 1, v1
	v_cmp_lt_i32_e32 vcc, v3, v2
	s_mov_b64 s[14:15], 0
	s_mov_b32 s11, 0x6b7b000
	v_cndmask_b32_e32 v1, v1, v3, vcc
	v_lshlrev_b32_e32 v57, 2, v1
	v_lshlrev_b64 v[0:1], 12, v[32:33]
	v_lshl_add_u64 v[40:41], s[2:3], 0, v[0:1]
	s_mov_b32 s2, 0x358637bd
	v_lshl_add_u64 v[38:39], s[6:7], 0, v[0:1]
	s_mov_b32 s16, 0x3a800000
	v_mov_b64_e32 v[42:43], s[2:3]
	s_mov_b32 s18, 0x800000
	s_mov_b32 s19, 0x6b7c000
	s_mov_b32 s20, 0x6b7d000
	s_movk_i32 s21, 0x1000
	s_movk_i32 s22, 0x3000
	s_movk_i32 s23, 0x1fff
.LBB0_2972:
	v_lshl_add_u64 v[16:17], v[40:41], 0, v[34:35]
	v_add_co_u32_e64 v18, s[2:3], s11, v16
	v_add_co_u32_e32 v46, vcc, 0x6b7a000, v16
	s_nop 0
	v_addc_co_u32_e64 v19, s[2:3], 0, v17, s[2:3]
	v_add_co_u32_e64 v82, s[2:3], s19, v16
	v_addc_co_u32_e32 v47, vcc, 0, v17, vcc
	s_nop 0
	v_addc_co_u32_e64 v83, s[2:3], 0, v17, s[2:3]
	s_waitcnt vmcnt(2)
	v_add_co_u32_e64 v84, s[2:3], s20, v16
	global_load_dwordx4 v[0:3], v[36:37], off
	s_nop 0
	v_addc_co_u32_e64 v85, s[2:3], 0, v17, s[2:3]
	global_load_dwordx4 v[58:61], v[18:19], off offset:256 sc0 sc1
	global_load_dwordx4 v[62:65], v[18:19], off offset:1280 sc0 sc1
	global_load_dwordx4 v[20:23], v[18:19], off offset:2304 sc0 sc1
	global_load_dwordx4 v[4:7], v[18:19], off offset:3328 sc0 sc1
	global_load_dwordx4 v[66:69], v[82:83], off offset:256 sc0 sc1
	global_load_dwordx4 v[70:73], v[82:83], off offset:1280 sc0 sc1
	global_load_dwordx4 v[24:27], v[82:83], off offset:2304 sc0 sc1
	global_load_dwordx4 v[8:11], v[82:83], off offset:3328 sc0 sc1
	global_load_dwordx4 v[74:77], v[84:85], off offset:256 sc0 sc1
	global_load_dwordx4 v[78:81], v[84:85], off offset:1280 sc0 sc1
	global_load_dwordx4 v[28:31], v[84:85], off offset:2304 sc0 sc1
	global_load_dwordx4 v[12:15], v[84:85], off offset:3328 sc0 sc1
	s_nop 0
	global_load_dwordx4 v[82:85], v[46:47], off offset:256 sc0 sc1
	global_load_dwordx4 v[86:89], v[46:47], off offset:1280 sc0 sc1
	global_load_dwordx4 v[90:93], v[46:47], off offset:2304 sc0 sc1
	global_load_dwordx4 v[16:19], v[46:47], off offset:3328 sc0 sc1
	v_lshl_add_u64 v[44:45], v[38:39], 0, v[34:35]
	v_add_co_u32_e64 v48, s[2:3], s17, v44
	v_add_u32_e32 v32, s10, v32
	s_nop 0
	v_addc_co_u32_e64 v49, s[2:3], 0, v45, s[2:3]
	v_add_co_u32_e64 v50, s[2:3], s22, v44
	v_lshl_add_u64 v[38:39], v[38:39], 0, s[12:13]
	s_nop 0
	v_addc_co_u32_e64 v51, s[2:3], 0, v45, s[2:3]
	v_lshl_add_u64 v[40:41], v[40:41], 0, s[12:13]
	s_waitcnt vmcnt(15)
	v_mov_b32_e32 v94, v59
	s_waitcnt vmcnt(14)
	v_mov_b32_e32 v95, v63
	s_waitcnt vmcnt(13)
	v_mov_b32_e32 v102, v21
	s_waitcnt vmcnt(12)
	v_mov_b32_e32 v103, v5
	s_waitcnt vmcnt(11)
	v_mov_b32_e32 v110, v67
	s_waitcnt vmcnt(10)
	v_mov_b32_e32 v111, v71
	s_waitcnt vmcnt(9)
	v_mov_b32_e32 v118, v25
	s_waitcnt vmcnt(8)
	v_mov_b32_e32 v119, v9
	s_waitcnt vmcnt(7)
	v_mov_b32_e32 v126, v75
	s_waitcnt vmcnt(6)
	v_mov_b32_e32 v127, v79
	v_mov_b32_e32 v46, v58
	v_mov_b32_e32 v47, v62
	v_mov_b32_e32 v100, v20
	v_mov_b32_e32 v101, v4
	v_mov_b32_e32 v108, v66
	v_mov_b32_e32 v109, v70
	v_mov_b32_e32 v116, v24
	v_mov_b32_e32 v117, v8
	v_mov_b32_e32 v124, v74
	v_mov_b32_e32 v125, v78
	s_waitcnt vmcnt(5)
	v_mov_b32_e32 v134, v29
	s_waitcnt vmcnt(4)
	v_mov_b32_e32 v135, v13
	s_waitcnt vmcnt(3)
	v_mov_b32_e32 v142, v83
	s_waitcnt vmcnt(2)
	v_mov_b32_e32 v143, v87
	s_waitcnt vmcnt(1)
	v_mov_b32_e32 v150, v91
	s_waitcnt vmcnt(0)
	v_mov_b32_e32 v151, v17
	v_pk_mul_f32 v[94:95], v[94:95], v[94:95]
	v_pk_mul_f32 v[102:103], v[102:103], v[102:103]
	v_pk_mul_f32 v[110:111], v[110:111], v[110:111]
	v_pk_mul_f32 v[118:119], v[118:119], v[118:119]
	v_pk_mul_f32 v[126:127], v[126:127], v[126:127]
	v_mov_b32_e32 v96, v60
	v_mov_b32_e32 v97, v64
	v_mov_b32_e32 v112, v68
	v_mov_b32_e32 v113, v72
	v_mov_b32_e32 v120, v26
	v_mov_b32_e32 v121, v10
	v_mov_b32_e32 v128, v76
	v_mov_b32_e32 v129, v80
	v_mov_b32_e32 v132, v28
	v_mov_b32_e32 v133, v12
	v_mov_b32_e32 v140, v82
	v_mov_b32_e32 v141, v86
	v_mov_b32_e32 v148, v90
	v_mov_b32_e32 v149, v16
	v_pk_mul_f32 v[134:135], v[134:135], v[134:135]
	v_pk_mul_f32 v[142:143], v[142:143], v[142:143]
	v_pk_mul_f32 v[150:151], v[150:151], v[150:151]
	v_pk_fma_f32 v[46:47], v[46:47], v[46:47], v[94:95]
	v_pk_fma_f32 v[94:95], v[100:101], v[100:101], v[102:103]
	v_pk_fma_f32 v[100:101], v[108:109], v[108:109], v[110:111]
	v_pk_fma_f32 v[102:103], v[116:117], v[116:117], v[118:119]
	v_pk_fma_f32 v[108:109], v[124:125], v[124:125], v[126:127]
	v_mov_b32_e32 v98, v61
	v_mov_b32_e32 v99, v65
	v_mov_b32_e32 v104, v22
	v_mov_b32_e32 v105, v6
	v_mov_b32_e32 v114, v69
	v_mov_b32_e32 v115, v73
	v_mov_b32_e32 v122, v27
	v_mov_b32_e32 v123, v11
	v_mov_b32_e32 v130, v77
	v_mov_b32_e32 v131, v81
	v_mov_b32_e32 v136, v30
	v_mov_b32_e32 v137, v14
	v_mov_b32_e32 v144, v84
	v_mov_b32_e32 v145, v88
	v_mov_b32_e32 v152, v92
	v_mov_b32_e32 v153, v18
	v_pk_fma_f32 v[110:111], v[132:133], v[132:133], v[134:135]
	v_pk_fma_f32 v[116:117], v[140:141], v[140:141], v[142:143]
	v_pk_fma_f32 v[118:119], v[148:149], v[148:149], v[150:151]
	v_pk_fma_f32 v[46:47], v[96:97], v[96:97], v[46:47]
	v_pk_fma_f32 v[96:97], v[112:113], v[112:113], v[100:101]
	v_pk_fma_f32 v[100:101], v[120:121], v[120:121], v[102:103]
	v_pk_fma_f32 v[102:103], v[128:129], v[128:129], v[108:109]
	v_mov_b32_e32 v106, v23
	v_mov_b32_e32 v107, v7
	v_mov_b32_e32 v138, v31
	v_mov_b32_e32 v139, v15
	v_mov_b32_e32 v146, v85
	v_mov_b32_e32 v147, v89
	v_mov_b32_e32 v154, v93
	v_mov_b32_e32 v155, v19
	v_pk_fma_f32 v[94:95], v[104:105], v[104:105], v[94:95]
	v_pk_fma_f32 v[104:105], v[136:137], v[136:137], v[110:111]
	v_pk_fma_f32 v[108:109], v[144:145], v[144:145], v[116:117]
	v_pk_fma_f32 v[110:111], v[152:153], v[152:153], v[118:119]
	v_pk_fma_f32 v[46:47], v[98:99], v[98:99], v[46:47]
	v_pk_fma_f32 v[96:97], v[114:115], v[114:115], v[96:97]
	v_pk_fma_f32 v[98:99], v[122:123], v[122:123], v[100:101]
	v_pk_fma_f32 v[100:101], v[130:131], v[130:131], v[102:103]
	v_pk_fma_f32 v[94:95], v[106:107], v[106:107], v[94:95]
	v_pk_fma_f32 v[102:103], v[138:139], v[138:139], v[104:105]
	v_pk_fma_f32 v[104:105], v[146:147], v[146:147], v[108:109]
	v_pk_fma_f32 v[106:107], v[154:155], v[154:155], v[110:111]
	v_mov_b32_e32 v110, v100
	v_mov_b32_e32 v111, v96
	v_mov_b32_e32 v96, v101
	v_mov_b32_e32 v108, v46
	v_mov_b32_e32 v46, v94
	v_mov_b32_e32 v100, v102
	v_mov_b32_e32 v101, v98
	v_mov_b32_e32 v109, v104
	v_mov_b32_e32 v104, v47
	v_mov_b32_e32 v47, v106
	v_mov_b32_e32 v106, v95
	v_pk_add_f32 v[94:95], v[110:111], v[96:97]
	v_mov_b32_e32 v98, v103
	v_pk_add_f32 v[96:97], v[108:109], v[104:105]
	v_pk_add_f32 v[94:95], v[94:95], v[100:101]
	v_pk_add_f32 v[46:47], v[96:97], v[46:47]
	v_pk_add_f32 v[94:95], v[94:95], v[98:99]
	v_pk_add_f32 v[46:47], v[46:47], v[106:107]
	ds_bpermute_b32 v97, v52, v95
	ds_bpermute_b32 v96, v52, v94
	ds_bpermute_b32 v99, v52, v47
	ds_bpermute_b32 v98, v52, v46
	s_waitcnt lgkmcnt(2)
	v_pk_add_f32 v[94:95], v[94:95], v[96:97]
	ds_bpermute_b32 v97, v53, v95
	s_waitcnt lgkmcnt(1)
	v_pk_add_f32 v[46:47], v[46:47], v[98:99]
	ds_bpermute_b32 v96, v53, v94
	ds_bpermute_b32 v99, v53, v47
	ds_bpermute_b32 v98, v53, v46
	s_waitcnt lgkmcnt(2)
	v_pk_add_f32 v[94:95], v[94:95], v[96:97]
	ds_bpermute_b32 v97, v54, v95
	s_waitcnt lgkmcnt(1)
	v_pk_add_f32 v[46:47], v[46:47], v[98:99]
	ds_bpermute_b32 v96, v54, v94
	ds_bpermute_b32 v99, v54, v47
	ds_bpermute_b32 v98, v54, v46
	s_waitcnt lgkmcnt(2)
	v_pk_add_f32 v[94:95], v[94:95], v[96:97]
	ds_bpermute_b32 v97, v55, v95
	s_waitcnt lgkmcnt(1)
	v_pk_add_f32 v[46:47], v[46:47], v[98:99]
	ds_bpermute_b32 v96, v55, v94
	ds_bpermute_b32 v99, v55, v47
	ds_bpermute_b32 v98, v55, v46
	s_waitcnt lgkmcnt(2)
	v_pk_add_f32 v[94:95], v[94:95], v[96:97]
	ds_bpermute_b32 v97, v56, v95
	s_waitcnt lgkmcnt(1)
	v_pk_add_f32 v[46:47], v[46:47], v[98:99]
	ds_bpermute_b32 v96, v56, v94
	ds_bpermute_b32 v99, v56, v47
	ds_bpermute_b32 v98, v56, v46
	s_waitcnt lgkmcnt(2)
	v_pk_add_f32 v[94:95], v[94:95], v[96:97]
	ds_bpermute_b32 v97, v57, v95
	s_waitcnt lgkmcnt(1)
	v_pk_add_f32 v[46:47], v[46:47], v[98:99]
	ds_bpermute_b32 v96, v57, v94
	ds_bpermute_b32 v99, v57, v47
	ds_bpermute_b32 v98, v57, v46
	s_waitcnt lgkmcnt(2)
	v_pk_add_f32 v[94:95], v[94:95], v[96:97]
	s_nop 0
	v_pk_fma_f32 v[94:95], v[94:95], s[16:17], v[42:43] op_sel_hi:[1,0,0]
	s_waitcnt lgkmcnt(0)
	v_pk_add_f32 v[46:47], v[46:47], v[98:99]
	v_mul_f32_e32 v33, 0x4b800000, v95
	v_pk_fma_f32 v[46:47], v[46:47], s[16:17], v[42:43] op_sel_hi:[1,0,0]
	v_cmp_gt_f32_e64 s[2:3], s18, v95
	v_mul_f32_e32 v96, 0x4b800000, v94
	v_cmp_gt_f32_e32 vcc, s18, v94
	v_mul_f32_e32 v97, 0x4b800000, v47
	v_mul_f32_e32 v98, 0x4b800000, v46
	v_cmp_gt_f32_e64 s[4:5], s18, v46
	v_cndmask_b32_e64 v33, v95, v33, s[2:3]
	v_cmp_gt_f32_e64 s[6:7], s18, v47
	v_cndmask_b32_e32 v94, v94, v96, vcc
	v_cndmask_b32_e64 v46, v46, v98, s[4:5]
	v_cndmask_b32_e64 v47, v47, v97, s[6:7]
	v_rsq_f32_e32 v33, v33
	v_rsq_f32_e32 v94, v94
	v_rsq_f32_e32 v47, v47
	v_rsq_f32_e32 v95, v46
	v_mul_f32_e32 v46, 0x45800000, v33
	v_mul_f32_e32 v96, 0x45800000, v94
	v_mul_f32_e32 v97, 0x45800000, v47
	v_mul_f32_e32 v98, 0x45800000, v95
	v_cndmask_b32_e64 v46, v33, v46, s[2:3]
	v_cndmask_b32_e32 v94, v94, v96, vcc
	v_cndmask_b32_e64 v96, v47, v97, s[6:7]
	v_cndmask_b32_e64 v98, v95, v98, s[4:5]
	v_pk_mul_f32 v[66:67], v[66:67], v[46:47] op_sel_hi:[1,0]
	v_pk_mul_f32 v[68:69], v[68:69], v[46:47] op_sel_hi:[1,0]
	v_pk_mul_f32 v[74:75], v[74:75], v[94:95] op_sel_hi:[1,0]
	v_pk_mul_f32 v[76:77], v[76:77], v[94:95] op_sel_hi:[1,0]
	v_pk_mul_f32 v[82:83], v[82:83], v[96:97] op_sel_hi:[1,0]
	v_pk_mul_f32 v[84:85], v[84:85], v[96:97] op_sel_hi:[1,0]
	v_pk_mul_f32 v[100:101], v[58:59], v[98:99] op_sel_hi:[1,0]
	v_pk_mul_f32 v[102:103], v[60:61], v[98:99] op_sel_hi:[1,0]
	v_pk_mul_f32 v[58:59], v[0:1], v[66:67]
	v_pk_mul_f32 v[60:61], v[2:3], v[68:69]
	v_pk_mul_f32 v[66:67], v[0:1], v[74:75]
	v_pk_mul_f32 v[68:69], v[2:3], v[76:77]
	v_pk_mul_f32 v[74:75], v[0:1], v[82:83]
	v_pk_mul_f32 v[76:77], v[2:3], v[84:85]
	v_pk_mul_f32 v[0:1], v[0:1], v[100:101]
	v_pk_mul_f32 v[2:3], v[2:3], v[102:103]
	global_store_dwordx4 v[48:49], v[58:61], off
	global_store_dwordx4 v[50:51], v[66:69], off
	global_store_dwordx4 v[44:45], v[74:77], off
	global_store_dwordx4 v[48:49], v[0:3], off offset:-4096
	global_load_dwordx4 v[0:3], v[36:37], off offset:1024
	v_pk_mul_f32 v[58:59], v[86:87], v[96:97] op_sel_hi:[1,0]
	v_pk_mul_f32 v[60:61], v[88:89], v[96:97] op_sel_hi:[1,0]
	v_add_co_u32_e32 v74, vcc, s21, v44
	v_pk_mul_f32 v[66:67], v[70:71], v[46:47] op_sel_hi:[1,0]
	v_pk_mul_f32 v[68:69], v[72:73], v[46:47] op_sel_hi:[1,0]
	v_pk_mul_f32 v[70:71], v[78:79], v[94:95] op_sel_hi:[1,0]
	v_pk_mul_f32 v[72:73], v[80:81], v[94:95] op_sel_hi:[1,0]
	v_pk_mul_f32 v[62:63], v[62:63], v[98:99] op_sel_hi:[1,0]
	v_pk_mul_f32 v[64:65], v[64:65], v[98:99] op_sel_hi:[1,0]
	v_addc_co_u32_e32 v75, vcc, 0, v45, vcc
	v_cmp_lt_i32_e32 vcc, s23, v32
	s_or_b64 s[14:15], vcc, s[14:15]
	s_waitcnt vmcnt(0)
	v_pk_mul_f32 v[58:59], v[58:59], v[0:1]
	v_pk_mul_f32 v[60:61], v[60:61], v[2:3]
	v_pk_mul_f32 v[62:63], v[62:63], v[0:1]
	v_pk_mul_f32 v[64:65], v[64:65], v[2:3]
	v_pk_mul_f32 v[66:67], v[66:67], v[0:1]
	v_pk_mul_f32 v[68:69], v[68:69], v[2:3]
	v_pk_mul_f32 v[0:1], v[70:71], v[0:1]
	v_pk_mul_f32 v[2:3], v[72:73], v[2:3]
	global_store_dwordx4 v[44:45], v[58:61], off offset:1024
	global_store_dwordx4 v[74:75], v[62:65], off offset:1024
	global_store_dwordx4 v[48:49], v[66:69], off offset:1024
	global_store_dwordx4 v[50:51], v[0:3], off offset:1024
	global_load_dwordx4 v[0:3], v[36:37], off offset:2048
	v_pk_mul_f32 v[58:59], v[24:25], v[46:47] op_sel_hi:[1,0]
	v_pk_mul_f32 v[60:61], v[26:27], v[46:47] op_sel_hi:[1,0]
	v_pk_mul_f32 v[24:25], v[90:91], v[96:97] op_sel_hi:[1,0]
	v_pk_mul_f32 v[26:27], v[92:93], v[96:97] op_sel_hi:[1,0]
	v_pk_mul_f32 v[62:63], v[28:29], v[94:95] op_sel_hi:[1,0]
	v_pk_mul_f32 v[64:65], v[30:31], v[94:95] op_sel_hi:[1,0]
	v_pk_mul_f32 v[28:29], v[20:21], v[98:99] op_sel_hi:[1,0]
	v_pk_mul_f32 v[30:31], v[22:23], v[98:99] op_sel_hi:[1,0]
	s_waitcnt vmcnt(0)
	v_pk_mul_f32 v[20:21], v[24:25], v[0:1]
	v_pk_mul_f32 v[22:23], v[26:27], v[2:3]
	v_pk_mul_f32 v[24:25], v[28:29], v[0:1]
	v_pk_mul_f32 v[26:27], v[30:31], v[2:3]
	v_pk_mul_f32 v[28:29], v[58:59], v[0:1]
	v_pk_mul_f32 v[30:31], v[60:61], v[2:3]
	v_pk_mul_f32 v[0:1], v[62:63], v[0:1]
	v_pk_mul_f32 v[2:3], v[64:65], v[2:3]
	global_store_dwordx4 v[44:45], v[20:23], off offset:2048
	global_store_dwordx4 v[74:75], v[24:27], off offset:2048
	global_store_dwordx4 v[48:49], v[28:31], off offset:2048
	global_store_dwordx4 v[50:51], v[0:3], off offset:2048
	global_load_dwordx4 v[0:3], v[36:37], off offset:3072
	v_pk_mul_f32 v[20:21], v[8:9], v[46:47] op_sel_hi:[1,0]
	v_pk_mul_f32 v[22:23], v[10:11], v[46:47] op_sel_hi:[1,0]
	v_pk_mul_f32 v[8:9], v[16:17], v[96:97] op_sel_hi:[1,0]
	v_pk_mul_f32 v[10:11], v[18:19], v[96:97] op_sel_hi:[1,0]
	v_pk_mul_f32 v[24:25], v[12:13], v[94:95] op_sel_hi:[1,0]
	v_pk_mul_f32 v[26:27], v[14:15], v[94:95] op_sel_hi:[1,0]
	v_pk_mul_f32 v[12:13], v[4:5], v[98:99] op_sel_hi:[1,0]
	v_pk_mul_f32 v[14:15], v[6:7], v[98:99] op_sel_hi:[1,0]
	s_waitcnt vmcnt(0)
	v_pk_mul_f32 v[4:5], v[8:9], v[0:1]
	v_pk_mul_f32 v[6:7], v[10:11], v[2:3]
	v_pk_mul_f32 v[8:9], v[12:13], v[0:1]
	v_pk_mul_f32 v[10:11], v[14:15], v[2:3]
	v_pk_mul_f32 v[12:13], v[20:21], v[0:1]
	v_pk_mul_f32 v[14:15], v[22:23], v[2:3]
	v_pk_mul_f32 v[0:1], v[24:25], v[0:1]
	v_pk_mul_f32 v[2:3], v[26:27], v[2:3]
	global_store_dwordx4 v[44:45], v[4:7], off offset:3072
	global_store_dwordx4 v[74:75], v[8:11], off offset:3072
	global_store_dwordx4 v[48:49], v[12:15], off offset:3072
	global_store_dwordx4 v[50:51], v[0:3], off offset:3072
	s_andn2_b64 exec, exec, s[14:15]
	s_cbranch_execnz .LBB0_2972
